# K-loops: hipcc's per-segment s_setprio 3/0 flips deleted (all 11 GEMM loops)
# speedup vs baseline: 1.0067x; 1.0067x over previous
; #define G_STAGE(bufoff, gbase, o0, h64) do { \
;         __builtin_amdgcn_global_load_lds((const unsigned*)((const char*)(gbase) + (o0)), (LAS unsigned*)(lds + (bufoff) + ldsw), 16, 0, 0); \
;         __builtin_amdgcn_global_load_lds((const unsigned*)((const char*)(gbase) + (h64) + (o0)), (LAS unsigned*)(lds + (bufoff) + ldsw + 8192), 16, 0, 0); } while (0)
; #define G_LDA(dst, b, h) do { _Pragma("unroll") for (int m = 0; m < 4; ++m) _Pragma("unroll") for (int k = 0; k < 2; ++k) dst[m][k] = *(const LAS bf16x8*)(lds + G_SA(b, h) + aoff + m * 2048 + k * 1024); } while (0)
; #define G_LDB(dst, b, h) do { _Pragma("unroll") for (int n = 0; n < 2; ++n) _Pragma("unroll") for (int k = 0; k < 2; ++k) dst[n][k] = *(const LAS bf16x8*)(lds + G_SB(b, h) + boff + n * 2048 + k * 1024); } while (0)
; #define G_WAIT_L(n) asm volatile("s_waitcnt lgkmcnt(" #n ")" ::: "memory")
; #define G_BAR __builtin_amdgcn_s_barrier()
; #define G_SCHED __builtin_amdgcn_sched_barrier(0)
;     ...
;         for (int t = 0; t < nt; t += 2) {
;             const bool last = (t == nt - 2);
;             const char* a1 = cA + (size_t)(t + 1) * ckA;
;             const char* a2 = last ? nA : cA + (size_t)(t + 2) * ckA; const char* b2 = last ? nB : cB + (size_t)(t + 2) * kB;
;             const char* a3 = a2 + ckA; const char* b3 = b2 + kB;
;             G_LDB(B0, 0, 0); G_SCHED; G_LDA(At, 0, 0); G_STAGE(G_SA(1, 1), a1 + chA, cA0, qA);
;             G_WAIT_L(8); G_BAR; G_WAIT_L(0); G_MMA(0, 0, At, B0); G_BAR; G_SCHED;
;             G_LDB(B1, 0, 1); G_STAGE(G_SB(0, 0), b2, cB0, qB);
;             G_BAR; G_WAIT_L(0); G_MMA(0, 1, At, B1); G_BAR;
;             G_LDA(At, 0, 1); G_STAGE(G_SA(0, 0), a2, cA0, qA);
;             G_BAR; G_WAIT_L(0); G_MMA(1, 0, At, B0); G_BAR; G_SCHED;
.Ldbj_WIN_in:
.LBB0_212:
	s_add_u32 s4, s2, 0xfffc0080
	s_addc_u32 s5, s3, -1
	s_add_i32 s41, 0, 0x10000
	v_add_u32_e32 v0, s41, v167
	ds_read_b128 v[136:139], v0
	ds_read_b128 v[144:147], v0 offset:1024
	ds_read_b128 v[148:151], v0 offset:2048
	ds_read_b128 v[152:155], v0 offset:3072
	s_cmp_eq_u32 s23, 12
	s_cselect_b32 s43, s19, s5
	s_cselect_b32 s42, s18, s4
	s_cselect_b32 s51, s21, s22
	s_cselect_b32 s50, s20, s7
	v_lshl_add_u64 v[164:165], s[2:3], 0, v[142:143]
	s_add_i32 m0, s27, 0xc000
	ds_read_b128 v[156:159], v172
	ds_read_b128 v[160:163], v172 offset:1024
	ds_read_b128 v[174:177], v172 offset:2048
	ds_read_b128 v[178:181], v172 offset:3072
	ds_read_b128 v[182:185], v172 offset:4096
	ds_read_b128 v[196:199], v172 offset:5120
	ds_read_b128 v[200:203], v172 offset:6144
	ds_read_b128 v[204:207], v172 offset:7168
	global_load_lds_dwordx4 v[164:165], off
	v_lshl_add_u64 v[164:165], v[164:165], 0, s[0:1]
	s_add_i32 m0, s27, 0xe000
	s_nop 0
	global_load_lds_dwordx4 v[164:165], off
	s_waitcnt lgkmcnt(8)
	s_barrier
	s_waitcnt lgkmcnt(0)
	s_waitcnt lgkmcnt(0)
	v_mfma_f32_16x16x32_bf16 v[132:135], v[136:139], v[156:159], v[132:135]
	v_mfma_f32_16x16x32_bf16 v[128:131], v[148:151], v[156:159], v[128:131]
	v_mfma_f32_16x16x32_bf16 v[116:119], v[136:139], v[174:177], v[116:119]
	v_mfma_f32_16x16x32_bf16 v[112:115], v[148:151], v[174:177], v[112:115]
	v_mfma_f32_16x16x32_bf16 v[100:103], v[136:139], v[182:185], v[100:103]
	v_mfma_f32_16x16x32_bf16 v[96:99], v[148:151], v[182:185], v[96:99]
	v_mfma_f32_16x16x32_bf16 v[84:87], v[136:139], v[200:203], v[84:87]
	v_mfma_f32_16x16x32_bf16 v[80:83], v[148:151], v[200:203], v[80:83]
	v_mfma_f32_16x16x32_bf16 v[132:135], v[144:147], v[160:163], v[132:135]
	v_mfma_f32_16x16x32_bf16 v[128:131], v[152:155], v[160:163], v[128:131]
	v_mfma_f32_16x16x32_bf16 v[116:119], v[144:147], v[178:181], v[116:119]
	v_mfma_f32_16x16x32_bf16 v[112:115], v[152:155], v[178:181], v[112:115]
	v_mfma_f32_16x16x32_bf16 v[100:103], v[144:147], v[196:199], v[100:103]
	v_mfma_f32_16x16x32_bf16 v[96:99], v[152:155], v[196:199], v[96:99]
	v_mfma_f32_16x16x32_bf16 v[84:87], v[144:147], v[204:207], v[84:87]
	v_mfma_f32_16x16x32_bf16 v[80:83], v[152:155], v[204:207], v[80:83]
	s_barrier
	s_add_i32 s4, 0, 0x14000
	s_add_i32 s5, s41, s26
	v_add_u32_e32 v0, s4, v167
	v_lshl_add_u64 v[164:165], s[50:51], 0, v[140:141]
	s_mov_b32 m0, s5
	ds_read_b128 v[208:211], v0
	ds_read_b128 v[212:215], v0 offset:1024
	ds_read_b128 v[216:219], v0 offset:2048
	ds_read_b128 v[220:223], v0 offset:3072
	global_load_lds_dwordx4 v[164:165], off
	v_lshl_add_u64 v[224:225], v[164:165], 0, s[0:1]
	s_add_i32 m0, s5, 0x2000
	s_nop 0
	global_load_lds_dwordx4 v[224:225], off
	s_barrier
	s_waitcnt lgkmcnt(0)
	s_waitcnt lgkmcnt(0)
	v_mfma_f32_16x16x32_bf16 v[124:127], v[208:211], v[156:159], v[124:127]
	v_mfma_f32_16x16x32_bf16 v[120:123], v[216:219], v[156:159], v[120:123]
	v_mfma_f32_16x16x32_bf16 v[108:111], v[208:211], v[174:177], v[108:111]
	v_mfma_f32_16x16x32_bf16 v[104:107], v[216:219], v[174:177], v[104:107]
	v_mfma_f32_16x16x32_bf16 v[92:95], v[208:211], v[182:185], v[92:95]
	v_mfma_f32_16x16x32_bf16 v[88:91], v[216:219], v[182:185], v[88:91]
	v_mfma_f32_16x16x32_bf16 v[76:79], v[208:211], v[200:203], v[76:79]
	v_mfma_f32_16x16x32_bf16 v[72:75], v[216:219], v[200:203], v[72:75]
	v_mfma_f32_16x16x32_bf16 v[124:127], v[212:215], v[160:163], v[124:127]
	v_mfma_f32_16x16x32_bf16 v[120:123], v[220:223], v[160:163], v[120:123]
	v_mfma_f32_16x16x32_bf16 v[108:111], v[212:215], v[178:181], v[108:111]
	v_mfma_f32_16x16x32_bf16 v[104:107], v[220:223], v[178:181], v[104:107]
	v_mfma_f32_16x16x32_bf16 v[92:95], v[212:215], v[196:199], v[92:95]
	v_mfma_f32_16x16x32_bf16 v[88:91], v[220:223], v[196:199], v[88:91]
	v_mfma_f32_16x16x32_bf16 v[76:79], v[212:215], v[204:207], v[76:79]
	v_mfma_f32_16x16x32_bf16 v[72:75], v[220:223], v[204:207], v[72:75]
	s_mov_b32 m0, s27
	v_lshl_add_u64 v[224:225], s[42:43], 0, v[2:3]
	s_barrier
	ds_read_b128 v[156:159], v172 offset:16384
	ds_read_b128 v[160:163], v172 offset:17408
	ds_read_b128 v[174:177], v172 offset:18432
	ds_read_b128 v[178:181], v172 offset:19456
	ds_read_b128 v[182:185], v172 offset:20480
	ds_read_b128 v[196:199], v172 offset:21504
	ds_read_b128 v[200:203], v172 offset:22528
	ds_read_b128 v[204:207], v172 offset:23552
	global_load_lds_dwordx4 v[224:225], off
	v_lshl_add_u64 v[226:227], v[224:225], 0, s[0:1]
	s_mov_b32 m0, s28
	s_nop 0
	global_load_lds_dwordx4 v[226:227], off
	s_barrier
	s_waitcnt lgkmcnt(0)
	s_waitcnt lgkmcnt(0)
	v_mfma_f32_16x16x32_bf16 v[68:71], v[136:139], v[156:159], v[68:71]
	v_mfma_f32_16x16x32_bf16 v[64:67], v[148:151], v[156:159], v[64:67]
	v_mfma_f32_16x16x32_bf16 v[52:55], v[136:139], v[174:177], v[52:55]
	v_mfma_f32_16x16x32_bf16 v[48:51], v[148:151], v[174:177], v[48:51]
	v_mfma_f32_16x16x32_bf16 v[36:39], v[136:139], v[182:185], v[36:39]
	v_mfma_f32_16x16x32_bf16 v[32:35], v[148:151], v[182:185], v[32:35]
	v_mfma_f32_16x16x32_bf16 v[20:23], v[136:139], v[200:203], v[20:23]
	v_mfma_f32_16x16x32_bf16 v[16:19], v[148:151], v[200:203], v[16:19]
	v_mfma_f32_16x16x32_bf16 v[68:71], v[144:147], v[160:163], v[68:71]
	v_mfma_f32_16x16x32_bf16 v[64:67], v[152:155], v[160:163], v[64:67]
	v_mfma_f32_16x16x32_bf16 v[52:55], v[144:147], v[178:181], v[52:55]
	v_mfma_f32_16x16x32_bf16 v[48:51], v[152:155], v[178:181], v[48:51]
	v_mfma_f32_16x16x32_bf16 v[36:39], v[144:147], v[196:199], v[36:39]
	v_mfma_f32_16x16x32_bf16 v[32:35], v[152:155], v[196:199], v[32:35]
	v_mfma_f32_16x16x32_bf16 v[20:23], v[144:147], v[204:207], v[20:23]
	v_mfma_f32_16x16x32_bf16 v[16:19], v[152:155], v[204:207], v[16:19]
	s_barrier
; #define G_STAGE(bufoff, gbase, o0, h64) do { \
;         __builtin_amdgcn_global_load_lds((const unsigned*)((const char*)(gbase) + (o0)), (LAS unsigned*)(lds + (bufoff) + ldsw), 16, 0, 0); \
;         __builtin_amdgcn_global_load_lds((const unsigned*)((const char*)(gbase) + (h64) + (o0)), (LAS unsigned*)(lds + (bufoff) + ldsw + 8192), 16, 0, 0); } while (0)
; #define G_LDA(dst, b, h) do { _Pragma("unroll") for (int m = 0; m < 4; ++m) _Pragma("unroll") for (int k = 0; k < 2; ++k) dst[m][k] = *(const LAS bf16x8*)(lds + G_SA(b, h) + aoff + m * 2048 + k * 1024); } while (0)
; #define G_LDB(dst, b, h) do { _Pragma("unroll") for (int n = 0; n < 2; ++n) _Pragma("unroll") for (int k = 0; k < 2; ++k) dst[n][k] = *(const LAS bf16x8*)(lds + G_SB(b, h) + boff + n * 2048 + k * 1024); } while (0)
; #define G_WAIT_V(n) asm volatile("s_waitcnt vmcnt(" #n ")" ::: "memory")
; #define G_WAIT_L(n) asm volatile("s_waitcnt lgkmcnt(" #n ")" ::: "memory")
; #define G_BAR __builtin_amdgcn_s_barrier()
; #define G_SCHED __builtin_amdgcn_sched_barrier(0)
;     ...
;             G_STAGE(G_SB(0, 1), b2 + chB, cB0, qB);
;             G_WAIT_V(6); G_BAR; G_MMA(1, 1, At, B1); G_BAR;
;             G_LDB(B0, 1, 0); G_SCHED; G_LDA(At, 1, 0); G_STAGE(G_SA(0, 1), a2 + chA, cA0, qA);
;             G_WAIT_L(8); G_BAR; G_WAIT_L(0); G_MMA(0, 0, At, B0); G_BAR; G_SCHED;
;             G_LDB(B1, 1, 1); G_STAGE(G_SB(1, 0), b3, cB0, qB);
;             G_BAR; G_WAIT_L(0); G_MMA(0, 1, At, B1); G_BAR;
	s_add_i32 s4, s4, s26
	v_lshl_add_u64 v[136:137], v[164:165], 0, s[52:53]
	s_mov_b32 m0, s4
	s_nop 0
	global_load_lds_dwordx4 v[136:137], off
	v_lshl_add_u64 v[136:137], v[164:165], 0, s[54:55]
	s_add_i32 m0, s4, 0x2000
	s_nop 0
	global_load_lds_dwordx4 v[136:137], off
	s_waitcnt vmcnt(6)
	s_barrier
	v_mfma_f32_16x16x32_bf16 v[60:63], v[208:211], v[156:159], v[60:63]
	v_mfma_f32_16x16x32_bf16 v[56:59], v[216:219], v[156:159], v[56:59]
	v_mfma_f32_16x16x32_bf16 v[44:47], v[208:211], v[174:177], v[44:47]
	v_mfma_f32_16x16x32_bf16 v[40:43], v[216:219], v[174:177], v[40:43]
	v_mfma_f32_16x16x32_bf16 v[28:31], v[208:211], v[182:185], v[28:31]
	v_mfma_f32_16x16x32_bf16 v[24:27], v[216:219], v[182:185], v[24:27]
	v_mfma_f32_16x16x32_bf16 v[12:15], v[208:211], v[200:203], v[12:15]
	v_mfma_f32_16x16x32_bf16 v[8:11], v[216:219], v[200:203], v[8:11]
	v_mfma_f32_16x16x32_bf16 v[60:63], v[212:215], v[160:163], v[60:63]
	v_mfma_f32_16x16x32_bf16 v[56:59], v[220:223], v[160:163], v[56:59]
	v_mfma_f32_16x16x32_bf16 v[44:47], v[212:215], v[178:181], v[44:47]
	v_mfma_f32_16x16x32_bf16 v[40:43], v[220:223], v[178:181], v[40:43]
	v_mfma_f32_16x16x32_bf16 v[28:31], v[212:215], v[196:199], v[28:31]
	v_mfma_f32_16x16x32_bf16 v[24:27], v[220:223], v[196:199], v[24:27]
	v_mfma_f32_16x16x32_bf16 v[12:15], v[212:215], v[204:207], v[12:15]
	v_mfma_f32_16x16x32_bf16 v[8:11], v[220:223], v[204:207], v[8:11]
	s_add_i32 s4, 0, 0x18000
	v_add_u32_e32 v0, s4, v167
	s_barrier
	ds_read_b128 v[136:139], v0
	ds_read_b128 v[144:147], v0 offset:1024
	ds_read_b128 v[148:151], v0 offset:2048
	ds_read_b128 v[152:155], v0 offset:3072
	s_mov_b32 m0, s29
	v_lshl_add_u64 v[208:209], v[224:225], 0, s[52:53]
	ds_read_b128 v[156:159], v172 offset:32768
	ds_read_b128 v[160:163], v172 offset:33792
	ds_read_b128 v[174:177], v172 offset:34816
	ds_read_b128 v[178:181], v172 offset:35840
	ds_read_b128 v[182:185], v172 offset:36864
	ds_read_b128 v[196:199], v172 offset:37888
	ds_read_b128 v[200:203], v172 offset:38912
	ds_read_b128 v[204:207], v172 offset:39936
	global_load_lds_dwordx4 v[208:209], off
	v_lshl_add_u64 v[208:209], v[224:225], 0, s[54:55]
	s_mov_b32 m0, s30
	s_nop 0
	global_load_lds_dwordx4 v[208:209], off
	s_waitcnt lgkmcnt(8)
	s_barrier
	s_waitcnt lgkmcnt(0)
	s_waitcnt lgkmcnt(0)
	v_mfma_f32_16x16x32_bf16 v[132:135], v[136:139], v[156:159], v[132:135]
	v_mfma_f32_16x16x32_bf16 v[128:131], v[148:151], v[156:159], v[128:131]
	v_mfma_f32_16x16x32_bf16 v[116:119], v[136:139], v[174:177], v[116:119]
	v_mfma_f32_16x16x32_bf16 v[112:115], v[148:151], v[174:177], v[112:115]
	v_mfma_f32_16x16x32_bf16 v[100:103], v[136:139], v[182:185], v[100:103]
	v_mfma_f32_16x16x32_bf16 v[96:99], v[148:151], v[182:185], v[96:99]
	v_mfma_f32_16x16x32_bf16 v[84:87], v[136:139], v[200:203], v[84:87]
	v_mfma_f32_16x16x32_bf16 v[80:83], v[148:151], v[200:203], v[80:83]
	v_mfma_f32_16x16x32_bf16 v[132:135], v[144:147], v[160:163], v[132:135]
	v_mfma_f32_16x16x32_bf16 v[128:131], v[152:155], v[160:163], v[128:131]
	v_mfma_f32_16x16x32_bf16 v[116:119], v[144:147], v[178:181], v[116:119]
	v_mfma_f32_16x16x32_bf16 v[112:115], v[152:155], v[178:181], v[112:115]
	v_mfma_f32_16x16x32_bf16 v[100:103], v[144:147], v[196:199], v[100:103]
	v_mfma_f32_16x16x32_bf16 v[96:99], v[152:155], v[196:199], v[96:99]
	v_mfma_f32_16x16x32_bf16 v[84:87], v[144:147], v[204:207], v[84:87]
	v_mfma_f32_16x16x32_bf16 v[80:83], v[152:155], v[204:207], v[80:83]
	s_barrier
	s_add_i32 s5, 0, 0x1c000
	s_add_i32 s4, s4, s26
	v_add_u32_e32 v0, s5, v167
	v_lshl_add_u64 v[226:227], v[164:165], 0, s[46:47]
	s_mov_b32 m0, s4
	ds_read_b128 v[208:211], v0
	ds_read_b128 v[212:215], v0 offset:1024
	ds_read_b128 v[216:219], v0 offset:2048
	ds_read_b128 v[220:223], v0 offset:3072
	global_load_lds_dwordx4 v[226:227], off
	v_lshl_add_u64 v[226:227], v[164:165], 0, s[58:59]
	s_add_i32 m0, s4, 0x2000
	s_nop 0
	global_load_lds_dwordx4 v[226:227], off
	s_barrier
; #define G_STAGE(bufoff, gbase, o0, h64) do { \
;         __builtin_amdgcn_global_load_lds((const unsigned*)((const char*)(gbase) + (o0)), (LAS unsigned*)(lds + (bufoff) + ldsw), 16, 0, 0); \
;         __builtin_amdgcn_global_load_lds((const unsigned*)((const char*)(gbase) + (h64) + (o0)), (LAS unsigned*)(lds + (bufoff) + ldsw + 8192), 16, 0, 0); } while (0)
; #define G_LDA(dst, b, h) do { _Pragma("unroll") for (int m = 0; m < 4; ++m) _Pragma("unroll") for (int k = 0; k < 2; ++k) dst[m][k] = *(const LAS bf16x8*)(lds + G_SA(b, h) + aoff + m * 2048 + k * 1024); } while (0)
; #define G_WAIT_V(n) asm volatile("s_waitcnt vmcnt(" #n ")" ::: "memory")
; #define G_WAIT_L(n) asm volatile("s_waitcnt lgkmcnt(" #n ")" ::: "memory")
; #define G_BAR __builtin_amdgcn_s_barrier()
; #define G_SCHED __builtin_amdgcn_sched_barrier(0)
;     ...
;             G_BAR; G_WAIT_L(0); G_MMA(0, 1, At, B1); G_BAR;
;             G_LDA(At, 1, 1); G_STAGE(G_SA(1, 0), a3, cA0, qA);
;             G_BAR; G_WAIT_L(0); G_MMA(1, 0, At, B0); G_BAR; G_SCHED;
;             G_STAGE(G_SB(1, 1), b3 + chB, cB0, qB);
;             G_WAIT_V(6); G_BAR; G_MMA(1, 1, At, B1); G_BAR;
;         }
	s_waitcnt lgkmcnt(0)
	s_waitcnt lgkmcnt(0)
	v_mfma_f32_16x16x32_bf16 v[124:127], v[208:211], v[156:159], v[124:127]
	v_mfma_f32_16x16x32_bf16 v[120:123], v[216:219], v[156:159], v[120:123]
	v_mfma_f32_16x16x32_bf16 v[108:111], v[208:211], v[174:177], v[108:111]
	v_mfma_f32_16x16x32_bf16 v[104:107], v[216:219], v[174:177], v[104:107]
	v_mfma_f32_16x16x32_bf16 v[92:95], v[208:211], v[182:185], v[92:95]
	v_mfma_f32_16x16x32_bf16 v[88:91], v[216:219], v[182:185], v[88:91]
	v_mfma_f32_16x16x32_bf16 v[76:79], v[208:211], v[200:203], v[76:79]
	v_mfma_f32_16x16x32_bf16 v[72:75], v[216:219], v[200:203], v[72:75]
	v_mfma_f32_16x16x32_bf16 v[124:127], v[212:215], v[160:163], v[124:127]
	v_mfma_f32_16x16x32_bf16 v[120:123], v[220:223], v[160:163], v[120:123]
	v_mfma_f32_16x16x32_bf16 v[108:111], v[212:215], v[178:181], v[108:111]
	v_mfma_f32_16x16x32_bf16 v[104:107], v[220:223], v[178:181], v[104:107]
	v_mfma_f32_16x16x32_bf16 v[92:95], v[212:215], v[196:199], v[92:95]
	v_mfma_f32_16x16x32_bf16 v[88:91], v[220:223], v[196:199], v[88:91]
	v_mfma_f32_16x16x32_bf16 v[76:79], v[212:215], v[204:207], v[76:79]
	v_mfma_f32_16x16x32_bf16 v[72:75], v[220:223], v[204:207], v[72:75]
	s_mov_b32 m0, s31
	v_lshl_add_u64 v[226:227], v[224:225], 0, s[46:47]
	s_barrier
	ds_read_b128 v[156:159], v172 offset:49152
	ds_read_b128 v[160:163], v172 offset:50176
	ds_read_b128 v[174:177], v172 offset:51200
	ds_read_b128 v[178:181], v172 offset:52224
	ds_read_b128 v[182:185], v172 offset:53248
	ds_read_b128 v[196:199], v172 offset:54272
	ds_read_b128 v[200:203], v172 offset:55296
	ds_read_b128 v[204:207], v172 offset:56320
	global_load_lds_dwordx4 v[226:227], off
	v_lshl_add_u64 v[224:225], v[224:225], 0, s[58:59]
	s_mov_b32 m0, s34
	s_nop 0
	global_load_lds_dwordx4 v[224:225], off
	s_barrier
	s_waitcnt lgkmcnt(0)
	s_waitcnt lgkmcnt(0)
	v_mfma_f32_16x16x32_bf16 v[68:71], v[136:139], v[156:159], v[68:71]
	v_mfma_f32_16x16x32_bf16 v[64:67], v[148:151], v[156:159], v[64:67]
	v_mfma_f32_16x16x32_bf16 v[52:55], v[136:139], v[174:177], v[52:55]
	v_mfma_f32_16x16x32_bf16 v[48:51], v[148:151], v[174:177], v[48:51]
	v_mfma_f32_16x16x32_bf16 v[36:39], v[136:139], v[182:185], v[36:39]
	v_mfma_f32_16x16x32_bf16 v[32:35], v[148:151], v[182:185], v[32:35]
	v_mfma_f32_16x16x32_bf16 v[20:23], v[136:139], v[200:203], v[20:23]
	v_mfma_f32_16x16x32_bf16 v[16:19], v[148:151], v[200:203], v[16:19]
	v_mfma_f32_16x16x32_bf16 v[68:71], v[144:147], v[160:163], v[68:71]
	v_mfma_f32_16x16x32_bf16 v[64:67], v[152:155], v[160:163], v[64:67]
	v_mfma_f32_16x16x32_bf16 v[52:55], v[144:147], v[178:181], v[52:55]
	v_mfma_f32_16x16x32_bf16 v[48:51], v[152:155], v[178:181], v[48:51]
	v_mfma_f32_16x16x32_bf16 v[36:39], v[144:147], v[196:199], v[36:39]
	v_mfma_f32_16x16x32_bf16 v[32:35], v[152:155], v[196:199], v[32:35]
	v_mfma_f32_16x16x32_bf16 v[20:23], v[144:147], v[204:207], v[20:23]
	v_mfma_f32_16x16x32_bf16 v[16:19], v[152:155], v[204:207], v[16:19]
	s_barrier
	s_add_i32 s4, s5, s26
	v_lshl_add_u64 v[136:137], v[164:165], 0, s[62:63]
	s_mov_b32 m0, s4
	s_nop 0
	global_load_lds_dwordx4 v[136:137], off
	v_lshl_add_u64 v[136:137], v[164:165], 0, s[64:65]
	s_add_i32 m0, s4, 0x2000
	s_nop 0
	global_load_lds_dwordx4 v[136:137], off
	s_waitcnt vmcnt(6)
	s_barrier
	v_mfma_f32_16x16x32_bf16 v[60:63], v[208:211], v[156:159], v[60:63]
	v_mfma_f32_16x16x32_bf16 v[56:59], v[216:219], v[156:159], v[56:59]
	v_mfma_f32_16x16x32_bf16 v[44:47], v[208:211], v[174:177], v[44:47]
	v_mfma_f32_16x16x32_bf16 v[40:43], v[216:219], v[174:177], v[40:43]
	v_mfma_f32_16x16x32_bf16 v[28:31], v[208:211], v[182:185], v[28:31]
	v_mfma_f32_16x16x32_bf16 v[24:27], v[216:219], v[182:185], v[24:27]
	v_mfma_f32_16x16x32_bf16 v[12:15], v[208:211], v[200:203], v[12:15]
	v_mfma_f32_16x16x32_bf16 v[8:11], v[216:219], v[200:203], v[8:11]
	v_mfma_f32_16x16x32_bf16 v[60:63], v[212:215], v[160:163], v[60:63]
	v_mfma_f32_16x16x32_bf16 v[56:59], v[220:223], v[160:163], v[56:59]
	v_mfma_f32_16x16x32_bf16 v[44:47], v[212:215], v[178:181], v[44:47]
	v_mfma_f32_16x16x32_bf16 v[40:43], v[220:223], v[178:181], v[40:43]
	v_mfma_f32_16x16x32_bf16 v[28:31], v[212:215], v[196:199], v[28:31]
	v_mfma_f32_16x16x32_bf16 v[24:27], v[220:223], v[196:199], v[24:27]
	v_mfma_f32_16x16x32_bf16 v[12:15], v[212:215], v[204:207], v[12:15]
	v_mfma_f32_16x16x32_bf16 v[8:11], v[220:223], v[204:207], v[8:11]
	s_add_i32 s23, s23, 2
	s_add_u32 s2, s2, 0x100
	s_addc_u32 s3, s3, 0
	s_add_u32 s7, s7, 0x100
	s_addc_u32 s22, s22, 0
	s_cmp_gt_u32 s23, 13
	s_cbranch_scc0 .Ldb_WIN_cont
	v_readfirstlane_b32 s101, v186
	s_cmpk_gt_u32 s101, 0xff
	s_cbranch_scc1 .Ldb_WIN_exit
	s_barrier
	s_branch .Ldb_WIN_exit

; #define G_STAGE(bufoff, gbase, o0, h64) do { \
;         __builtin_amdgcn_global_load_lds((const unsigned*)((const char*)(gbase) + (o0)), (LAS unsigned*)(lds + (bufoff) + ldsw), 16, 0, 0); \
;         __builtin_amdgcn_global_load_lds((const unsigned*)((const char*)(gbase) + (h64) + (o0)), (LAS unsigned*)(lds + (bufoff) + ldsw + 8192), 16, 0, 0); } while (0)
; #define G_LDA(dst, b, h) do { _Pragma("unroll") for (int m = 0; m < 4; ++m) _Pragma("unroll") for (int k = 0; k < 2; ++k) dst[m][k] = *(const LAS bf16x8*)(lds + G_SA(b, h) + aoff + m * 2048 + k * 1024); } while (0)
; #define G_LDB(dst, b, h) do { _Pragma("unroll") for (int n = 0; n < 2; ++n) _Pragma("unroll") for (int k = 0; k < 2; ++k) dst[n][k] = *(const LAS bf16x8*)(lds + G_SB(b, h) + boff + n * 2048 + k * 1024); } while (0)
; #define G_WAIT_L(n) asm volatile("s_waitcnt lgkmcnt(" #n ")" ::: "memory")
; #define G_BAR __builtin_amdgcn_s_barrier()
; #define G_SCHED __builtin_amdgcn_sched_barrier(0)
;     ...
;         for (int t = 0; t < nt; t += 2) {
;             const bool last = (t == nt - 2);
;             const char* a1 = cA + (size_t)(t + 1) * ckA;
;             const char* a2 = last ? nA : cA + (size_t)(t + 2) * ckA; const char* b2 = last ? nB : cB + (size_t)(t + 2) * kB;
;             const char* a3 = a2 + ckA; const char* b3 = b2 + kB;
;             G_LDB(B0, 0, 0); G_SCHED; G_LDA(At, 0, 0); G_STAGE(G_SA(1, 1), a1 + chA, cA0, qA);
;             G_WAIT_L(8); G_BAR; G_WAIT_L(0); G_MMA(0, 0, At, B0); G_BAR; G_SCHED;
;             G_LDB(B1, 0, 1); G_STAGE(G_SB(0, 0), b2, cB0, qB);
;             G_BAR; G_WAIT_L(0); G_MMA(0, 1, At, B1); G_BAR;
;             G_LDA(At, 0, 1); G_STAGE(G_SA(0, 0), a2, cA0, qA);
;             G_BAR; G_WAIT_L(0); G_MMA(1, 0, At, B0); G_BAR; G_SCHED;
.Ldbj_SSM1_in:
.LBB0_450:
	s_add_u32 s4, s6, 0xfffe0080
	s_addc_u32 s5, s7, -1
	s_add_i32 s41, 0, 0x10000
	v_add_u32_e32 v0, s41, v145
	ds_read_b128 v[140:143], v0
	ds_read_b128 v[148:151], v0 offset:1024
	ds_read_b128 v[152:155], v0 offset:2048
	ds_read_b128 v[156:159], v0 offset:3072
	s_cmp_eq_u32 s21, 4
	s_cselect_b32 s23, s11, s5
	s_cselect_b32 s22, s10, s4
	s_cselect_b32 s43, s17, s20
	s_cselect_b32 s42, s16, s19
	v_lshl_add_u64 v[184:185], s[6:7], 0, v[138:139]
	s_add_i32 m0, s27, 0xc000
	ds_read_b128 v[160:163], v146
	ds_read_b128 v[164:167], v146 offset:1024
	ds_read_b128 v[172:175], v146 offset:2048
	ds_read_b128 v[176:179], v146 offset:3072
	ds_read_b128 v[180:183], v146 offset:4096
	ds_read_b128 v[196:199], v146 offset:5120
	ds_read_b128 v[200:203], v146 offset:6144
	ds_read_b128 v[204:207], v146 offset:7168
	global_load_lds_dwordx4 v[184:185], off
	v_lshl_add_u64 v[184:185], v[184:185], 0, s[52:53]
	s_add_i32 m0, s27, 0xe000
	s_nop 0
	global_load_lds_dwordx4 v[184:185], off
	s_waitcnt lgkmcnt(8)
	s_barrier
	s_waitcnt lgkmcnt(0)
	s_waitcnt lgkmcnt(0)
	v_mfma_f32_16x16x32_bf16 v[132:135], v[140:143], v[160:163], v[132:135]
	v_mfma_f32_16x16x32_bf16 v[128:131], v[152:155], v[160:163], v[128:131]
	v_mfma_f32_16x16x32_bf16 v[116:119], v[140:143], v[172:175], v[116:119]
	v_mfma_f32_16x16x32_bf16 v[112:115], v[152:155], v[172:175], v[112:115]
	v_mfma_f32_16x16x32_bf16 v[100:103], v[140:143], v[180:183], v[100:103]
	v_mfma_f32_16x16x32_bf16 v[96:99], v[152:155], v[180:183], v[96:99]
	v_mfma_f32_16x16x32_bf16 v[84:87], v[140:143], v[200:203], v[84:87]
	v_mfma_f32_16x16x32_bf16 v[80:83], v[152:155], v[200:203], v[80:83]
	v_mfma_f32_16x16x32_bf16 v[132:135], v[148:151], v[164:167], v[132:135]
	v_mfma_f32_16x16x32_bf16 v[128:131], v[156:159], v[164:167], v[128:131]
	v_mfma_f32_16x16x32_bf16 v[116:119], v[148:151], v[176:179], v[116:119]
	v_mfma_f32_16x16x32_bf16 v[112:115], v[156:159], v[176:179], v[112:115]
	v_mfma_f32_16x16x32_bf16 v[100:103], v[148:151], v[196:199], v[100:103]
	v_mfma_f32_16x16x32_bf16 v[96:99], v[156:159], v[196:199], v[96:99]
	v_mfma_f32_16x16x32_bf16 v[84:87], v[148:151], v[204:207], v[84:87]
	v_mfma_f32_16x16x32_bf16 v[80:83], v[156:159], v[204:207], v[80:83]
	s_barrier
	s_add_i32 s4, 0, 0x14000
	s_add_i32 s5, s41, s26
	v_add_u32_e32 v0, s4, v145
	v_lshl_add_u64 v[184:185], s[42:43], 0, v[136:137]
	s_mov_b32 m0, s5
	ds_read_b128 v[208:211], v0
	ds_read_b128 v[212:215], v0 offset:1024
	ds_read_b128 v[216:219], v0 offset:2048
	ds_read_b128 v[220:223], v0 offset:3072
	global_load_lds_dwordx4 v[184:185], off
	v_lshl_add_u64 v[224:225], v[184:185], 0, s[52:53]
	s_add_i32 m0, s5, 0x2000
	s_nop 0
	global_load_lds_dwordx4 v[224:225], off
	s_barrier
	s_waitcnt lgkmcnt(0)
	s_waitcnt lgkmcnt(0)
	v_mfma_f32_16x16x32_bf16 v[124:127], v[208:211], v[160:163], v[124:127]
	v_mfma_f32_16x16x32_bf16 v[120:123], v[216:219], v[160:163], v[120:123]
	v_mfma_f32_16x16x32_bf16 v[108:111], v[208:211], v[172:175], v[108:111]
	v_mfma_f32_16x16x32_bf16 v[104:107], v[216:219], v[172:175], v[104:107]
	v_mfma_f32_16x16x32_bf16 v[92:95], v[208:211], v[180:183], v[92:95]
	v_mfma_f32_16x16x32_bf16 v[88:91], v[216:219], v[180:183], v[88:91]
	v_mfma_f32_16x16x32_bf16 v[76:79], v[208:211], v[200:203], v[76:79]
	v_mfma_f32_16x16x32_bf16 v[72:75], v[216:219], v[200:203], v[72:75]
	v_mfma_f32_16x16x32_bf16 v[124:127], v[212:215], v[164:167], v[124:127]
	v_mfma_f32_16x16x32_bf16 v[120:123], v[220:223], v[164:167], v[120:123]
	v_mfma_f32_16x16x32_bf16 v[108:111], v[212:215], v[176:179], v[108:111]
	v_mfma_f32_16x16x32_bf16 v[104:107], v[220:223], v[176:179], v[104:107]
	v_mfma_f32_16x16x32_bf16 v[92:95], v[212:215], v[196:199], v[92:95]
	v_mfma_f32_16x16x32_bf16 v[88:91], v[220:223], v[196:199], v[88:91]
	v_mfma_f32_16x16x32_bf16 v[76:79], v[212:215], v[204:207], v[76:79]
	v_mfma_f32_16x16x32_bf16 v[72:75], v[220:223], v[204:207], v[72:75]
	s_mov_b32 m0, s27
	v_lshl_add_u64 v[224:225], s[22:23], 0, v[2:3]
	s_barrier
	ds_read_b128 v[160:163], v146 offset:16384
	ds_read_b128 v[164:167], v146 offset:17408
	ds_read_b128 v[172:175], v146 offset:18432
	ds_read_b128 v[176:179], v146 offset:19456
	ds_read_b128 v[180:183], v146 offset:20480
	ds_read_b128 v[196:199], v146 offset:21504
	ds_read_b128 v[200:203], v146 offset:22528
	ds_read_b128 v[204:207], v146 offset:23552
	global_load_lds_dwordx4 v[224:225], off
	v_lshl_add_u64 v[226:227], v[224:225], 0, s[52:53]
	s_mov_b32 m0, s28
	s_nop 0
	global_load_lds_dwordx4 v[226:227], off
	s_barrier
	s_waitcnt lgkmcnt(0)
	s_waitcnt lgkmcnt(0)
	v_mfma_f32_16x16x32_bf16 v[68:71], v[140:143], v[160:163], v[68:71]
	v_mfma_f32_16x16x32_bf16 v[64:67], v[152:155], v[160:163], v[64:67]
	v_mfma_f32_16x16x32_bf16 v[52:55], v[140:143], v[172:175], v[52:55]
	v_mfma_f32_16x16x32_bf16 v[48:51], v[152:155], v[172:175], v[48:51]
	v_mfma_f32_16x16x32_bf16 v[36:39], v[140:143], v[180:183], v[36:39]
	v_mfma_f32_16x16x32_bf16 v[32:35], v[152:155], v[180:183], v[32:35]
	v_mfma_f32_16x16x32_bf16 v[20:23], v[140:143], v[200:203], v[20:23]
	v_mfma_f32_16x16x32_bf16 v[16:19], v[152:155], v[200:203], v[16:19]
	v_mfma_f32_16x16x32_bf16 v[68:71], v[148:151], v[164:167], v[68:71]
	v_mfma_f32_16x16x32_bf16 v[64:67], v[156:159], v[164:167], v[64:67]
	v_mfma_f32_16x16x32_bf16 v[52:55], v[148:151], v[176:179], v[52:55]
	v_mfma_f32_16x16x32_bf16 v[48:51], v[156:159], v[176:179], v[48:51]
	v_mfma_f32_16x16x32_bf16 v[36:39], v[148:151], v[196:199], v[36:39]
	v_mfma_f32_16x16x32_bf16 v[32:35], v[156:159], v[196:199], v[32:35]
	v_mfma_f32_16x16x32_bf16 v[20:23], v[148:151], v[204:207], v[20:23]
	v_mfma_f32_16x16x32_bf16 v[16:19], v[156:159], v[204:207], v[16:19]
	s_barrier
; #define G_STAGE(bufoff, gbase, o0, h64) do { \
;         __builtin_amdgcn_global_load_lds((const unsigned*)((const char*)(gbase) + (o0)), (LAS unsigned*)(lds + (bufoff) + ldsw), 16, 0, 0); \
;         __builtin_amdgcn_global_load_lds((const unsigned*)((const char*)(gbase) + (h64) + (o0)), (LAS unsigned*)(lds + (bufoff) + ldsw + 8192), 16, 0, 0); } while (0)
; #define G_LDA(dst, b, h) do { _Pragma("unroll") for (int m = 0; m < 4; ++m) _Pragma("unroll") for (int k = 0; k < 2; ++k) dst[m][k] = *(const LAS bf16x8*)(lds + G_SA(b, h) + aoff + m * 2048 + k * 1024); } while (0)
; #define G_LDB(dst, b, h) do { _Pragma("unroll") for (int n = 0; n < 2; ++n) _Pragma("unroll") for (int k = 0; k < 2; ++k) dst[n][k] = *(const LAS bf16x8*)(lds + G_SB(b, h) + boff + n * 2048 + k * 1024); } while (0)
; #define G_WAIT_V(n) asm volatile("s_waitcnt vmcnt(" #n ")" ::: "memory")
; #define G_WAIT_L(n) asm volatile("s_waitcnt lgkmcnt(" #n ")" ::: "memory")
; #define G_BAR __builtin_amdgcn_s_barrier()
; #define G_SCHED __builtin_amdgcn_sched_barrier(0)
;     ...
;             G_STAGE(G_SB(0, 1), b2 + chB, cB0, qB);
;             G_WAIT_V(6); G_BAR; G_MMA(1, 1, At, B1); G_BAR;
;             G_LDB(B0, 1, 0); G_SCHED; G_LDA(At, 1, 0); G_STAGE(G_SA(0, 1), a2 + chA, cA0, qA);
;             G_WAIT_L(8); G_BAR; G_WAIT_L(0); G_MMA(0, 0, At, B0); G_BAR; G_SCHED;
;             G_LDB(B1, 1, 1); G_STAGE(G_SB(1, 0), b3, cB0, qB);
;             G_BAR; G_WAIT_L(0); G_MMA(0, 1, At, B1); G_BAR;
	s_add_i32 s4, s4, s26
	v_lshl_add_u64 v[140:141], v[184:185], 0, s[0:1]
	s_mov_b32 m0, s4
	s_nop 0
	global_load_lds_dwordx4 v[140:141], off
	v_lshl_add_u64 v[140:141], v[184:185], 0, s[54:55]
	s_add_i32 m0, s4, 0x2000
	s_nop 0
	global_load_lds_dwordx4 v[140:141], off
	s_waitcnt vmcnt(6)
	s_barrier
	v_mfma_f32_16x16x32_bf16 v[60:63], v[208:211], v[160:163], v[60:63]
	v_mfma_f32_16x16x32_bf16 v[56:59], v[216:219], v[160:163], v[56:59]
	v_mfma_f32_16x16x32_bf16 v[44:47], v[208:211], v[172:175], v[44:47]
	v_mfma_f32_16x16x32_bf16 v[40:43], v[216:219], v[172:175], v[40:43]
	v_mfma_f32_16x16x32_bf16 v[28:31], v[208:211], v[180:183], v[28:31]
	v_mfma_f32_16x16x32_bf16 v[24:27], v[216:219], v[180:183], v[24:27]
	v_mfma_f32_16x16x32_bf16 v[12:15], v[208:211], v[200:203], v[12:15]
	v_mfma_f32_16x16x32_bf16 v[8:11], v[216:219], v[200:203], v[8:11]
	v_mfma_f32_16x16x32_bf16 v[60:63], v[212:215], v[164:167], v[60:63]
	v_mfma_f32_16x16x32_bf16 v[56:59], v[220:223], v[164:167], v[56:59]
	v_mfma_f32_16x16x32_bf16 v[44:47], v[212:215], v[176:179], v[44:47]
	v_mfma_f32_16x16x32_bf16 v[40:43], v[220:223], v[176:179], v[40:43]
	v_mfma_f32_16x16x32_bf16 v[28:31], v[212:215], v[196:199], v[28:31]
	v_mfma_f32_16x16x32_bf16 v[24:27], v[220:223], v[196:199], v[24:27]
	v_mfma_f32_16x16x32_bf16 v[12:15], v[212:215], v[204:207], v[12:15]
	v_mfma_f32_16x16x32_bf16 v[8:11], v[220:223], v[204:207], v[8:11]
	s_add_i32 s4, 0, 0x18000
	v_add_u32_e32 v0, s4, v145
	s_barrier
	ds_read_b128 v[140:143], v0
	ds_read_b128 v[148:151], v0 offset:1024
	ds_read_b128 v[152:155], v0 offset:2048
	ds_read_b128 v[156:159], v0 offset:3072
	s_mov_b32 m0, s29
	v_lshl_add_u64 v[208:209], v[224:225], 0, s[0:1]
	ds_read_b128 v[160:163], v146 offset:32768
	ds_read_b128 v[164:167], v146 offset:33792
	ds_read_b128 v[172:175], v146 offset:34816
	ds_read_b128 v[176:179], v146 offset:35840
	ds_read_b128 v[180:183], v146 offset:36864
	ds_read_b128 v[196:199], v146 offset:37888
	ds_read_b128 v[200:203], v146 offset:38912
	ds_read_b128 v[204:207], v146 offset:39936
	global_load_lds_dwordx4 v[208:209], off
	v_lshl_add_u64 v[208:209], v[224:225], 0, s[54:55]
	s_mov_b32 m0, s30
	s_nop 0
	global_load_lds_dwordx4 v[208:209], off
	s_waitcnt lgkmcnt(8)
	s_barrier
	s_waitcnt lgkmcnt(0)
	s_waitcnt lgkmcnt(0)
	v_mfma_f32_16x16x32_bf16 v[132:135], v[140:143], v[160:163], v[132:135]
	v_mfma_f32_16x16x32_bf16 v[128:131], v[152:155], v[160:163], v[128:131]
	v_mfma_f32_16x16x32_bf16 v[116:119], v[140:143], v[172:175], v[116:119]
	v_mfma_f32_16x16x32_bf16 v[112:115], v[152:155], v[172:175], v[112:115]
	v_mfma_f32_16x16x32_bf16 v[100:103], v[140:143], v[180:183], v[100:103]
	v_mfma_f32_16x16x32_bf16 v[96:99], v[152:155], v[180:183], v[96:99]
	v_mfma_f32_16x16x32_bf16 v[84:87], v[140:143], v[200:203], v[84:87]
	v_mfma_f32_16x16x32_bf16 v[80:83], v[152:155], v[200:203], v[80:83]
	v_mfma_f32_16x16x32_bf16 v[132:135], v[148:151], v[164:167], v[132:135]
	v_mfma_f32_16x16x32_bf16 v[128:131], v[156:159], v[164:167], v[128:131]
	v_mfma_f32_16x16x32_bf16 v[116:119], v[148:151], v[176:179], v[116:119]
	v_mfma_f32_16x16x32_bf16 v[112:115], v[156:159], v[176:179], v[112:115]
	v_mfma_f32_16x16x32_bf16 v[100:103], v[148:151], v[196:199], v[100:103]
	v_mfma_f32_16x16x32_bf16 v[96:99], v[156:159], v[196:199], v[96:99]
	v_mfma_f32_16x16x32_bf16 v[84:87], v[148:151], v[204:207], v[84:87]
	v_mfma_f32_16x16x32_bf16 v[80:83], v[156:159], v[204:207], v[80:83]
	s_barrier
	s_add_i32 s5, 0, 0x1c000
	s_add_i32 s4, s4, s26
	v_add_u32_e32 v0, s5, v145
	v_lshl_add_u64 v[226:227], v[184:185], 0, s[46:47]
	s_mov_b32 m0, s4
	ds_read_b128 v[208:211], v0
	ds_read_b128 v[212:215], v0 offset:1024
	ds_read_b128 v[216:219], v0 offset:2048
	ds_read_b128 v[220:223], v0 offset:3072
	global_load_lds_dwordx4 v[226:227], off
	v_lshl_add_u64 v[226:227], v[184:185], 0, s[58:59]
	s_add_i32 m0, s4, 0x2000
	s_nop 0
	global_load_lds_dwordx4 v[226:227], off
	s_barrier
; #define G_STAGE(bufoff, gbase, o0, h64) do { \
;         __builtin_amdgcn_global_load_lds((const unsigned*)((const char*)(gbase) + (o0)), (LAS unsigned*)(lds + (bufoff) + ldsw), 16, 0, 0); \
;         __builtin_amdgcn_global_load_lds((const unsigned*)((const char*)(gbase) + (h64) + (o0)), (LAS unsigned*)(lds + (bufoff) + ldsw + 8192), 16, 0, 0); } while (0)
; #define G_LDA(dst, b, h) do { _Pragma("unroll") for (int m = 0; m < 4; ++m) _Pragma("unroll") for (int k = 0; k < 2; ++k) dst[m][k] = *(const LAS bf16x8*)(lds + G_SA(b, h) + aoff + m * 2048 + k * 1024); } while (0)
; #define G_WAIT_V(n) asm volatile("s_waitcnt vmcnt(" #n ")" ::: "memory")
; #define G_WAIT_L(n) asm volatile("s_waitcnt lgkmcnt(" #n ")" ::: "memory")
; #define G_BAR __builtin_amdgcn_s_barrier()
; #define G_SCHED __builtin_amdgcn_sched_barrier(0)
;     ...
;             G_BAR; G_WAIT_L(0); G_MMA(0, 1, At, B1); G_BAR;
;             G_LDA(At, 1, 1); G_STAGE(G_SA(1, 0), a3, cA0, qA);
;             G_BAR; G_WAIT_L(0); G_MMA(1, 0, At, B0); G_BAR; G_SCHED;
;             G_STAGE(G_SB(1, 1), b3 + chB, cB0, qB);
;             G_WAIT_V(6); G_BAR; G_MMA(1, 1, At, B1); G_BAR;
;         }
	s_waitcnt lgkmcnt(0)
	s_waitcnt lgkmcnt(0)
	v_mfma_f32_16x16x32_bf16 v[124:127], v[208:211], v[160:163], v[124:127]
	v_mfma_f32_16x16x32_bf16 v[120:123], v[216:219], v[160:163], v[120:123]
	v_mfma_f32_16x16x32_bf16 v[108:111], v[208:211], v[172:175], v[108:111]
	v_mfma_f32_16x16x32_bf16 v[104:107], v[216:219], v[172:175], v[104:107]
	v_mfma_f32_16x16x32_bf16 v[92:95], v[208:211], v[180:183], v[92:95]
	v_mfma_f32_16x16x32_bf16 v[88:91], v[216:219], v[180:183], v[88:91]
	v_mfma_f32_16x16x32_bf16 v[76:79], v[208:211], v[200:203], v[76:79]
	v_mfma_f32_16x16x32_bf16 v[72:75], v[216:219], v[200:203], v[72:75]
	v_mfma_f32_16x16x32_bf16 v[124:127], v[212:215], v[164:167], v[124:127]
	v_mfma_f32_16x16x32_bf16 v[120:123], v[220:223], v[164:167], v[120:123]
	v_mfma_f32_16x16x32_bf16 v[108:111], v[212:215], v[176:179], v[108:111]
	v_mfma_f32_16x16x32_bf16 v[104:107], v[220:223], v[176:179], v[104:107]
	v_mfma_f32_16x16x32_bf16 v[92:95], v[212:215], v[196:199], v[92:95]
	v_mfma_f32_16x16x32_bf16 v[88:91], v[220:223], v[196:199], v[88:91]
	v_mfma_f32_16x16x32_bf16 v[76:79], v[212:215], v[204:207], v[76:79]
	v_mfma_f32_16x16x32_bf16 v[72:75], v[220:223], v[204:207], v[72:75]
	s_mov_b32 m0, s31
	v_lshl_add_u64 v[226:227], v[224:225], 0, s[46:47]
	s_barrier
	ds_read_b128 v[160:163], v146 offset:49152
	ds_read_b128 v[164:167], v146 offset:50176
	ds_read_b128 v[172:175], v146 offset:51200
	ds_read_b128 v[176:179], v146 offset:52224
	ds_read_b128 v[180:183], v146 offset:53248
	ds_read_b128 v[196:199], v146 offset:54272
	ds_read_b128 v[200:203], v146 offset:55296
	ds_read_b128 v[204:207], v146 offset:56320
	global_load_lds_dwordx4 v[226:227], off
	v_lshl_add_u64 v[224:225], v[224:225], 0, s[58:59]
	s_mov_b32 m0, s33
	s_nop 0
	global_load_lds_dwordx4 v[224:225], off
	s_barrier
	s_waitcnt lgkmcnt(0)
	s_waitcnt lgkmcnt(0)
	v_mfma_f32_16x16x32_bf16 v[68:71], v[140:143], v[160:163], v[68:71]
	v_mfma_f32_16x16x32_bf16 v[64:67], v[152:155], v[160:163], v[64:67]
	v_mfma_f32_16x16x32_bf16 v[52:55], v[140:143], v[172:175], v[52:55]
	v_mfma_f32_16x16x32_bf16 v[48:51], v[152:155], v[172:175], v[48:51]
	v_mfma_f32_16x16x32_bf16 v[36:39], v[140:143], v[180:183], v[36:39]
	v_mfma_f32_16x16x32_bf16 v[32:35], v[152:155], v[180:183], v[32:35]
	v_mfma_f32_16x16x32_bf16 v[20:23], v[140:143], v[200:203], v[20:23]
	v_mfma_f32_16x16x32_bf16 v[16:19], v[152:155], v[200:203], v[16:19]
	v_mfma_f32_16x16x32_bf16 v[68:71], v[148:151], v[164:167], v[68:71]
	v_mfma_f32_16x16x32_bf16 v[64:67], v[156:159], v[164:167], v[64:67]
	v_mfma_f32_16x16x32_bf16 v[52:55], v[148:151], v[176:179], v[52:55]
	v_mfma_f32_16x16x32_bf16 v[48:51], v[156:159], v[176:179], v[48:51]
	v_mfma_f32_16x16x32_bf16 v[36:39], v[148:151], v[196:199], v[36:39]
	v_mfma_f32_16x16x32_bf16 v[32:35], v[156:159], v[196:199], v[32:35]
	v_mfma_f32_16x16x32_bf16 v[20:23], v[148:151], v[204:207], v[20:23]
	v_mfma_f32_16x16x32_bf16 v[16:19], v[156:159], v[204:207], v[16:19]
	s_barrier
	s_add_i32 s4, s5, s26
	v_lshl_add_u64 v[140:141], v[184:185], 0, s[50:51]
	s_mov_b32 m0, s4
	s_nop 0
	global_load_lds_dwordx4 v[140:141], off
	v_lshl_add_u64 v[140:141], v[184:185], 0, s[62:63]
	s_add_i32 m0, s4, 0x2000
	s_nop 0
	global_load_lds_dwordx4 v[140:141], off
	s_waitcnt vmcnt(6)
	s_barrier
	v_mfma_f32_16x16x32_bf16 v[60:63], v[208:211], v[160:163], v[60:63]
	v_mfma_f32_16x16x32_bf16 v[56:59], v[216:219], v[160:163], v[56:59]
	v_mfma_f32_16x16x32_bf16 v[44:47], v[208:211], v[172:175], v[44:47]
	v_mfma_f32_16x16x32_bf16 v[40:43], v[216:219], v[172:175], v[40:43]
	v_mfma_f32_16x16x32_bf16 v[28:31], v[208:211], v[180:183], v[28:31]
	v_mfma_f32_16x16x32_bf16 v[24:27], v[216:219], v[180:183], v[24:27]
	v_mfma_f32_16x16x32_bf16 v[12:15], v[208:211], v[200:203], v[12:15]
	v_mfma_f32_16x16x32_bf16 v[8:11], v[216:219], v[200:203], v[8:11]
	v_mfma_f32_16x16x32_bf16 v[60:63], v[212:215], v[164:167], v[60:63]
	v_mfma_f32_16x16x32_bf16 v[56:59], v[220:223], v[164:167], v[56:59]
	v_mfma_f32_16x16x32_bf16 v[44:47], v[212:215], v[176:179], v[44:47]
	v_mfma_f32_16x16x32_bf16 v[40:43], v[220:223], v[176:179], v[40:43]
	v_mfma_f32_16x16x32_bf16 v[28:31], v[212:215], v[196:199], v[28:31]
	v_mfma_f32_16x16x32_bf16 v[24:27], v[220:223], v[196:199], v[24:27]
	v_mfma_f32_16x16x32_bf16 v[12:15], v[212:215], v[204:207], v[12:15]
	v_mfma_f32_16x16x32_bf16 v[8:11], v[220:223], v[204:207], v[8:11]
	s_add_i32 s21, s21, 2
	s_add_u32 s6, s6, 0x100
	s_addc_u32 s7, s7, 0
	s_add_u32 s19, s19, 0x100
	s_addc_u32 s20, s20, 0
	s_cmp_gt_u32 s21, 5
	s_cbranch_scc0 .Ldb_SSM1_cont
	v_readfirstlane_b32 s101, v186
	s_cmpk_gt_u32 s101, 0xff
	s_cbranch_scc1 .Ldb_SSM1_exit
	s_barrier
	s_branch .Ldb_SSM1_exit

; #define G_STAGE(bufoff, gbase, o0, h64) do { \
;         __builtin_amdgcn_global_load_lds((const unsigned*)((const char*)(gbase) + (o0)), (LAS unsigned*)(lds + (bufoff) + ldsw), 16, 0, 0); \
;         __builtin_amdgcn_global_load_lds((const unsigned*)((const char*)(gbase) + (h64) + (o0)), (LAS unsigned*)(lds + (bufoff) + ldsw + 8192), 16, 0, 0); } while (0)
; #define G_LDA(dst, b, h) do { _Pragma("unroll") for (int m = 0; m < 4; ++m) _Pragma("unroll") for (int k = 0; k < 2; ++k) dst[m][k] = *(const LAS bf16x8*)(lds + G_SA(b, h) + aoff + m * 2048 + k * 1024); } while (0)
; #define G_LDB(dst, b, h) do { _Pragma("unroll") for (int n = 0; n < 2; ++n) _Pragma("unroll") for (int k = 0; k < 2; ++k) dst[n][k] = *(const LAS bf16x8*)(lds + G_SB(b, h) + boff + n * 2048 + k * 1024); } while (0)
; #define G_WAIT_L(n) asm volatile("s_waitcnt lgkmcnt(" #n ")" ::: "memory")
; #define G_BAR __builtin_amdgcn_s_barrier()
; #define G_SCHED __builtin_amdgcn_sched_barrier(0)
;     ...
;         for (int t = 0; t < nt; t += 2) {
;             const bool last = (t == nt - 2);
;             const char* a1 = cA + (size_t)(t + 1) * ckA;
;             const char* a2 = last ? nA : cA + (size_t)(t + 2) * ckA; const char* b2 = last ? nB : cB + (size_t)(t + 2) * kB;
;             const char* a3 = a2 + ckA; const char* b3 = b2 + kB;
;             G_LDB(B0, 0, 0); G_SCHED; G_LDA(At, 0, 0); G_STAGE(G_SA(1, 1), a1 + chA, cA0, qA);
;             G_WAIT_L(8); G_BAR; G_WAIT_L(0); G_MMA(0, 0, At, B0); G_BAR; G_SCHED;
;             G_LDB(B1, 0, 1); G_STAGE(G_SB(0, 0), b2, cB0, qB);
;             G_BAR; G_WAIT_L(0); G_MMA(0, 1, At, B1); G_BAR;
;             G_LDA(At, 0, 1); G_STAGE(G_SA(0, 0), a2, cA0, qA);
;             G_BAR; G_WAIT_L(0); G_MMA(1, 0, At, B0); G_BAR; G_SCHED;
.Ldbj_SSM2_in:
.LBB0_742:
	s_add_u32 s36, s2, s30
	s_addc_u32 s37, s3, s31
	s_add_u32 s19, s36, 0x100
	s_addc_u32 s35, s37, 0
	s_and_b64 s[4:5], s[26:27], exec
	s_cselect_b32 s34, s12, s19
	s_cselect_b32 s35, s13, s35
	s_add_u32 s4, s20, s30
	s_addc_u32 s5, s21, s31
	s_add_u32 s19, s4, 0x100
	s_addc_u32 s30, s5, 0
	s_add_i32 s44, 0, 0x10000
	v_add_u32_e32 v0, s44, v183
	ds_read_b128 v[56:59], v0
	ds_read_b128 v[60:63], v0 offset:1024
	ds_read_b128 v[144:147], v0 offset:2048
	ds_read_b128 v[148:151], v0 offset:3072
	s_and_b64 s[4:5], s[26:27], exec
	s_cselect_b32 s26, s16, s19
	s_cselect_b32 s27, s17, s30
	s_add_i32 s48, 0, 0x14000
	s_add_i32 s31, 0, 0x18000
	s_add_i32 s19, 0, 0x1c000
	s_add_i32 s49, s44, s38
	s_add_i32 s63, s48, s38
	s_add_i32 s30, s31, s38
	s_add_i32 s65, s19, s38
	s_add_i32 m0, s43, 0xc000
	s_add_i32 s45, s43, 0xe000
	s_add_i32 s66, s49, 0x2000
	s_add_i32 s62, s63, 0x2000
	s_add_i32 s67, s30, 0x2000
	s_add_i32 s64, s65, 0x2000
	v_lshl_add_u64 v[166:167], s[36:37], 0, v[160:161]
	s_mov_b64 s[4:5], 0x200080
	v_lshl_add_u64 v[180:181], v[166:167], 0, s[4:5]
	s_mov_b64 s[4:5], 0x300080
	ds_read_b128 v[152:155], v184
	ds_read_b128 v[156:159], v184 offset:1024
	ds_read_b128 v[162:165], v184 offset:2048
	ds_read_b128 v[172:175], v184 offset:3072
	ds_read_b128 v[176:179], v184 offset:4096
	ds_read_b128 v[196:199], v184 offset:5120
	ds_read_b128 v[200:203], v184 offset:6144
	ds_read_b128 v[204:207], v184 offset:7168
	global_load_lds_dwordx4 v[180:181], off
	v_lshl_add_u64 v[166:167], v[166:167], 0, s[4:5]
	s_mov_b32 m0, s45
	s_nop 0
	global_load_lds_dwordx4 v[166:167], off
	s_waitcnt lgkmcnt(8)
	s_barrier
	s_waitcnt lgkmcnt(0)
	s_waitcnt lgkmcnt(0)
	v_mfma_f32_16x16x32_bf16 v[140:143], v[56:59], v[152:155], v[140:143]
	v_mfma_f32_16x16x32_bf16 v[136:139], v[144:147], v[152:155], v[136:139]
	v_mfma_f32_16x16x32_bf16 v[124:127], v[56:59], v[162:165], v[124:127]
	v_mfma_f32_16x16x32_bf16 v[120:123], v[144:147], v[162:165], v[120:123]
	v_mfma_f32_16x16x32_bf16 v[108:111], v[56:59], v[176:179], v[108:111]
	v_mfma_f32_16x16x32_bf16 v[104:107], v[144:147], v[176:179], v[104:107]
	v_mfma_f32_16x16x32_bf16 v[92:95], v[56:59], v[200:203], v[92:95]
	v_mfma_f32_16x16x32_bf16 v[88:91], v[144:147], v[200:203], v[88:91]
	v_mfma_f32_16x16x32_bf16 v[140:143], v[60:63], v[156:159], v[140:143]
	v_mfma_f32_16x16x32_bf16 v[136:139], v[148:151], v[156:159], v[136:139]
	v_mfma_f32_16x16x32_bf16 v[124:127], v[60:63], v[172:175], v[124:127]
	v_mfma_f32_16x16x32_bf16 v[120:123], v[148:151], v[172:175], v[120:123]
	v_mfma_f32_16x16x32_bf16 v[108:111], v[60:63], v[196:199], v[108:111]
	v_mfma_f32_16x16x32_bf16 v[104:107], v[148:151], v[196:199], v[104:107]
	v_mfma_f32_16x16x32_bf16 v[92:95], v[60:63], v[204:207], v[92:95]
	v_mfma_f32_16x16x32_bf16 v[88:91], v[148:151], v[204:207], v[88:91]
	s_barrier
	s_mov_b32 m0, s49
	v_add_u32_e32 v0, s48, v183
	v_lshl_add_u64 v[166:167], s[26:27], 0, v[2:3]
	ds_read_b128 v[208:211], v0
	ds_read_b128 v[212:215], v0 offset:1024
	ds_read_b128 v[216:219], v0 offset:2048
	ds_read_b128 v[220:223], v0 offset:3072
	global_load_lds_dwordx4 v[166:167], off
	v_lshl_add_u64 v[180:181], v[166:167], 0, s[92:93]
	s_mov_b32 m0, s66
	s_nop 0
	global_load_lds_dwordx4 v[180:181], off
	s_barrier
	s_waitcnt lgkmcnt(0)
	s_waitcnt lgkmcnt(0)
	v_mfma_f32_16x16x32_bf16 v[132:135], v[208:211], v[152:155], v[132:135]
	v_mfma_f32_16x16x32_bf16 v[128:131], v[216:219], v[152:155], v[128:131]
	v_mfma_f32_16x16x32_bf16 v[116:119], v[208:211], v[162:165], v[116:119]
	v_mfma_f32_16x16x32_bf16 v[112:115], v[216:219], v[162:165], v[112:115]
	v_mfma_f32_16x16x32_bf16 v[100:103], v[208:211], v[176:179], v[100:103]
	v_mfma_f32_16x16x32_bf16 v[96:99], v[216:219], v[176:179], v[96:99]
	v_mfma_f32_16x16x32_bf16 v[84:87], v[208:211], v[200:203], v[84:87]
	v_mfma_f32_16x16x32_bf16 v[80:83], v[216:219], v[200:203], v[80:83]
	v_mfma_f32_16x16x32_bf16 v[132:135], v[212:215], v[156:159], v[132:135]
	v_mfma_f32_16x16x32_bf16 v[128:131], v[220:223], v[156:159], v[128:131]
	v_mfma_f32_16x16x32_bf16 v[116:119], v[212:215], v[172:175], v[116:119]
	v_mfma_f32_16x16x32_bf16 v[112:115], v[220:223], v[172:175], v[112:115]
	v_mfma_f32_16x16x32_bf16 v[100:103], v[212:215], v[196:199], v[100:103]
	v_mfma_f32_16x16x32_bf16 v[96:99], v[220:223], v[196:199], v[96:99]
	v_mfma_f32_16x16x32_bf16 v[84:87], v[212:215], v[204:207], v[84:87]
	v_mfma_f32_16x16x32_bf16 v[80:83], v[220:223], v[204:207], v[80:83]
	s_mov_b32 m0, s43
	v_lshl_add_u64 v[180:181], s[34:35], 0, v[160:161]
	s_barrier
	ds_read_b128 v[152:155], v184 offset:16384
	ds_read_b128 v[156:159], v184 offset:17408
	ds_read_b128 v[162:165], v184 offset:18432
	ds_read_b128 v[172:175], v184 offset:19456
	ds_read_b128 v[176:179], v184 offset:20480
	ds_read_b128 v[196:199], v184 offset:21504
	ds_read_b128 v[200:203], v184 offset:22528
	ds_read_b128 v[204:207], v184 offset:23552
	global_load_lds_dwordx4 v[180:181], off
	v_lshl_add_u64 v[224:225], v[180:181], 0, s[88:89]
	s_mov_b32 m0, s50
	s_nop 0
	global_load_lds_dwordx4 v[224:225], off
	s_barrier
	s_waitcnt lgkmcnt(0)
	s_waitcnt lgkmcnt(0)
	v_mfma_f32_16x16x32_bf16 v[76:79], v[56:59], v[152:155], v[76:79]
	v_mfma_f32_16x16x32_bf16 v[72:75], v[144:147], v[152:155], v[72:75]
	v_mfma_f32_16x16x32_bf16 v[52:55], v[56:59], v[162:165], v[52:55]
	v_mfma_f32_16x16x32_bf16 v[48:51], v[144:147], v[162:165], v[48:51]
	v_mfma_f32_16x16x32_bf16 v[36:39], v[56:59], v[176:179], v[36:39]
	v_mfma_f32_16x16x32_bf16 v[32:35], v[144:147], v[176:179], v[32:35]
	v_mfma_f32_16x16x32_bf16 v[20:23], v[56:59], v[200:203], v[20:23]
	v_mfma_f32_16x16x32_bf16 v[16:19], v[144:147], v[200:203], v[16:19]
	v_mfma_f32_16x16x32_bf16 v[76:79], v[60:63], v[156:159], v[76:79]
	v_mfma_f32_16x16x32_bf16 v[72:75], v[148:151], v[156:159], v[72:75]
	v_mfma_f32_16x16x32_bf16 v[52:55], v[60:63], v[172:175], v[52:55]
	v_mfma_f32_16x16x32_bf16 v[48:51], v[148:151], v[172:175], v[48:51]
	v_mfma_f32_16x16x32_bf16 v[36:39], v[60:63], v[196:199], v[36:39]
	v_mfma_f32_16x16x32_bf16 v[32:35], v[148:151], v[196:199], v[32:35]
	v_mfma_f32_16x16x32_bf16 v[20:23], v[60:63], v[204:207], v[20:23]
	v_mfma_f32_16x16x32_bf16 v[16:19], v[148:151], v[204:207], v[16:19]
	s_barrier
; #define G_STAGE(bufoff, gbase, o0, h64) do { \
;         __builtin_amdgcn_global_load_lds((const unsigned*)((const char*)(gbase) + (o0)), (LAS unsigned*)(lds + (bufoff) + ldsw), 16, 0, 0); \
;         __builtin_amdgcn_global_load_lds((const unsigned*)((const char*)(gbase) + (h64) + (o0)), (LAS unsigned*)(lds + (bufoff) + ldsw + 8192), 16, 0, 0); } while (0)
; #define G_LDA(dst, b, h) do { _Pragma("unroll") for (int m = 0; m < 4; ++m) _Pragma("unroll") for (int k = 0; k < 2; ++k) dst[m][k] = *(const LAS bf16x8*)(lds + G_SA(b, h) + aoff + m * 2048 + k * 1024); } while (0)
; #define G_LDB(dst, b, h) do { _Pragma("unroll") for (int n = 0; n < 2; ++n) _Pragma("unroll") for (int k = 0; k < 2; ++k) dst[n][k] = *(const LAS bf16x8*)(lds + G_SB(b, h) + boff + n * 2048 + k * 1024); } while (0)
; #define G_WAIT_V(n) asm volatile("s_waitcnt vmcnt(" #n ")" ::: "memory")
; #define G_WAIT_L(n) asm volatile("s_waitcnt lgkmcnt(" #n ")" ::: "memory")
; #define G_BAR __builtin_amdgcn_s_barrier()
; #define G_SCHED __builtin_amdgcn_sched_barrier(0)
;     ...
;             G_STAGE(G_SB(0, 1), b2 + chB, cB0, qB);
;             G_WAIT_V(6); G_BAR; G_MMA(1, 1, At, B1); G_BAR;
;             G_LDB(B0, 1, 0); G_SCHED; G_LDA(At, 1, 0); G_STAGE(G_SA(0, 1), a2 + chA, cA0, qA);
;             G_WAIT_L(8); G_BAR; G_WAIT_L(0); G_MMA(0, 0, At, B0); G_BAR; G_SCHED;
;             G_LDB(B1, 1, 1); G_STAGE(G_SB(1, 0), b3, cB0, qB);
;             G_BAR; G_WAIT_L(0); G_MMA(0, 1, At, B1); G_BAR;
	s_mov_b32 m0, s63
	v_lshl_add_u64 v[56:57], v[166:167], 0, s[82:83]
	global_load_lds_dwordx4 v[56:57], off
	v_lshl_add_u64 v[56:57], v[166:167], 0, s[94:95]
	s_mov_b32 m0, s62
	s_nop 0
	global_load_lds_dwordx4 v[56:57], off
	s_waitcnt vmcnt(6)
	s_barrier
	v_mfma_f32_16x16x32_bf16 v[44:47], v[208:211], v[162:165], v[44:47]
	v_mfma_f32_16x16x32_bf16 v[40:43], v[216:219], v[162:165], v[40:43]
	v_mfma_f32_16x16x32_bf16 v[28:31], v[208:211], v[176:179], v[28:31]
	v_mfma_f32_16x16x32_bf16 v[24:27], v[216:219], v[176:179], v[24:27]
	v_mfma_f32_16x16x32_bf16 v[12:15], v[208:211], v[200:203], v[12:15]
	v_mfma_f32_16x16x32_bf16 v[8:11], v[216:219], v[200:203], v[8:11]
	v_mfma_f32_16x16x32_bf16 v[56:59], v[208:211], v[152:155], v[68:71]
	v_mfma_f32_16x16x32_bf16 v[60:63], v[216:219], v[152:155], v[64:67]
	v_mfma_f32_16x16x32_bf16 v[44:47], v[212:215], v[172:175], v[44:47]
	v_mfma_f32_16x16x32_bf16 v[40:43], v[220:223], v[172:175], v[40:43]
	v_mfma_f32_16x16x32_bf16 v[28:31], v[212:215], v[196:199], v[28:31]
	v_mfma_f32_16x16x32_bf16 v[24:27], v[220:223], v[196:199], v[24:27]
	v_mfma_f32_16x16x32_bf16 v[12:15], v[212:215], v[204:207], v[12:15]
	v_mfma_f32_16x16x32_bf16 v[8:11], v[220:223], v[204:207], v[8:11]
	v_mfma_f32_16x16x32_bf16 v[56:59], v[212:215], v[156:159], v[56:59]
	v_mfma_f32_16x16x32_bf16 v[60:63], v[220:223], v[156:159], v[60:63]
	v_add_u32_e32 v0, s31, v183
	s_barrier
	ds_read_b128 v[64:67], v0
	ds_read_b128 v[68:71], v0 offset:1024
	ds_read_b128 v[144:147], v0 offset:2048
	ds_read_b128 v[148:151], v0 offset:3072
	s_mov_b32 m0, s51
	v_lshl_add_u64 v[208:209], v[180:181], 0, s[86:87]
	ds_read_b128 v[152:155], v184 offset:32768
	ds_read_b128 v[156:159], v184 offset:33792
	ds_read_b128 v[162:165], v184 offset:34816
	ds_read_b128 v[172:175], v184 offset:35840
	ds_read_b128 v[176:179], v184 offset:36864
	ds_read_b128 v[196:199], v184 offset:37888
	ds_read_b128 v[200:203], v184 offset:38912
	ds_read_b128 v[204:207], v184 offset:39936
	global_load_lds_dwordx4 v[208:209], off
	v_lshl_add_u64 v[208:209], v[180:181], 0, s[96:97]
	s_mov_b32 m0, s52
	s_nop 0
	global_load_lds_dwordx4 v[208:209], off
	s_waitcnt lgkmcnt(8)
	s_barrier
	s_waitcnt lgkmcnt(0)
	s_waitcnt lgkmcnt(0)
	v_mfma_f32_16x16x32_bf16 v[140:143], v[64:67], v[152:155], v[140:143]
	v_mfma_f32_16x16x32_bf16 v[136:139], v[144:147], v[152:155], v[136:139]
	v_mfma_f32_16x16x32_bf16 v[124:127], v[64:67], v[162:165], v[124:127]
	v_mfma_f32_16x16x32_bf16 v[120:123], v[144:147], v[162:165], v[120:123]
	v_mfma_f32_16x16x32_bf16 v[108:111], v[64:67], v[176:179], v[108:111]
	v_mfma_f32_16x16x32_bf16 v[104:107], v[144:147], v[176:179], v[104:107]
	v_mfma_f32_16x16x32_bf16 v[92:95], v[64:67], v[200:203], v[92:95]
	v_mfma_f32_16x16x32_bf16 v[88:91], v[144:147], v[200:203], v[88:91]
	v_mfma_f32_16x16x32_bf16 v[140:143], v[68:71], v[156:159], v[140:143]
	v_mfma_f32_16x16x32_bf16 v[136:139], v[148:151], v[156:159], v[136:139]
	v_mfma_f32_16x16x32_bf16 v[124:127], v[68:71], v[172:175], v[124:127]
	v_mfma_f32_16x16x32_bf16 v[120:123], v[148:151], v[172:175], v[120:123]
	v_mfma_f32_16x16x32_bf16 v[108:111], v[68:71], v[196:199], v[108:111]
	v_mfma_f32_16x16x32_bf16 v[104:107], v[148:151], v[196:199], v[104:107]
	v_mfma_f32_16x16x32_bf16 v[92:95], v[68:71], v[204:207], v[92:95]
	v_mfma_f32_16x16x32_bf16 v[88:91], v[148:151], v[204:207], v[88:91]
	s_barrier
	s_mov_b32 m0, s30
	v_add_u32_e32 v0, s19, v183
	v_lshl_add_u64 v[224:225], v[166:167], 0, s[46:47]
	ds_read_b128 v[208:211], v0
	ds_read_b128 v[212:215], v0 offset:1024
	ds_read_b128 v[216:219], v0 offset:2048
	ds_read_b128 v[220:223], v0 offset:3072
	global_load_lds_dwordx4 v[224:225], off
	v_lshl_add_u64 v[224:225], v[166:167], 0, s[70:71]
	s_mov_b32 m0, s67
	s_nop 0
	global_load_lds_dwordx4 v[224:225], off
	s_barrier
; #define G_STAGE(bufoff, gbase, o0, h64) do { \
;         __builtin_amdgcn_global_load_lds((const unsigned*)((const char*)(gbase) + (o0)), (LAS unsigned*)(lds + (bufoff) + ldsw), 16, 0, 0); \
;         __builtin_amdgcn_global_load_lds((const unsigned*)((const char*)(gbase) + (h64) + (o0)), (LAS unsigned*)(lds + (bufoff) + ldsw + 8192), 16, 0, 0); } while (0)
; #define G_LDA(dst, b, h) do { _Pragma("unroll") for (int m = 0; m < 4; ++m) _Pragma("unroll") for (int k = 0; k < 2; ++k) dst[m][k] = *(const LAS bf16x8*)(lds + G_SA(b, h) + aoff + m * 2048 + k * 1024); } while (0)
; #define G_WAIT_V(n) asm volatile("s_waitcnt vmcnt(" #n ")" ::: "memory")
; #define G_WAIT_L(n) asm volatile("s_waitcnt lgkmcnt(" #n ")" ::: "memory")
; #define G_BAR __builtin_amdgcn_s_barrier()
; #define G_SCHED __builtin_amdgcn_sched_barrier(0)
;     ...
;             G_BAR; G_WAIT_L(0); G_MMA(0, 1, At, B1); G_BAR;
;             G_LDA(At, 1, 1); G_STAGE(G_SA(1, 0), a3, cA0, qA);
;             G_BAR; G_WAIT_L(0); G_MMA(1, 0, At, B0); G_BAR; G_SCHED;
;             G_STAGE(G_SB(1, 1), b3 + chB, cB0, qB);
;             G_WAIT_V(6); G_BAR; G_MMA(1, 1, At, B1); G_BAR;
;         }
	s_waitcnt lgkmcnt(0)
	s_waitcnt lgkmcnt(0)
	v_mfma_f32_16x16x32_bf16 v[132:135], v[208:211], v[152:155], v[132:135]
	v_mfma_f32_16x16x32_bf16 v[128:131], v[216:219], v[152:155], v[128:131]
	v_mfma_f32_16x16x32_bf16 v[116:119], v[208:211], v[162:165], v[116:119]
	v_mfma_f32_16x16x32_bf16 v[112:115], v[216:219], v[162:165], v[112:115]
	v_mfma_f32_16x16x32_bf16 v[100:103], v[208:211], v[176:179], v[100:103]
	v_mfma_f32_16x16x32_bf16 v[96:99], v[216:219], v[176:179], v[96:99]
	v_mfma_f32_16x16x32_bf16 v[84:87], v[208:211], v[200:203], v[84:87]
	v_mfma_f32_16x16x32_bf16 v[80:83], v[216:219], v[200:203], v[80:83]
	v_mfma_f32_16x16x32_bf16 v[132:135], v[212:215], v[156:159], v[132:135]
	v_mfma_f32_16x16x32_bf16 v[128:131], v[220:223], v[156:159], v[128:131]
	v_mfma_f32_16x16x32_bf16 v[116:119], v[212:215], v[172:175], v[116:119]
	v_mfma_f32_16x16x32_bf16 v[112:115], v[220:223], v[172:175], v[112:115]
	v_mfma_f32_16x16x32_bf16 v[100:103], v[212:215], v[196:199], v[100:103]
	v_mfma_f32_16x16x32_bf16 v[96:99], v[220:223], v[196:199], v[96:99]
	v_mfma_f32_16x16x32_bf16 v[84:87], v[212:215], v[204:207], v[84:87]
	v_mfma_f32_16x16x32_bf16 v[80:83], v[220:223], v[204:207], v[80:83]
	s_mov_b32 m0, s53
	v_lshl_add_u64 v[224:225], v[180:181], 0, s[46:47]
	s_barrier
	ds_read_b128 v[152:155], v184 offset:49152
	ds_read_b128 v[156:159], v184 offset:50176
	ds_read_b128 v[162:165], v184 offset:51200
	ds_read_b128 v[172:175], v184 offset:52224
	ds_read_b128 v[176:179], v184 offset:53248
	ds_read_b128 v[196:199], v184 offset:54272
	ds_read_b128 v[200:203], v184 offset:55296
	ds_read_b128 v[204:207], v184 offset:56320
	global_load_lds_dwordx4 v[224:225], off
	v_lshl_add_u64 v[180:181], v[180:181], 0, s[68:69]
	s_mov_b32 m0, s54
	s_nop 0
	global_load_lds_dwordx4 v[180:181], off
	s_barrier
	s_waitcnt lgkmcnt(0)
	s_waitcnt lgkmcnt(0)
	v_mfma_f32_16x16x32_bf16 v[76:79], v[64:67], v[152:155], v[76:79]
	v_mfma_f32_16x16x32_bf16 v[72:75], v[144:147], v[152:155], v[72:75]
	v_mfma_f32_16x16x32_bf16 v[52:55], v[64:67], v[162:165], v[52:55]
	v_mfma_f32_16x16x32_bf16 v[48:51], v[144:147], v[162:165], v[48:51]
	v_mfma_f32_16x16x32_bf16 v[36:39], v[64:67], v[176:179], v[36:39]
	v_mfma_f32_16x16x32_bf16 v[32:35], v[144:147], v[176:179], v[32:35]
	v_mfma_f32_16x16x32_bf16 v[20:23], v[64:67], v[200:203], v[20:23]
	v_mfma_f32_16x16x32_bf16 v[16:19], v[144:147], v[200:203], v[16:19]
	v_mfma_f32_16x16x32_bf16 v[76:79], v[68:71], v[156:159], v[76:79]
	v_mfma_f32_16x16x32_bf16 v[72:75], v[148:151], v[156:159], v[72:75]
	v_mfma_f32_16x16x32_bf16 v[52:55], v[68:71], v[172:175], v[52:55]
	v_mfma_f32_16x16x32_bf16 v[48:51], v[148:151], v[172:175], v[48:51]
	v_mfma_f32_16x16x32_bf16 v[36:39], v[68:71], v[196:199], v[36:39]
	v_mfma_f32_16x16x32_bf16 v[32:35], v[148:151], v[196:199], v[32:35]
	v_mfma_f32_16x16x32_bf16 v[20:23], v[68:71], v[204:207], v[20:23]
	v_mfma_f32_16x16x32_bf16 v[16:19], v[148:151], v[204:207], v[16:19]
	s_barrier
	s_mov_b32 m0, s65
	v_lshl_add_u64 v[64:65], v[166:167], 0, s[84:85]
	global_load_lds_dwordx4 v[64:65], off
	v_lshl_add_u64 v[64:65], v[166:167], 0, s[28:29]
	s_mov_b32 m0, s64
	s_nop 0
	global_load_lds_dwordx4 v[64:65], off
	s_waitcnt vmcnt(6)
	s_barrier
	v_mfma_f32_16x16x32_bf16 v[56:59], v[208:211], v[152:155], v[56:59]
	v_mfma_f32_16x16x32_bf16 v[68:71], v[212:215], v[156:159], v[56:59]
	v_mfma_f32_16x16x32_bf16 v[56:59], v[216:219], v[152:155], v[60:63]
	v_mfma_f32_16x16x32_bf16 v[44:47], v[208:211], v[162:165], v[44:47]
	v_mfma_f32_16x16x32_bf16 v[40:43], v[216:219], v[162:165], v[40:43]
	v_mfma_f32_16x16x32_bf16 v[28:31], v[208:211], v[176:179], v[28:31]
	v_mfma_f32_16x16x32_bf16 v[24:27], v[216:219], v[176:179], v[24:27]
	v_mfma_f32_16x16x32_bf16 v[12:15], v[208:211], v[200:203], v[12:15]
	v_mfma_f32_16x16x32_bf16 v[8:11], v[216:219], v[200:203], v[8:11]
	v_mfma_f32_16x16x32_bf16 v[64:67], v[220:223], v[156:159], v[56:59]
	v_mfma_f32_16x16x32_bf16 v[44:47], v[212:215], v[172:175], v[44:47]
	v_mfma_f32_16x16x32_bf16 v[40:43], v[220:223], v[172:175], v[40:43]
	v_mfma_f32_16x16x32_bf16 v[28:31], v[212:215], v[196:199], v[28:31]
	v_mfma_f32_16x16x32_bf16 v[24:27], v[220:223], v[196:199], v[24:27]
	v_mfma_f32_16x16x32_bf16 v[12:15], v[212:215], v[204:207], v[12:15]
	v_mfma_f32_16x16x32_bf16 v[8:11], v[220:223], v[204:207], v[8:11]
	s_andn2_b64 vcc, exec, s[24:25]
	s_mov_b64 s[26:27], -1
	s_mov_b64 s[24:25], 0
	s_mov_b64 s[30:31], 0x100
	s_cbranch_vccz .Ldb_SSM2_cont
	v_readfirstlane_b32 s101, v186
	s_cmpk_gt_u32 s101, 0xff
	s_cbranch_scc1 .Ldb_SSM2_exit
	s_barrier
	s_branch .Ldb_SSM2_exit

; #define G_STAGE(bufoff, gbase, o0, h64) do { \
;         __builtin_amdgcn_global_load_lds((const unsigned*)((const char*)(gbase) + (o0)), (LAS unsigned*)(lds + (bufoff) + ldsw), 16, 0, 0); \
;         __builtin_amdgcn_global_load_lds((const unsigned*)((const char*)(gbase) + (h64) + (o0)), (LAS unsigned*)(lds + (bufoff) + ldsw + 8192), 16, 0, 0); } while (0)
; #define G_LDA(dst, b, h) do { _Pragma("unroll") for (int m = 0; m < 4; ++m) _Pragma("unroll") for (int k = 0; k < 2; ++k) dst[m][k] = *(const LAS bf16x8*)(lds + G_SA(b, h) + aoff + m * 2048 + k * 1024); } while (0)
; #define G_LDB(dst, b, h) do { _Pragma("unroll") for (int n = 0; n < 2; ++n) _Pragma("unroll") for (int k = 0; k < 2; ++k) dst[n][k] = *(const LAS bf16x8*)(lds + G_SB(b, h) + boff + n * 2048 + k * 1024); } while (0)
; #define G_WAIT_L(n) asm volatile("s_waitcnt lgkmcnt(" #n ")" ::: "memory")
; #define G_BAR __builtin_amdgcn_s_barrier()
; #define G_SCHED __builtin_amdgcn_sched_barrier(0)
;     ...
;         for (int t = 0; t < nt; t += 2) {
;             const bool last = (t == nt - 2);
;             const char* a1 = cA + (size_t)(t + 1) * ckA;
;             const char* a2 = last ? nA : cA + (size_t)(t + 2) * ckA; const char* b2 = last ? nB : cB + (size_t)(t + 2) * kB;
;             const char* a3 = a2 + ckA; const char* b3 = b2 + kB;
;             G_LDB(B0, 0, 0); G_SCHED; G_LDA(At, 0, 0); G_STAGE(G_SA(1, 1), a1 + chA, cA0, qA);
;             G_WAIT_L(8); G_BAR; G_WAIT_L(0); G_MMA(0, 0, At, B0); G_BAR; G_SCHED;
;             G_LDB(B1, 0, 1); G_STAGE(G_SB(0, 0), b2, cB0, qB);
;             G_BAR; G_WAIT_L(0); G_MMA(0, 1, At, B1); G_BAR;
;             G_LDA(At, 0, 1); G_STAGE(G_SA(0, 0), a2, cA0, qA);
;             G_BAR; G_WAIT_L(0); G_MMA(1, 0, At, B0); G_BAR; G_SCHED;
.Ldbj_GLU_in:
.LBB0_804:
	s_add_i32 s40, 0, 0x10000
	v_add_u32_e32 v0, s40, v196
	ds_read_b128 v[112:115], v0
	ds_read_b128 v[124:127], v0 offset:1024
	ds_read_b128 v[136:139], v0 offset:2048
	ds_read_b128 v[148:151], v0 offset:3072
	s_cmp_eq_u32 s19, 4
	s_cselect_b32 s5, s15, s3
	s_cselect_b32 s4, s14, s2
	s_cselect_b32 s37, s17, s18
	s_cselect_b32 s36, s16, s13
	s_mov_b32 s38, 0xffc01000
	v_lshl_add_u64 v[184:185], s[2:3], 0, v[166:167]
	s_mov_b32 s39, -1
	v_lshl_add_u64 v[206:207], v[184:185], 0, s[38:39]
	s_mov_b32 s38, 0xffc01800
	s_add_i32 m0, s24, 0xc000
	s_mov_b32 s39, -1
	ds_read_b128 v[152:155], v197
	ds_read_b128 v[156:159], v197 offset:1024
	ds_read_b128 v[160:163], v197 offset:2048
	ds_read_b128 v[172:175], v197 offset:3072
	ds_read_b128 v[176:179], v197 offset:4096
	ds_read_b128 v[180:183], v197 offset:5120
	ds_read_b128 v[198:201], v197 offset:6144
	ds_read_b128 v[202:205], v197 offset:7168
	global_load_lds_dwordx4 v[206:207], off
	v_lshl_add_u64 v[184:185], v[184:185], 0, s[38:39]
	s_add_i32 m0, s24, 0xe000
	s_nop 0
	global_load_lds_dwordx4 v[184:185], off
	s_waitcnt lgkmcnt(8)
	s_barrier
	s_waitcnt lgkmcnt(0)
	s_waitcnt lgkmcnt(0)
	v_mfma_f32_16x16x32_bf16 v[144:147], v[112:115], v[152:155], v[144:147]
	v_mfma_f32_16x16x32_bf16 v[140:143], v[136:139], v[152:155], v[140:143]
	v_mfma_f32_16x16x32_bf16 v[120:123], v[112:115], v[160:163], v[120:123]
	v_mfma_f32_16x16x32_bf16 v[116:119], v[136:139], v[160:163], v[116:119]
	v_mfma_f32_16x16x32_bf16 v[100:103], v[112:115], v[176:179], v[100:103]
	v_mfma_f32_16x16x32_bf16 v[96:99], v[136:139], v[176:179], v[96:99]
	v_mfma_f32_16x16x32_bf16 v[84:87], v[112:115], v[198:201], v[84:87]
	v_mfma_f32_16x16x32_bf16 v[80:83], v[136:139], v[198:201], v[80:83]
	v_mfma_f32_16x16x32_bf16 v[144:147], v[124:127], v[156:159], v[144:147]
	v_mfma_f32_16x16x32_bf16 v[140:143], v[148:151], v[156:159], v[140:143]
	v_mfma_f32_16x16x32_bf16 v[120:123], v[124:127], v[172:175], v[120:123]
	v_mfma_f32_16x16x32_bf16 v[116:119], v[148:151], v[172:175], v[116:119]
	v_mfma_f32_16x16x32_bf16 v[100:103], v[124:127], v[180:183], v[100:103]
	v_mfma_f32_16x16x32_bf16 v[96:99], v[148:151], v[180:183], v[96:99]
	v_mfma_f32_16x16x32_bf16 v[84:87], v[124:127], v[202:205], v[84:87]
	v_mfma_f32_16x16x32_bf16 v[80:83], v[148:151], v[202:205], v[80:83]
	s_barrier
	s_add_i32 s38, 0, 0x14000
	v_lshl_add_u64 v[184:185], s[36:37], 0, v[2:3]
	s_add_i32 s36, s40, s21
	v_add_u32_e32 v0, s38, v196
	s_mov_b32 m0, s36
	ds_read_b128 v[206:209], v0
	ds_read_b128 v[210:213], v0 offset:1024
	ds_read_b128 v[214:217], v0 offset:2048
	ds_read_b128 v[218:221], v0 offset:3072
	global_load_lds_dwordx4 v[184:185], off
	v_lshl_add_u64 v[222:223], v[184:185], 0, s[50:51]
	s_add_i32 m0, s36, 0x2000
	s_nop 0
	global_load_lds_dwordx4 v[222:223], off
	s_barrier
	s_waitcnt lgkmcnt(0)
	s_waitcnt lgkmcnt(0)
	v_mfma_f32_16x16x32_bf16 v[132:135], v[206:209], v[152:155], v[132:135]
	v_mfma_f32_16x16x32_bf16 v[128:131], v[214:217], v[152:155], v[128:131]
	v_mfma_f32_16x16x32_bf16 v[108:111], v[206:209], v[160:163], v[108:111]
	v_mfma_f32_16x16x32_bf16 v[104:107], v[214:217], v[160:163], v[104:107]
	v_mfma_f32_16x16x32_bf16 v[92:95], v[206:209], v[176:179], v[92:95]
	v_mfma_f32_16x16x32_bf16 v[88:91], v[214:217], v[176:179], v[88:91]
	v_mfma_f32_16x16x32_bf16 v[76:79], v[206:209], v[198:201], v[76:79]
	v_mfma_f32_16x16x32_bf16 v[72:75], v[214:217], v[198:201], v[72:75]
	v_mfma_f32_16x16x32_bf16 v[132:135], v[210:213], v[156:159], v[132:135]
	v_mfma_f32_16x16x32_bf16 v[128:131], v[218:221], v[156:159], v[128:131]
	v_mfma_f32_16x16x32_bf16 v[108:111], v[210:213], v[172:175], v[108:111]
	v_mfma_f32_16x16x32_bf16 v[104:107], v[218:221], v[172:175], v[104:107]
	v_mfma_f32_16x16x32_bf16 v[92:95], v[210:213], v[180:183], v[92:95]
	v_mfma_f32_16x16x32_bf16 v[88:91], v[218:221], v[180:183], v[88:91]
	v_mfma_f32_16x16x32_bf16 v[76:79], v[210:213], v[202:205], v[76:79]
	v_mfma_f32_16x16x32_bf16 v[72:75], v[218:221], v[202:205], v[72:75]
	s_mov_b32 m0, s24
	v_lshl_add_u64 v[222:223], s[4:5], 0, v[164:165]
	s_barrier
	ds_read_b128 v[152:155], v197 offset:16384
	ds_read_b128 v[156:159], v197 offset:17408
	ds_read_b128 v[160:163], v197 offset:18432
	ds_read_b128 v[172:175], v197 offset:19456
	ds_read_b128 v[176:179], v197 offset:20480
	ds_read_b128 v[180:183], v197 offset:21504
	ds_read_b128 v[198:201], v197 offset:22528
	ds_read_b128 v[202:205], v197 offset:23552
	global_load_lds_dwordx4 v[222:223], off
	v_lshl_add_u64 v[224:225], v[222:223], 0, s[70:71]
	s_mov_b32 m0, s25
	s_nop 0
	global_load_lds_dwordx4 v[224:225], off
	s_barrier
	s_waitcnt lgkmcnt(0)
	s_waitcnt lgkmcnt(0)
	v_mfma_f32_16x16x32_bf16 v[68:71], v[112:115], v[152:155], v[68:71]
	v_mfma_f32_16x16x32_bf16 v[64:67], v[136:139], v[152:155], v[64:67]
	v_mfma_f32_16x16x32_bf16 v[52:55], v[112:115], v[160:163], v[52:55]
	v_mfma_f32_16x16x32_bf16 v[48:51], v[136:139], v[160:163], v[48:51]
	v_mfma_f32_16x16x32_bf16 v[36:39], v[112:115], v[176:179], v[36:39]
	v_mfma_f32_16x16x32_bf16 v[32:35], v[136:139], v[176:179], v[32:35]
	v_mfma_f32_16x16x32_bf16 v[20:23], v[112:115], v[198:201], v[20:23]
	v_mfma_f32_16x16x32_bf16 v[16:19], v[136:139], v[198:201], v[16:19]
	v_mfma_f32_16x16x32_bf16 v[68:71], v[124:127], v[156:159], v[68:71]
	v_mfma_f32_16x16x32_bf16 v[64:67], v[148:151], v[156:159], v[64:67]
	v_mfma_f32_16x16x32_bf16 v[52:55], v[124:127], v[172:175], v[52:55]
	v_mfma_f32_16x16x32_bf16 v[48:51], v[148:151], v[172:175], v[48:51]
	v_mfma_f32_16x16x32_bf16 v[36:39], v[124:127], v[180:183], v[36:39]
	v_mfma_f32_16x16x32_bf16 v[32:35], v[148:151], v[180:183], v[32:35]
	v_mfma_f32_16x16x32_bf16 v[20:23], v[124:127], v[202:205], v[20:23]
	v_mfma_f32_16x16x32_bf16 v[16:19], v[148:151], v[202:205], v[16:19]
	s_barrier
; #define G_STAGE(bufoff, gbase, o0, h64) do { \
;         __builtin_amdgcn_global_load_lds((const unsigned*)((const char*)(gbase) + (o0)), (LAS unsigned*)(lds + (bufoff) + ldsw), 16, 0, 0); \
;         __builtin_amdgcn_global_load_lds((const unsigned*)((const char*)(gbase) + (h64) + (o0)), (LAS unsigned*)(lds + (bufoff) + ldsw + 8192), 16, 0, 0); } while (0)
; #define G_LDA(dst, b, h) do { _Pragma("unroll") for (int m = 0; m < 4; ++m) _Pragma("unroll") for (int k = 0; k < 2; ++k) dst[m][k] = *(const LAS bf16x8*)(lds + G_SA(b, h) + aoff + m * 2048 + k * 1024); } while (0)
; #define G_LDB(dst, b, h) do { _Pragma("unroll") for (int n = 0; n < 2; ++n) _Pragma("unroll") for (int k = 0; k < 2; ++k) dst[n][k] = *(const LAS bf16x8*)(lds + G_SB(b, h) + boff + n * 2048 + k * 1024); } while (0)
; #define G_WAIT_V(n) asm volatile("s_waitcnt vmcnt(" #n ")" ::: "memory")
; #define G_WAIT_L(n) asm volatile("s_waitcnt lgkmcnt(" #n ")" ::: "memory")
; #define G_BAR __builtin_amdgcn_s_barrier()
; #define G_SCHED __builtin_amdgcn_sched_barrier(0)
;     ...
;             G_STAGE(G_SB(0, 1), b2 + chB, cB0, qB);
;             G_WAIT_V(6); G_BAR; G_MMA(1, 1, At, B1); G_BAR;
;             G_LDB(B0, 1, 0); G_SCHED; G_LDA(At, 1, 0); G_STAGE(G_SA(0, 1), a2 + chA, cA0, qA);
;             G_WAIT_L(8); G_BAR; G_WAIT_L(0); G_MMA(0, 0, At, B0); G_BAR; G_SCHED;
;             G_LDB(B1, 1, 1); G_STAGE(G_SB(1, 0), b3, cB0, qB);
;             G_BAR; G_WAIT_L(0); G_MMA(0, 1, At, B1); G_BAR;
	s_add_i32 s4, s38, s21
	v_lshl_add_u64 v[112:113], v[184:185], 0, s[0:1]
	s_mov_b32 m0, s4
	s_nop 0
	global_load_lds_dwordx4 v[112:113], off
	v_lshl_add_u64 v[112:113], v[184:185], 0, s[52:53]
	s_add_i32 m0, s4, 0x2000
	s_nop 0
	global_load_lds_dwordx4 v[112:113], off
	s_waitcnt vmcnt(6)
	s_barrier
	v_mfma_f32_16x16x32_bf16 v[60:63], v[206:209], v[152:155], v[60:63]
	v_mfma_f32_16x16x32_bf16 v[56:59], v[214:217], v[152:155], v[56:59]
	v_mfma_f32_16x16x32_bf16 v[44:47], v[206:209], v[160:163], v[44:47]
	v_mfma_f32_16x16x32_bf16 v[40:43], v[214:217], v[160:163], v[40:43]
	v_mfma_f32_16x16x32_bf16 v[28:31], v[206:209], v[176:179], v[28:31]
	v_mfma_f32_16x16x32_bf16 v[24:27], v[214:217], v[176:179], v[24:27]
	v_mfma_f32_16x16x32_bf16 v[12:15], v[206:209], v[198:201], v[12:15]
	v_mfma_f32_16x16x32_bf16 v[8:11], v[214:217], v[198:201], v[8:11]
	v_mfma_f32_16x16x32_bf16 v[60:63], v[210:213], v[156:159], v[60:63]
	v_mfma_f32_16x16x32_bf16 v[56:59], v[218:221], v[156:159], v[56:59]
	v_mfma_f32_16x16x32_bf16 v[44:47], v[210:213], v[172:175], v[44:47]
	v_mfma_f32_16x16x32_bf16 v[40:43], v[218:221], v[172:175], v[40:43]
	v_mfma_f32_16x16x32_bf16 v[28:31], v[210:213], v[180:183], v[28:31]
	v_mfma_f32_16x16x32_bf16 v[24:27], v[218:221], v[180:183], v[24:27]
	v_mfma_f32_16x16x32_bf16 v[12:15], v[210:213], v[202:205], v[12:15]
	v_mfma_f32_16x16x32_bf16 v[8:11], v[218:221], v[202:205], v[8:11]
	s_add_i32 s4, 0, 0x18000
	v_add_u32_e32 v0, s4, v196
	s_barrier
	ds_read_b128 v[112:115], v0
	ds_read_b128 v[124:127], v0 offset:1024
	ds_read_b128 v[136:139], v0 offset:2048
	ds_read_b128 v[148:151], v0 offset:3072
	s_mov_b32 m0, s26
	v_lshl_add_u64 v[206:207], v[222:223], 0, s[80:81]
	ds_read_b128 v[152:155], v197 offset:32768
	ds_read_b128 v[156:159], v197 offset:33792
	ds_read_b128 v[160:163], v197 offset:34816
	ds_read_b128 v[172:175], v197 offset:35840
	ds_read_b128 v[176:179], v197 offset:36864
	ds_read_b128 v[180:183], v197 offset:37888
	ds_read_b128 v[198:201], v197 offset:38912
	ds_read_b128 v[202:205], v197 offset:39936
	global_load_lds_dwordx4 v[206:207], off
	v_lshl_add_u64 v[206:207], v[222:223], 0, s[82:83]
	s_mov_b32 m0, s27
	s_nop 0
	global_load_lds_dwordx4 v[206:207], off
	s_waitcnt lgkmcnt(8)
	s_barrier
	s_waitcnt lgkmcnt(0)
	s_waitcnt lgkmcnt(0)
	v_mfma_f32_16x16x32_bf16 v[144:147], v[112:115], v[152:155], v[144:147]
	v_mfma_f32_16x16x32_bf16 v[140:143], v[136:139], v[152:155], v[140:143]
	v_mfma_f32_16x16x32_bf16 v[120:123], v[112:115], v[160:163], v[120:123]
	v_mfma_f32_16x16x32_bf16 v[116:119], v[136:139], v[160:163], v[116:119]
	v_mfma_f32_16x16x32_bf16 v[100:103], v[112:115], v[176:179], v[100:103]
	v_mfma_f32_16x16x32_bf16 v[96:99], v[136:139], v[176:179], v[96:99]
	v_mfma_f32_16x16x32_bf16 v[84:87], v[112:115], v[198:201], v[84:87]
	v_mfma_f32_16x16x32_bf16 v[80:83], v[136:139], v[198:201], v[80:83]
	v_mfma_f32_16x16x32_bf16 v[144:147], v[124:127], v[156:159], v[144:147]
	v_mfma_f32_16x16x32_bf16 v[140:143], v[148:151], v[156:159], v[140:143]
	v_mfma_f32_16x16x32_bf16 v[120:123], v[124:127], v[172:175], v[120:123]
	v_mfma_f32_16x16x32_bf16 v[116:119], v[148:151], v[172:175], v[116:119]
	v_mfma_f32_16x16x32_bf16 v[100:103], v[124:127], v[180:183], v[100:103]
	v_mfma_f32_16x16x32_bf16 v[96:99], v[148:151], v[180:183], v[96:99]
	v_mfma_f32_16x16x32_bf16 v[84:87], v[124:127], v[202:205], v[84:87]
	v_mfma_f32_16x16x32_bf16 v[80:83], v[148:151], v[202:205], v[80:83]
	s_barrier
	s_add_i32 s5, 0, 0x1c000
	s_add_i32 s4, s4, s21
	v_add_u32_e32 v0, s5, v196
	v_lshl_add_u64 v[224:225], v[184:185], 0, s[46:47]
	s_mov_b32 m0, s4
	ds_read_b128 v[206:209], v0
	ds_read_b128 v[210:213], v0 offset:1024
	ds_read_b128 v[214:217], v0 offset:2048
	ds_read_b128 v[218:221], v0 offset:3072
	global_load_lds_dwordx4 v[224:225], off
	v_lshl_add_u64 v[224:225], v[184:185], 0, s[54:55]
	s_add_i32 m0, s4, 0x2000
	s_nop 0
	global_load_lds_dwordx4 v[224:225], off
	s_barrier
; #define G_STAGE(bufoff, gbase, o0, h64) do { \
;         __builtin_amdgcn_global_load_lds((const unsigned*)((const char*)(gbase) + (o0)), (LAS unsigned*)(lds + (bufoff) + ldsw), 16, 0, 0); \
;         __builtin_amdgcn_global_load_lds((const unsigned*)((const char*)(gbase) + (h64) + (o0)), (LAS unsigned*)(lds + (bufoff) + ldsw + 8192), 16, 0, 0); } while (0)
; #define G_LDA(dst, b, h) do { _Pragma("unroll") for (int m = 0; m < 4; ++m) _Pragma("unroll") for (int k = 0; k < 2; ++k) dst[m][k] = *(const LAS bf16x8*)(lds + G_SA(b, h) + aoff + m * 2048 + k * 1024); } while (0)
; #define G_WAIT_V(n) asm volatile("s_waitcnt vmcnt(" #n ")" ::: "memory")
; #define G_WAIT_L(n) asm volatile("s_waitcnt lgkmcnt(" #n ")" ::: "memory")
; #define G_BAR __builtin_amdgcn_s_barrier()
; #define G_SCHED __builtin_amdgcn_sched_barrier(0)
;     ...
;             G_BAR; G_WAIT_L(0); G_MMA(0, 1, At, B1); G_BAR;
;             G_LDA(At, 1, 1); G_STAGE(G_SA(1, 0), a3, cA0, qA);
;             G_BAR; G_WAIT_L(0); G_MMA(1, 0, At, B0); G_BAR; G_SCHED;
;             G_STAGE(G_SB(1, 1), b3 + chB, cB0, qB);
;             G_WAIT_V(6); G_BAR; G_MMA(1, 1, At, B1); G_BAR;
;         }
	s_waitcnt lgkmcnt(0)
	s_waitcnt lgkmcnt(0)
	v_mfma_f32_16x16x32_bf16 v[132:135], v[206:209], v[152:155], v[132:135]
	v_mfma_f32_16x16x32_bf16 v[128:131], v[214:217], v[152:155], v[128:131]
	v_mfma_f32_16x16x32_bf16 v[108:111], v[206:209], v[160:163], v[108:111]
	v_mfma_f32_16x16x32_bf16 v[104:107], v[214:217], v[160:163], v[104:107]
	v_mfma_f32_16x16x32_bf16 v[92:95], v[206:209], v[176:179], v[92:95]
	v_mfma_f32_16x16x32_bf16 v[88:91], v[214:217], v[176:179], v[88:91]
	v_mfma_f32_16x16x32_bf16 v[76:79], v[206:209], v[198:201], v[76:79]
	v_mfma_f32_16x16x32_bf16 v[72:75], v[214:217], v[198:201], v[72:75]
	v_mfma_f32_16x16x32_bf16 v[132:135], v[210:213], v[156:159], v[132:135]
	v_mfma_f32_16x16x32_bf16 v[128:131], v[218:221], v[156:159], v[128:131]
	v_mfma_f32_16x16x32_bf16 v[108:111], v[210:213], v[172:175], v[108:111]
	v_mfma_f32_16x16x32_bf16 v[104:107], v[218:221], v[172:175], v[104:107]
	v_mfma_f32_16x16x32_bf16 v[92:95], v[210:213], v[180:183], v[92:95]
	v_mfma_f32_16x16x32_bf16 v[88:91], v[218:221], v[180:183], v[88:91]
	v_mfma_f32_16x16x32_bf16 v[76:79], v[210:213], v[202:205], v[76:79]
	v_mfma_f32_16x16x32_bf16 v[72:75], v[218:221], v[202:205], v[72:75]
	s_mov_b32 m0, s29
	v_lshl_add_u64 v[224:225], v[222:223], 0, s[62:63]
	s_barrier
	ds_read_b128 v[152:155], v197 offset:49152
	ds_read_b128 v[156:159], v197 offset:50176
	ds_read_b128 v[160:163], v197 offset:51200
	ds_read_b128 v[172:175], v197 offset:52224
	ds_read_b128 v[176:179], v197 offset:53248
	ds_read_b128 v[180:183], v197 offset:54272
	ds_read_b128 v[198:201], v197 offset:55296
	ds_read_b128 v[202:205], v197 offset:56320
	global_load_lds_dwordx4 v[224:225], off
	v_lshl_add_u64 v[222:223], v[222:223], 0, s[84:85]
	s_mov_b32 m0, s30
	s_nop 0
	global_load_lds_dwordx4 v[222:223], off
	s_barrier
	s_waitcnt lgkmcnt(0)
	s_waitcnt lgkmcnt(0)
	v_mfma_f32_16x16x32_bf16 v[68:71], v[112:115], v[152:155], v[68:71]
	v_mfma_f32_16x16x32_bf16 v[64:67], v[136:139], v[152:155], v[64:67]
	v_mfma_f32_16x16x32_bf16 v[52:55], v[112:115], v[160:163], v[52:55]
	v_mfma_f32_16x16x32_bf16 v[48:51], v[136:139], v[160:163], v[48:51]
	v_mfma_f32_16x16x32_bf16 v[36:39], v[112:115], v[176:179], v[36:39]
	v_mfma_f32_16x16x32_bf16 v[32:35], v[136:139], v[176:179], v[32:35]
	v_mfma_f32_16x16x32_bf16 v[20:23], v[112:115], v[198:201], v[20:23]
	v_mfma_f32_16x16x32_bf16 v[16:19], v[136:139], v[198:201], v[16:19]
	v_mfma_f32_16x16x32_bf16 v[68:71], v[124:127], v[156:159], v[68:71]
	v_mfma_f32_16x16x32_bf16 v[64:67], v[148:151], v[156:159], v[64:67]
	v_mfma_f32_16x16x32_bf16 v[52:55], v[124:127], v[172:175], v[52:55]
	v_mfma_f32_16x16x32_bf16 v[48:51], v[148:151], v[172:175], v[48:51]
	v_mfma_f32_16x16x32_bf16 v[36:39], v[124:127], v[180:183], v[36:39]
	v_mfma_f32_16x16x32_bf16 v[32:35], v[148:151], v[180:183], v[32:35]
	v_mfma_f32_16x16x32_bf16 v[20:23], v[124:127], v[202:205], v[20:23]
	v_mfma_f32_16x16x32_bf16 v[16:19], v[148:151], v[202:205], v[16:19]
	s_barrier
	s_add_i32 s4, s5, s21
	v_lshl_add_u64 v[112:113], v[184:185], 0, s[42:43]
	s_mov_b32 m0, s4
	s_nop 0
	global_load_lds_dwordx4 v[112:113], off
	v_lshl_add_u64 v[112:113], v[184:185], 0, s[58:59]
	s_add_i32 m0, s4, 0x2000
	s_nop 0
	global_load_lds_dwordx4 v[112:113], off
	s_waitcnt vmcnt(6)
	s_barrier
	v_mfma_f32_16x16x32_bf16 v[60:63], v[206:209], v[152:155], v[60:63]
	v_mfma_f32_16x16x32_bf16 v[56:59], v[214:217], v[152:155], v[56:59]
	v_mfma_f32_16x16x32_bf16 v[44:47], v[206:209], v[160:163], v[44:47]
	v_mfma_f32_16x16x32_bf16 v[40:43], v[214:217], v[160:163], v[40:43]
	v_mfma_f32_16x16x32_bf16 v[28:31], v[206:209], v[176:179], v[28:31]
	v_mfma_f32_16x16x32_bf16 v[24:27], v[214:217], v[176:179], v[24:27]
	v_mfma_f32_16x16x32_bf16 v[12:15], v[206:209], v[198:201], v[12:15]
	v_mfma_f32_16x16x32_bf16 v[8:11], v[214:217], v[198:201], v[8:11]
	v_mfma_f32_16x16x32_bf16 v[60:63], v[210:213], v[156:159], v[60:63]
	v_mfma_f32_16x16x32_bf16 v[56:59], v[218:221], v[156:159], v[56:59]
	v_mfma_f32_16x16x32_bf16 v[44:47], v[210:213], v[172:175], v[44:47]
	v_mfma_f32_16x16x32_bf16 v[40:43], v[218:221], v[172:175], v[40:43]
	v_mfma_f32_16x16x32_bf16 v[28:31], v[210:213], v[180:183], v[28:31]
	v_mfma_f32_16x16x32_bf16 v[24:27], v[218:221], v[180:183], v[24:27]
	v_mfma_f32_16x16x32_bf16 v[12:15], v[210:213], v[202:205], v[12:15]
	v_mfma_f32_16x16x32_bf16 v[8:11], v[218:221], v[202:205], v[8:11]
	s_add_i32 s19, s19, 2
	s_add_u32 s13, s13, 0x100
	s_addc_u32 s18, s18, 0
	s_add_u32 s2, s2, 0x800000
	s_addc_u32 s3, s3, 0
	s_cmp_gt_u32 s19, 5
	s_cbranch_scc0 .Ldb_GLU_cont
	v_readfirstlane_b32 s101, v186
	s_cmpk_gt_u32 s101, 0xff
	s_cbranch_scc1 .Ldb_GLU_exit
	s_barrier
	s_branch .Ldb_GLU_exit

; #define G_STAGE(bufoff, gbase, o0, h64) do { \
;         __builtin_amdgcn_global_load_lds((const unsigned*)((const char*)(gbase) + (o0)), (LAS unsigned*)(lds + (bufoff) + ldsw), 16, 0, 0); \
;         __builtin_amdgcn_global_load_lds((const unsigned*)((const char*)(gbase) + (h64) + (o0)), (LAS unsigned*)(lds + (bufoff) + ldsw + 8192), 16, 0, 0); } while (0)
; #define G_LDA(dst, b, h) do { _Pragma("unroll") for (int m = 0; m < 4; ++m) _Pragma("unroll") for (int k = 0; k < 2; ++k) dst[m][k] = *(const LAS bf16x8*)(lds + G_SA(b, h) + aoff + m * 2048 + k * 1024); } while (0)
; #define G_LDB(dst, b, h) do { _Pragma("unroll") for (int n = 0; n < 2; ++n) _Pragma("unroll") for (int k = 0; k < 2; ++k) dst[n][k] = *(const LAS bf16x8*)(lds + G_SB(b, h) + boff + n * 2048 + k * 1024); } while (0)
; #define G_WAIT_V(n) asm volatile("s_waitcnt vmcnt(" #n ")" ::: "memory")
; #define G_WAIT_L(n) asm volatile("s_waitcnt lgkmcnt(" #n ")" ::: "memory")
; #define G_BAR __builtin_amdgcn_s_barrier()
; #define G_SCHED __builtin_amdgcn_sched_barrier(0)
;     ...
;         for (int t = 0; t < nt; t += 2) {
;             const bool last = (t == nt - 2);
;             const char* a1 = cA + (size_t)(t + 1) * ckA;
;             const char* a2 = last ? nA : cA + (size_t)(t + 2) * ckA; const char* b2 = last ? nB : cB + (size_t)(t + 2) * kB;
;             const char* a3 = a2 + ckA; const char* b3 = b2 + kB;
;             G_LDB(B0, 0, 0); G_SCHED; G_LDA(At, 0, 0); G_STAGE(G_SA(1, 1), a1 + chA, cA0, qA);
;             G_WAIT_L(8); G_BAR; G_WAIT_L(0); G_MMA(0, 0, At, B0); G_BAR; G_SCHED;
;             G_LDB(B1, 0, 1); G_STAGE(G_SB(0, 0), b2, cB0, qB);
;             G_BAR; G_WAIT_L(0); G_MMA(0, 1, At, B1); G_BAR;
;             G_LDA(At, 0, 1); G_STAGE(G_SA(0, 0), a2, cA0, qA);
;             G_BAR; G_WAIT_L(0); G_MMA(1, 0, At, B0); G_BAR; G_SCHED;
;             G_STAGE(G_SB(0, 1), b2 + chB, cB0, qB);
;             G_WAIT_V(6); G_BAR; G_MMA(1, 1, At, B1); G_BAR;
;             G_LDB(B0, 1, 0); G_SCHED; G_LDA(At, 1, 0); G_STAGE(G_SA(0, 1), a2 + chA, cA0, qA);
;             G_WAIT_L(8); G_BAR; G_WAIT_L(0); G_MMA(0, 0, At, B0); G_BAR; G_SCHED;
.Ldbj_MG0_in:
.LBB0_872:
	s_add_u32 s4, s2, 0xfff50080
	s_addc_u32 s5, s3, -1
	s_add_i32 s40, 0, 0x10000
	v_add_u32_e32 v140, s40, v159
	ds_read_b128 v[144:147], v140
	ds_read_b128 v[148:151], v140 offset:1024
	ds_read_b128 v[136:139], v140 offset:2048
	ds_read_b128 v[140:143], v140 offset:3072
	s_cmp_eq_u32 s39, 4
	s_cselect_b32 s13, s9, s5
	s_cselect_b32 s12, s8, s4
	s_cselect_b32 s15, s11, s38
	s_cselect_b32 s14, s10, s37
	v_lshl_add_u64 v[154:155], s[2:3], 0, v[152:153]
	s_add_i32 m0, s22, 0xc000
	ds_read_b128 v[160:163], v236
	ds_read_b128 v[164:167], v236 offset:1024
	ds_read_b128 v[176:179], v236 offset:2048
	ds_read_b128 v[180:183], v236 offset:3072
	ds_read_b128 v[196:199], v236 offset:4096
	ds_read_b128 v[200:203], v236 offset:5120
	ds_read_b128 v[204:207], v236 offset:6144
	ds_read_b128 v[208:211], v236 offset:7168
	global_load_lds_dwordx4 v[154:155], off
	v_lshl_add_u64 v[154:155], v[154:155], 0, s[86:87]
	s_add_i32 m0, s22, 0xe000
	s_nop 0
	global_load_lds_dwordx4 v[154:155], off
	s_waitcnt lgkmcnt(8)
	s_barrier
	s_waitcnt lgkmcnt(0)
	s_waitcnt lgkmcnt(0)
	v_mfma_f32_16x16x128_f8f6f4 v[128:131], v[144:151], v[160:167], v[128:131]
	v_mfma_f32_16x16x128_f8f6f4 v[132:135], v[136:143], v[160:167], v[132:135]
	v_mfma_f32_16x16x128_f8f6f4 v[112:115], v[144:151], v[176:183], v[112:115]
	v_mfma_f32_16x16x128_f8f6f4 v[116:119], v[136:143], v[176:183], v[116:119]
	v_mfma_f32_16x16x128_f8f6f4 v[96:99], v[144:151], v[196:203], v[96:99]
	v_mfma_f32_16x16x128_f8f6f4 v[100:103], v[136:143], v[196:203], v[100:103]
	v_mfma_f32_16x16x128_f8f6f4 v[80:83], v[144:151], v[204:211], v[80:83]
	v_mfma_f32_16x16x128_f8f6f4 v[84:87], v[136:143], v[204:211], v[84:87]
	s_barrier
	s_add_i32 s4, 0, 0x14000
	v_add_u32_e32 v154, s4, v159
	s_add_i32 s5, s40, s17
	ds_read_b128 v[212:215], v154
	ds_read_b128 v[216:219], v154 offset:1024
	ds_read_b128 v[220:223], v154 offset:2048
	ds_read_b128 v[224:227], v154 offset:3072
	v_lshl_add_u64 v[154:155], s[14:15], 0, v[0:1]
	s_mov_b32 m0, s5
	v_lshl_add_u64 v[156:157], v[154:155], 0, s[50:51]
	global_load_lds_dwordx4 v[154:155], off
	s_add_i32 m0, s5, 0x2000
	s_nop 0
	global_load_lds_dwordx4 v[156:157], off
	s_barrier
	s_waitcnt lgkmcnt(0)
	s_waitcnt lgkmcnt(0)
	v_mfma_f32_16x16x128_f8f6f4 v[124:127], v[212:219], v[160:167], v[124:127]
	v_mfma_f32_16x16x128_f8f6f4 v[120:123], v[220:227], v[160:167], v[120:123]
	v_mfma_f32_16x16x128_f8f6f4 v[108:111], v[212:219], v[176:183], v[108:111]
	v_mfma_f32_16x16x128_f8f6f4 v[104:107], v[220:227], v[176:183], v[104:107]
	v_mfma_f32_16x16x128_f8f6f4 v[92:95], v[212:219], v[196:203], v[92:95]
	v_mfma_f32_16x16x128_f8f6f4 v[88:91], v[220:227], v[196:203], v[88:91]
	v_mfma_f32_16x16x128_f8f6f4 v[76:79], v[212:219], v[204:211], v[76:79]
	v_mfma_f32_16x16x128_f8f6f4 v[72:75], v[220:227], v[204:211], v[72:75]
	s_mov_b32 m0, s22
	v_lshl_add_u64 v[156:157], s[12:13], 0, v[2:3]
	s_barrier
	ds_read_b128 v[160:163], v236 offset:16384
	ds_read_b128 v[164:167], v236 offset:17408
	ds_read_b128 v[176:179], v236 offset:18432
	ds_read_b128 v[180:183], v236 offset:19456
	ds_read_b128 v[196:199], v236 offset:20480
	ds_read_b128 v[200:203], v236 offset:21504
	ds_read_b128 v[204:207], v236 offset:22528
	ds_read_b128 v[208:211], v236 offset:23552
	global_load_lds_dwordx4 v[156:157], off
	v_lshl_add_u64 v[234:235], v[156:157], 0, s[86:87]
	s_mov_b32 m0, s23
	s_nop 0
	global_load_lds_dwordx4 v[234:235], off
	s_barrier
	s_waitcnt lgkmcnt(0)
	s_waitcnt lgkmcnt(0)
	v_mfma_f32_16x16x128_f8f6f4 v[64:67], v[144:151], v[160:167], v[64:67]
	v_mfma_f32_16x16x128_f8f6f4 v[68:71], v[136:143], v[160:167], v[68:71]
	v_mfma_f32_16x16x128_f8f6f4 v[48:51], v[144:151], v[176:183], v[48:51]
	v_mfma_f32_16x16x128_f8f6f4 v[52:55], v[136:143], v[176:183], v[52:55]
	v_mfma_f32_16x16x128_f8f6f4 v[32:35], v[144:151], v[196:203], v[32:35]
	v_mfma_f32_16x16x128_f8f6f4 v[36:39], v[136:143], v[196:203], v[36:39]
	v_mfma_f32_16x16x128_f8f6f4 v[20:23], v[144:151], v[204:211], v[20:23]
	v_mfma_f32_16x16x128_f8f6f4 v[16:19], v[136:143], v[204:211], v[16:19]
	s_barrier
	s_add_i32 s4, s4, s17
	v_lshl_add_u64 v[140:141], v[154:155], 0, s[0:1]
	s_mov_b32 m0, s4
	s_nop 0
	global_load_lds_dwordx4 v[140:141], off
	v_lshl_add_u64 v[140:141], v[154:155], 0, s[52:53]
	s_add_i32 m0, s4, 0x2000
	s_nop 0
	global_load_lds_dwordx4 v[140:141], off
	s_waitcnt vmcnt(6)
	s_barrier
	v_mfma_f32_16x16x128_f8f6f4 v[60:63], v[212:219], v[160:167], v[60:63]
	v_mfma_f32_16x16x128_f8f6f4 v[56:59], v[220:227], v[160:167], v[56:59]
	v_mfma_f32_16x16x128_f8f6f4 v[44:47], v[212:219], v[176:183], v[44:47]
	v_mfma_f32_16x16x128_f8f6f4 v[40:43], v[220:227], v[176:183], v[40:43]
	v_mfma_f32_16x16x128_f8f6f4 v[28:31], v[212:219], v[196:203], v[28:31]
	v_mfma_f32_16x16x128_f8f6f4 v[24:27], v[220:227], v[196:203], v[24:27]
	v_mfma_f32_16x16x128_f8f6f4 v[12:15], v[212:219], v[204:211], v[12:15]
	v_mfma_f32_16x16x128_f8f6f4 v[8:11], v[220:227], v[204:211], v[8:11]
	s_add_i32 s4, 0, 0x18000
	v_add_u32_e32 v140, s4, v159
	s_barrier
; #define G_STAGE(bufoff, gbase, o0, h64) do { \
;         __builtin_amdgcn_global_load_lds((const unsigned*)((const char*)(gbase) + (o0)), (LAS unsigned*)(lds + (bufoff) + ldsw), 16, 0, 0); \
;         __builtin_amdgcn_global_load_lds((const unsigned*)((const char*)(gbase) + (h64) + (o0)), (LAS unsigned*)(lds + (bufoff) + ldsw + 8192), 16, 0, 0); } while (0)
; #define G_LDA(dst, b, h) do { _Pragma("unroll") for (int m = 0; m < 4; ++m) _Pragma("unroll") for (int k = 0; k < 2; ++k) dst[m][k] = *(const LAS bf16x8*)(lds + G_SA(b, h) + aoff + m * 2048 + k * 1024); } while (0)
; #define G_LDB(dst, b, h) do { _Pragma("unroll") for (int n = 0; n < 2; ++n) _Pragma("unroll") for (int k = 0; k < 2; ++k) dst[n][k] = *(const LAS bf16x8*)(lds + G_SB(b, h) + boff + n * 2048 + k * 1024); } while (0)
; #define G_WAIT_V(n) asm volatile("s_waitcnt vmcnt(" #n ")" ::: "memory")
; #define G_WAIT_L(n) asm volatile("s_waitcnt lgkmcnt(" #n ")" ::: "memory")
; #define G_BAR __builtin_amdgcn_s_barrier()
; #define G_SCHED __builtin_amdgcn_sched_barrier(0)
;     ...
;             G_LDB(B0, 1, 0); G_SCHED; G_LDA(At, 1, 0); G_STAGE(G_SA(0, 1), a2 + chA, cA0, qA);
;             G_WAIT_L(8); G_BAR; G_WAIT_L(0); G_MMA(0, 0, At, B0); G_BAR; G_SCHED;
;             G_LDB(B1, 1, 1); G_STAGE(G_SB(1, 0), b3, cB0, qB);
;             G_BAR; G_WAIT_L(0); G_MMA(0, 1, At, B1); G_BAR;
;             G_LDA(At, 1, 1); G_STAGE(G_SA(1, 0), a3, cA0, qA);
;             G_BAR; G_WAIT_L(0); G_MMA(1, 0, At, B0); G_BAR; G_SCHED;
;             G_STAGE(G_SB(1, 1), b3 + chB, cB0, qB);
;             G_WAIT_V(6); G_BAR; G_MMA(1, 1, At, B1); G_BAR;
;         }
	ds_read_b128 v[144:147], v140
	ds_read_b128 v[148:151], v140 offset:1024
	ds_read_b128 v[136:139], v140 offset:2048
	ds_read_b128 v[140:143], v140 offset:3072
	s_mov_b32 m0, s24
	v_lshl_add_u64 v[234:235], v[156:157], 0, s[88:89]
	ds_read_b128 v[160:163], v236 offset:32768
	ds_read_b128 v[164:167], v236 offset:33792
	ds_read_b128 v[176:179], v236 offset:34816
	ds_read_b128 v[180:183], v236 offset:35840
	ds_read_b128 v[196:199], v236 offset:36864
	ds_read_b128 v[200:203], v236 offset:37888
	ds_read_b128 v[204:207], v236 offset:38912
	ds_read_b128 v[208:211], v236 offset:39936
	global_load_lds_dwordx4 v[234:235], off
	v_lshl_add_u64 v[234:235], v[156:157], 0, s[64:65]
	s_mov_b32 m0, s25
	s_nop 0
	global_load_lds_dwordx4 v[234:235], off
	s_waitcnt lgkmcnt(8)
	s_barrier
	s_waitcnt lgkmcnt(0)
	s_waitcnt lgkmcnt(0)
	v_mfma_f32_16x16x128_f8f6f4 v[128:131], v[144:151], v[160:167], v[128:131]
	v_mfma_f32_16x16x128_f8f6f4 v[132:135], v[136:143], v[160:167], v[132:135]
	v_mfma_f32_16x16x128_f8f6f4 v[112:115], v[144:151], v[176:183], v[112:115]
	v_mfma_f32_16x16x128_f8f6f4 v[116:119], v[136:143], v[176:183], v[116:119]
	v_mfma_f32_16x16x128_f8f6f4 v[96:99], v[144:151], v[196:203], v[96:99]
	v_mfma_f32_16x16x128_f8f6f4 v[100:103], v[136:143], v[196:203], v[100:103]
	v_mfma_f32_16x16x128_f8f6f4 v[80:83], v[144:151], v[204:211], v[80:83]
	v_mfma_f32_16x16x128_f8f6f4 v[84:87], v[136:143], v[204:211], v[84:87]
	s_barrier
	s_add_i32 s5, 0, 0x1c000
	s_add_i32 s4, s4, s17
	v_add_u32_e32 v237, s5, v159
	v_lshl_add_u64 v[234:235], v[154:155], 0, s[46:47]
	s_mov_b32 m0, s4
	ds_read_b128 v[212:215], v237
	ds_read_b128 v[216:219], v237 offset:1024
	ds_read_b128 v[220:223], v237 offset:2048
	ds_read_b128 v[224:227], v237 offset:3072
	global_load_lds_dwordx4 v[234:235], off
	v_lshl_add_u64 v[234:235], v[154:155], 0, s[54:55]
	s_add_i32 m0, s4, 0x2000
	s_nop 0
	global_load_lds_dwordx4 v[234:235], off
	s_barrier
	s_waitcnt lgkmcnt(0)
	s_waitcnt lgkmcnt(0)
	v_mfma_f32_16x16x128_f8f6f4 v[124:127], v[212:219], v[160:167], v[124:127]
	v_mfma_f32_16x16x128_f8f6f4 v[120:123], v[220:227], v[160:167], v[120:123]
	v_mfma_f32_16x16x128_f8f6f4 v[108:111], v[212:219], v[176:183], v[108:111]
	v_mfma_f32_16x16x128_f8f6f4 v[104:107], v[220:227], v[176:183], v[104:107]
	v_mfma_f32_16x16x128_f8f6f4 v[92:95], v[212:219], v[196:203], v[92:95]
	v_mfma_f32_16x16x128_f8f6f4 v[88:91], v[220:227], v[196:203], v[88:91]
	v_mfma_f32_16x16x128_f8f6f4 v[76:79], v[212:219], v[204:211], v[76:79]
	v_mfma_f32_16x16x128_f8f6f4 v[72:75], v[220:227], v[204:211], v[72:75]
	s_mov_b32 m0, s26
	v_lshl_add_u64 v[234:235], v[156:157], 0, s[46:47]
	s_barrier
	ds_read_b128 v[160:163], v236 offset:49152
	ds_read_b128 v[164:167], v236 offset:50176
	ds_read_b128 v[176:179], v236 offset:51200
	ds_read_b128 v[180:183], v236 offset:52224
	ds_read_b128 v[196:199], v236 offset:53248
	ds_read_b128 v[200:203], v236 offset:54272
	ds_read_b128 v[204:207], v236 offset:55296
	ds_read_b128 v[208:211], v236 offset:56320
	global_load_lds_dwordx4 v[234:235], off
	v_lshl_add_u64 v[156:157], v[156:157], 0, s[66:67]
	s_mov_b32 m0, s27
	s_nop 0
	global_load_lds_dwordx4 v[156:157], off
	s_barrier
	s_waitcnt lgkmcnt(0)
	s_waitcnt lgkmcnt(0)
	v_mfma_f32_16x16x128_f8f6f4 v[64:67], v[144:151], v[160:167], v[64:67]
	v_mfma_f32_16x16x128_f8f6f4 v[68:71], v[136:143], v[160:167], v[68:71]
	v_mfma_f32_16x16x128_f8f6f4 v[48:51], v[144:151], v[176:183], v[48:51]
	v_mfma_f32_16x16x128_f8f6f4 v[52:55], v[136:143], v[176:183], v[52:55]
	v_mfma_f32_16x16x128_f8f6f4 v[32:35], v[144:151], v[196:203], v[32:35]
	v_mfma_f32_16x16x128_f8f6f4 v[36:39], v[136:143], v[196:203], v[36:39]
	v_mfma_f32_16x16x128_f8f6f4 v[20:23], v[144:151], v[204:211], v[20:23]
	v_mfma_f32_16x16x128_f8f6f4 v[16:19], v[136:143], v[204:211], v[16:19]
	s_barrier
	s_add_i32 s4, s5, s17
	v_lshl_add_u64 v[140:141], v[154:155], 0, s[42:43]
	s_mov_b32 m0, s4
	s_nop 0
	global_load_lds_dwordx4 v[140:141], off
	v_lshl_add_u64 v[140:141], v[154:155], 0, s[58:59]
	s_add_i32 m0, s4, 0x2000
	s_nop 0
	global_load_lds_dwordx4 v[140:141], off
	s_waitcnt vmcnt(6)
	s_barrier
	v_mfma_f32_16x16x128_f8f6f4 v[60:63], v[212:219], v[160:167], v[60:63]
	v_mfma_f32_16x16x128_f8f6f4 v[56:59], v[220:227], v[160:167], v[56:59]
	v_mfma_f32_16x16x128_f8f6f4 v[44:47], v[212:219], v[176:183], v[44:47]
	v_mfma_f32_16x16x128_f8f6f4 v[40:43], v[220:227], v[176:183], v[40:43]
	v_mfma_f32_16x16x128_f8f6f4 v[28:31], v[212:219], v[196:203], v[28:31]
	v_mfma_f32_16x16x128_f8f6f4 v[24:27], v[220:227], v[196:203], v[24:27]
	v_mfma_f32_16x16x128_f8f6f4 v[12:15], v[212:219], v[204:211], v[12:15]
	v_mfma_f32_16x16x128_f8f6f4 v[8:11], v[220:227], v[204:211], v[8:11]
	s_add_i32 s39, s39, 2
	s_add_u32 s2, s2, 0x100
	s_addc_u32 s3, s3, 0
	s_add_u32 s37, s37, 0x100
	s_addc_u32 s38, s38, 0
	s_cmp_gt_u32 s39, 5
	s_cbranch_scc0 .Ldb_MG0_cont
	v_readfirstlane_b32 s101, v186
	s_cmpk_gt_u32 s101, 0xff
	s_cbranch_scc1 .Ldb_MG0_exit
	s_barrier
	s_branch .Ldb_MG0_exit

; #define G_STAGE(bufoff, gbase, o0, h64) do { \
;         __builtin_amdgcn_global_load_lds((const unsigned*)((const char*)(gbase) + (o0)), (LAS unsigned*)(lds + (bufoff) + ldsw), 16, 0, 0); \
;         __builtin_amdgcn_global_load_lds((const unsigned*)((const char*)(gbase) + (h64) + (o0)), (LAS unsigned*)(lds + (bufoff) + ldsw + 8192), 16, 0, 0); } while (0)
; #define G_LDA(dst, b, h) do { _Pragma("unroll") for (int m = 0; m < 4; ++m) _Pragma("unroll") for (int k = 0; k < 2; ++k) dst[m][k] = *(const LAS bf16x8*)(lds + G_SA(b, h) + aoff + m * 2048 + k * 1024); } while (0)
; #define G_LDB(dst, b, h) do { _Pragma("unroll") for (int n = 0; n < 2; ++n) _Pragma("unroll") for (int k = 0; k < 2; ++k) dst[n][k] = *(const LAS bf16x8*)(lds + G_SB(b, h) + boff + n * 2048 + k * 1024); } while (0)
; #define G_WAIT_L(n) asm volatile("s_waitcnt lgkmcnt(" #n ")" ::: "memory")
; #define G_BAR __builtin_amdgcn_s_barrier()
; #define G_SCHED __builtin_amdgcn_sched_barrier(0)
;     ...
;         for (int t = 0; t < nt; t += 2) {
;             const bool last = (t == nt - 2);
;             const char* a1 = cA + (size_t)(t + 1) * ckA;
;             const char* a2 = last ? nA : cA + (size_t)(t + 2) * ckA; const char* b2 = last ? nB : cB + (size_t)(t + 2) * kB;
;             const char* a3 = a2 + ckA; const char* b3 = b2 + kB;
;             G_LDB(B0, 0, 0); G_SCHED; G_LDA(At, 0, 0); G_STAGE(G_SA(1, 1), a1 + chA, cA0, qA);
;             G_WAIT_L(8); G_BAR; G_WAIT_L(0); G_MMA(0, 0, At, B0); G_BAR; G_SCHED;
;             G_LDB(B1, 0, 1); G_STAGE(G_SB(0, 0), b2, cB0, qB);
;             G_BAR; G_WAIT_L(0); G_MMA(0, 1, At, B1); G_BAR;
;             G_LDA(At, 0, 1); G_STAGE(G_SA(0, 0), a2, cA0, qA);
;             G_BAR; G_WAIT_L(0); G_MMA(1, 0, At, B0); G_BAR; G_SCHED;
.Ldbj_MG1_in:
.LBB0_890:
	s_add_u32 s4, s6, 0xfff50080
	s_addc_u32 s5, s7, -1
	s_add_i32 s19, 0, 0x10000
	v_add_u32_e32 v0, s19, v175
	ds_read_b128 v[136:139], v0
	ds_read_b128 v[140:143], v0 offset:1024
	ds_read_b128 v[144:147], v0 offset:2048
	ds_read_b128 v[148:151], v0 offset:3072
	s_cmp_eq_u32 s18, 4
	s_cselect_b32 s45, s15, s9
	s_cselect_b32 s44, s14, s8
	s_cselect_b32 s5, s13, s5
	s_cselect_b32 s4, s12, s4
	v_lshl_add_u64 v[2:3], s[6:7], 0, v[156:157]
	s_add_i32 m0, s22, 0xc000
	ds_read_b128 v[158:161], v176
	ds_read_b128 v[162:165], v176 offset:1024
	ds_read_b128 v[178:181], v176 offset:2048
	ds_read_b128 v[182:185], v176 offset:3072
	ds_read_b128 v[196:199], v176 offset:4096
	ds_read_b128 v[200:203], v176 offset:5120
	ds_read_b128 v[204:207], v176 offset:6144
	ds_read_b128 v[208:211], v176 offset:7168
	global_load_lds_dwordx4 v[2:3], off
	v_lshl_add_u64 v[2:3], v[2:3], 0, s[86:87]
	s_add_i32 m0, s22, 0xe000
	s_nop 0
	global_load_lds_dwordx4 v[2:3], off
	s_waitcnt lgkmcnt(8)
	s_barrier
	s_waitcnt lgkmcnt(0)
	s_waitcnt lgkmcnt(0)
	v_mfma_f32_16x16x32_bf16 v[104:107], v[136:139], v[158:161], v[104:107]
	v_mfma_f32_16x16x32_bf16 v[108:111], v[144:147], v[158:161], v[108:111]
	v_mfma_f32_16x16x32_bf16 v[132:135], v[136:139], v[178:181], v[132:135]
	v_mfma_f32_16x16x32_bf16 v[128:131], v[144:147], v[178:181], v[128:131]
	v_mfma_f32_16x16x32_bf16 v[124:127], v[136:139], v[196:199], v[124:127]
	v_mfma_f32_16x16x32_bf16 v[120:123], v[144:147], v[196:199], v[120:123]
	v_mfma_f32_16x16x32_bf16 v[116:119], v[136:139], v[204:207], v[116:119]
	v_mfma_f32_16x16x32_bf16 v[112:115], v[144:147], v[204:207], v[112:115]
	v_mfma_f32_16x16x32_bf16 v[104:107], v[140:143], v[162:165], v[104:107]
	v_mfma_f32_16x16x32_bf16 v[108:111], v[148:151], v[162:165], v[108:111]
	v_mfma_f32_16x16x32_bf16 v[132:135], v[140:143], v[182:185], v[132:135]
	v_mfma_f32_16x16x32_bf16 v[128:131], v[148:151], v[182:185], v[128:131]
	v_mfma_f32_16x16x32_bf16 v[124:127], v[140:143], v[200:203], v[124:127]
	v_mfma_f32_16x16x32_bf16 v[120:123], v[148:151], v[200:203], v[120:123]
	v_mfma_f32_16x16x32_bf16 v[116:119], v[140:143], v[208:211], v[116:119]
	v_mfma_f32_16x16x32_bf16 v[112:115], v[148:151], v[208:211], v[112:115]
	s_barrier
	s_add_i32 s43, 0, 0x14000
	s_add_i32 s19, s19, s21
	v_add_u32_e32 v0, s43, v175
	v_lshl_add_u64 v[2:3], s[44:45], 0, v[154:155]
	s_mov_b64 s[44:45], 0x10000
	s_mov_b32 m0, s19
	ds_read_b128 v[212:215], v0
	ds_read_b128 v[216:219], v0 offset:1024
	ds_read_b128 v[220:223], v0 offset:2048
	ds_read_b128 v[224:227], v0 offset:3072
	global_load_lds_dwordx4 v[2:3], off
	v_lshl_add_u64 v[166:167], v[2:3], 0, s[44:45]
	s_add_i32 m0, s19, 0x2000
	s_nop 0
	global_load_lds_dwordx4 v[166:167], off
	s_barrier
	s_waitcnt lgkmcnt(0)
	s_waitcnt lgkmcnt(0)
	v_mfma_f32_16x16x32_bf16 v[100:103], v[212:215], v[158:161], v[100:103]
	v_mfma_f32_16x16x32_bf16 v[96:99], v[220:223], v[158:161], v[96:99]
	v_mfma_f32_16x16x32_bf16 v[92:95], v[212:215], v[178:181], v[92:95]
	v_mfma_f32_16x16x32_bf16 v[88:91], v[220:223], v[178:181], v[88:91]
	v_mfma_f32_16x16x32_bf16 v[84:87], v[212:215], v[196:199], v[84:87]
	v_mfma_f32_16x16x32_bf16 v[80:83], v[220:223], v[196:199], v[80:83]
	v_mfma_f32_16x16x32_bf16 v[76:79], v[212:215], v[204:207], v[76:79]
	v_mfma_f32_16x16x32_bf16 v[72:75], v[220:223], v[204:207], v[72:75]
	v_mfma_f32_16x16x32_bf16 v[100:103], v[216:219], v[162:165], v[100:103]
	v_mfma_f32_16x16x32_bf16 v[96:99], v[224:227], v[162:165], v[96:99]
	v_mfma_f32_16x16x32_bf16 v[92:95], v[216:219], v[182:185], v[92:95]
	v_mfma_f32_16x16x32_bf16 v[88:91], v[224:227], v[182:185], v[88:91]
	v_mfma_f32_16x16x32_bf16 v[84:87], v[216:219], v[200:203], v[84:87]
	v_mfma_f32_16x16x32_bf16 v[80:83], v[224:227], v[200:203], v[80:83]
	v_mfma_f32_16x16x32_bf16 v[76:79], v[216:219], v[208:211], v[76:79]
	v_mfma_f32_16x16x32_bf16 v[72:75], v[224:227], v[208:211], v[72:75]
	s_mov_b32 m0, s22
	v_lshl_add_u64 v[166:167], s[4:5], 0, v[152:153]
	s_barrier
	ds_read_b128 v[158:161], v176 offset:16384
	ds_read_b128 v[162:165], v176 offset:17408
	ds_read_b128 v[178:181], v176 offset:18432
	ds_read_b128 v[182:185], v176 offset:19456
	ds_read_b128 v[196:199], v176 offset:20480
	ds_read_b128 v[200:203], v176 offset:21504
	ds_read_b128 v[204:207], v176 offset:22528
	ds_read_b128 v[208:211], v176 offset:23552
	global_load_lds_dwordx4 v[166:167], off
	v_lshl_add_u64 v[172:173], v[166:167], 0, s[86:87]
	s_mov_b32 m0, s23
	s_nop 0
	global_load_lds_dwordx4 v[172:173], off
	s_barrier
	s_waitcnt lgkmcnt(0)
	s_waitcnt lgkmcnt(0)
	v_mfma_f32_16x16x32_bf16 v[68:71], v[136:139], v[158:161], v[68:71]
	v_mfma_f32_16x16x32_bf16 v[64:67], v[144:147], v[158:161], v[64:67]
	v_mfma_f32_16x16x32_bf16 v[60:63], v[136:139], v[178:181], v[60:63]
	v_mfma_f32_16x16x32_bf16 v[56:59], v[144:147], v[178:181], v[56:59]
	v_mfma_f32_16x16x32_bf16 v[52:55], v[136:139], v[196:199], v[52:55]
	v_mfma_f32_16x16x32_bf16 v[48:51], v[144:147], v[196:199], v[48:51]
	v_mfma_f32_16x16x32_bf16 v[44:47], v[136:139], v[204:207], v[44:47]
	v_mfma_f32_16x16x32_bf16 v[40:43], v[144:147], v[204:207], v[40:43]
	v_mfma_f32_16x16x32_bf16 v[68:71], v[140:143], v[162:165], v[68:71]
	v_mfma_f32_16x16x32_bf16 v[64:67], v[148:151], v[162:165], v[64:67]
	v_mfma_f32_16x16x32_bf16 v[60:63], v[140:143], v[182:185], v[60:63]
	v_mfma_f32_16x16x32_bf16 v[56:59], v[148:151], v[182:185], v[56:59]
	v_mfma_f32_16x16x32_bf16 v[52:55], v[140:143], v[200:203], v[52:55]
	v_mfma_f32_16x16x32_bf16 v[48:51], v[148:151], v[200:203], v[48:51]
	v_mfma_f32_16x16x32_bf16 v[44:47], v[140:143], v[208:211], v[44:47]
	v_mfma_f32_16x16x32_bf16 v[40:43], v[148:151], v[208:211], v[40:43]
	s_barrier
; #define G_STAGE(bufoff, gbase, o0, h64) do { \
;         __builtin_amdgcn_global_load_lds((const unsigned*)((const char*)(gbase) + (o0)), (LAS unsigned*)(lds + (bufoff) + ldsw), 16, 0, 0); \
;         __builtin_amdgcn_global_load_lds((const unsigned*)((const char*)(gbase) + (h64) + (o0)), (LAS unsigned*)(lds + (bufoff) + ldsw + 8192), 16, 0, 0); } while (0)
; #define G_LDA(dst, b, h) do { _Pragma("unroll") for (int m = 0; m < 4; ++m) _Pragma("unroll") for (int k = 0; k < 2; ++k) dst[m][k] = *(const LAS bf16x8*)(lds + G_SA(b, h) + aoff + m * 2048 + k * 1024); } while (0)
; #define G_LDB(dst, b, h) do { _Pragma("unroll") for (int n = 0; n < 2; ++n) _Pragma("unroll") for (int k = 0; k < 2; ++k) dst[n][k] = *(const LAS bf16x8*)(lds + G_SB(b, h) + boff + n * 2048 + k * 1024); } while (0)
; #define G_WAIT_V(n) asm volatile("s_waitcnt vmcnt(" #n ")" ::: "memory")
; #define G_WAIT_L(n) asm volatile("s_waitcnt lgkmcnt(" #n ")" ::: "memory")
; #define G_BAR __builtin_amdgcn_s_barrier()
; #define G_SCHED __builtin_amdgcn_sched_barrier(0)
;     ...
;             G_STAGE(G_SB(0, 1), b2 + chB, cB0, qB);
;             G_WAIT_V(6); G_BAR; G_MMA(1, 1, At, B1); G_BAR;
;             G_LDB(B0, 1, 0); G_SCHED; G_LDA(At, 1, 0); G_STAGE(G_SA(0, 1), a2 + chA, cA0, qA);
;             G_WAIT_L(8); G_BAR; G_WAIT_L(0); G_MMA(0, 0, At, B0); G_BAR; G_SCHED;
;             G_LDB(B1, 1, 1); G_STAGE(G_SB(1, 0), b3, cB0, qB);
;             G_BAR; G_WAIT_L(0); G_MMA(0, 1, At, B1); G_BAR;
	s_add_i32 s4, s43, s21
	v_lshl_add_u64 v[136:137], v[2:3], 0, s[0:1]
	s_mov_b32 m0, s4
	s_nop 0
	global_load_lds_dwordx4 v[136:137], off
	v_lshl_add_u64 v[136:137], v[2:3], 0, s[52:53]
	s_add_i32 m0, s4, 0x2000
	s_nop 0
	global_load_lds_dwordx4 v[136:137], off
	s_waitcnt vmcnt(6)
	s_barrier
	v_mfma_f32_16x16x32_bf16 v[36:39], v[212:215], v[158:161], v[36:39]
	v_mfma_f32_16x16x32_bf16 v[32:35], v[220:223], v[158:161], v[32:35]
	v_mfma_f32_16x16x32_bf16 v[28:31], v[212:215], v[178:181], v[28:31]
	v_mfma_f32_16x16x32_bf16 v[24:27], v[220:223], v[178:181], v[24:27]
	v_mfma_f32_16x16x32_bf16 v[20:23], v[212:215], v[196:199], v[20:23]
	v_mfma_f32_16x16x32_bf16 v[16:19], v[220:223], v[196:199], v[16:19]
	v_mfma_f32_16x16x32_bf16 v[12:15], v[212:215], v[204:207], v[12:15]
	v_mfma_f32_16x16x32_bf16 v[8:11], v[220:223], v[204:207], v[8:11]
	v_mfma_f32_16x16x32_bf16 v[36:39], v[216:219], v[162:165], v[36:39]
	v_mfma_f32_16x16x32_bf16 v[32:35], v[224:227], v[162:165], v[32:35]
	v_mfma_f32_16x16x32_bf16 v[28:31], v[216:219], v[182:185], v[28:31]
	v_mfma_f32_16x16x32_bf16 v[24:27], v[224:227], v[182:185], v[24:27]
	v_mfma_f32_16x16x32_bf16 v[20:23], v[216:219], v[200:203], v[20:23]
	v_mfma_f32_16x16x32_bf16 v[16:19], v[224:227], v[200:203], v[16:19]
	v_mfma_f32_16x16x32_bf16 v[12:15], v[216:219], v[208:211], v[12:15]
	v_mfma_f32_16x16x32_bf16 v[8:11], v[224:227], v[208:211], v[8:11]
	s_add_i32 s4, 0, 0x18000
	v_add_u32_e32 v0, s4, v175
	s_barrier
	ds_read_b128 v[136:139], v0
	ds_read_b128 v[140:143], v0 offset:1024
	ds_read_b128 v[144:147], v0 offset:2048
	ds_read_b128 v[148:151], v0 offset:3072
	s_mov_b32 m0, s24
	v_lshl_add_u64 v[172:173], v[166:167], 0, s[88:89]
	ds_read_b128 v[158:161], v176 offset:32768
	ds_read_b128 v[162:165], v176 offset:33792
	ds_read_b128 v[178:181], v176 offset:34816
	ds_read_b128 v[182:185], v176 offset:35840
	ds_read_b128 v[196:199], v176 offset:36864
	ds_read_b128 v[200:203], v176 offset:37888
	ds_read_b128 v[204:207], v176 offset:38912
	ds_read_b128 v[208:211], v176 offset:39936
	global_load_lds_dwordx4 v[172:173], off
	v_lshl_add_u64 v[172:173], v[166:167], 0, s[64:65]
	s_mov_b32 m0, s25
	s_nop 0
	global_load_lds_dwordx4 v[172:173], off
	s_waitcnt lgkmcnt(8)
	s_barrier
	s_waitcnt lgkmcnt(0)
	s_waitcnt lgkmcnt(0)
	v_mfma_f32_16x16x32_bf16 v[104:107], v[136:139], v[158:161], v[104:107]
	v_mfma_f32_16x16x32_bf16 v[108:111], v[144:147], v[158:161], v[108:111]
	v_mfma_f32_16x16x32_bf16 v[132:135], v[136:139], v[178:181], v[132:135]
	v_mfma_f32_16x16x32_bf16 v[128:131], v[144:147], v[178:181], v[128:131]
	v_mfma_f32_16x16x32_bf16 v[124:127], v[136:139], v[196:199], v[124:127]
	v_mfma_f32_16x16x32_bf16 v[120:123], v[144:147], v[196:199], v[120:123]
	v_mfma_f32_16x16x32_bf16 v[116:119], v[136:139], v[204:207], v[116:119]
	v_mfma_f32_16x16x32_bf16 v[112:115], v[144:147], v[204:207], v[112:115]
	v_mfma_f32_16x16x32_bf16 v[104:107], v[140:143], v[162:165], v[104:107]
	v_mfma_f32_16x16x32_bf16 v[108:111], v[148:151], v[162:165], v[108:111]
	v_mfma_f32_16x16x32_bf16 v[132:135], v[140:143], v[182:185], v[132:135]
	v_mfma_f32_16x16x32_bf16 v[128:131], v[148:151], v[182:185], v[128:131]
	v_mfma_f32_16x16x32_bf16 v[124:127], v[140:143], v[200:203], v[124:127]
	v_mfma_f32_16x16x32_bf16 v[120:123], v[148:151], v[200:203], v[120:123]
	v_mfma_f32_16x16x32_bf16 v[116:119], v[140:143], v[208:211], v[116:119]
	v_mfma_f32_16x16x32_bf16 v[112:115], v[148:151], v[208:211], v[112:115]
	s_barrier
	s_add_i32 s5, 0, 0x1c000
	s_add_i32 s4, s4, s21
	v_add_u32_e32 v0, s5, v175
	v_lshl_add_u64 v[172:173], v[2:3], 0, s[46:47]
	s_mov_b32 m0, s4
	ds_read_b128 v[212:215], v0
	ds_read_b128 v[216:219], v0 offset:1024
	ds_read_b128 v[220:223], v0 offset:2048
	ds_read_b128 v[224:227], v0 offset:3072
	global_load_lds_dwordx4 v[172:173], off
	v_lshl_add_u64 v[172:173], v[2:3], 0, s[54:55]
	s_add_i32 m0, s4, 0x2000
	s_nop 0
	global_load_lds_dwordx4 v[172:173], off
	s_barrier
; #define G_STAGE(bufoff, gbase, o0, h64) do { \
;         __builtin_amdgcn_global_load_lds((const unsigned*)((const char*)(gbase) + (o0)), (LAS unsigned*)(lds + (bufoff) + ldsw), 16, 0, 0); \
;         __builtin_amdgcn_global_load_lds((const unsigned*)((const char*)(gbase) + (h64) + (o0)), (LAS unsigned*)(lds + (bufoff) + ldsw + 8192), 16, 0, 0); } while (0)
; #define G_LDA(dst, b, h) do { _Pragma("unroll") for (int m = 0; m < 4; ++m) _Pragma("unroll") for (int k = 0; k < 2; ++k) dst[m][k] = *(const LAS bf16x8*)(lds + G_SA(b, h) + aoff + m * 2048 + k * 1024); } while (0)
; #define G_WAIT_V(n) asm volatile("s_waitcnt vmcnt(" #n ")" ::: "memory")
; #define G_WAIT_L(n) asm volatile("s_waitcnt lgkmcnt(" #n ")" ::: "memory")
; #define G_BAR __builtin_amdgcn_s_barrier()
; #define G_SCHED __builtin_amdgcn_sched_barrier(0)
;     ...
;             G_BAR; G_WAIT_L(0); G_MMA(0, 1, At, B1); G_BAR;
;             G_LDA(At, 1, 1); G_STAGE(G_SA(1, 0), a3, cA0, qA);
;             G_BAR; G_WAIT_L(0); G_MMA(1, 0, At, B0); G_BAR; G_SCHED;
;             G_STAGE(G_SB(1, 1), b3 + chB, cB0, qB);
;             G_WAIT_V(6); G_BAR; G_MMA(1, 1, At, B1); G_BAR;
;         }
	s_waitcnt lgkmcnt(0)
	s_waitcnt lgkmcnt(0)
	v_mfma_f32_16x16x32_bf16 v[100:103], v[212:215], v[158:161], v[100:103]
	v_mfma_f32_16x16x32_bf16 v[96:99], v[220:223], v[158:161], v[96:99]
	v_mfma_f32_16x16x32_bf16 v[92:95], v[212:215], v[178:181], v[92:95]
	v_mfma_f32_16x16x32_bf16 v[88:91], v[220:223], v[178:181], v[88:91]
	v_mfma_f32_16x16x32_bf16 v[84:87], v[212:215], v[196:199], v[84:87]
	v_mfma_f32_16x16x32_bf16 v[80:83], v[220:223], v[196:199], v[80:83]
	v_mfma_f32_16x16x32_bf16 v[76:79], v[212:215], v[204:207], v[76:79]
	v_mfma_f32_16x16x32_bf16 v[72:75], v[220:223], v[204:207], v[72:75]
	v_mfma_f32_16x16x32_bf16 v[100:103], v[216:219], v[162:165], v[100:103]
	v_mfma_f32_16x16x32_bf16 v[96:99], v[224:227], v[162:165], v[96:99]
	v_mfma_f32_16x16x32_bf16 v[92:95], v[216:219], v[182:185], v[92:95]
	v_mfma_f32_16x16x32_bf16 v[88:91], v[224:227], v[182:185], v[88:91]
	v_mfma_f32_16x16x32_bf16 v[84:87], v[216:219], v[200:203], v[84:87]
	v_mfma_f32_16x16x32_bf16 v[80:83], v[224:227], v[200:203], v[80:83]
	v_mfma_f32_16x16x32_bf16 v[76:79], v[216:219], v[208:211], v[76:79]
	v_mfma_f32_16x16x32_bf16 v[72:75], v[224:227], v[208:211], v[72:75]
	s_mov_b32 m0, s26
	v_lshl_add_u64 v[172:173], v[166:167], 0, s[46:47]
	s_barrier
	ds_read_b128 v[158:161], v176 offset:49152
	ds_read_b128 v[162:165], v176 offset:50176
	ds_read_b128 v[178:181], v176 offset:51200
	ds_read_b128 v[182:185], v176 offset:52224
	ds_read_b128 v[196:199], v176 offset:53248
	ds_read_b128 v[200:203], v176 offset:54272
	ds_read_b128 v[204:207], v176 offset:55296
	ds_read_b128 v[208:211], v176 offset:56320
	global_load_lds_dwordx4 v[172:173], off
	v_lshl_add_u64 v[166:167], v[166:167], 0, s[66:67]
	s_mov_b32 m0, s27
	s_nop 0
	global_load_lds_dwordx4 v[166:167], off
	s_barrier
	s_waitcnt lgkmcnt(0)
	s_waitcnt lgkmcnt(0)
	v_mfma_f32_16x16x32_bf16 v[68:71], v[136:139], v[158:161], v[68:71]
	v_mfma_f32_16x16x32_bf16 v[64:67], v[144:147], v[158:161], v[64:67]
	v_mfma_f32_16x16x32_bf16 v[60:63], v[136:139], v[178:181], v[60:63]
	v_mfma_f32_16x16x32_bf16 v[56:59], v[144:147], v[178:181], v[56:59]
	v_mfma_f32_16x16x32_bf16 v[52:55], v[136:139], v[196:199], v[52:55]
	v_mfma_f32_16x16x32_bf16 v[48:51], v[144:147], v[196:199], v[48:51]
	v_mfma_f32_16x16x32_bf16 v[44:47], v[136:139], v[204:207], v[44:47]
	v_mfma_f32_16x16x32_bf16 v[40:43], v[144:147], v[204:207], v[40:43]
	v_mfma_f32_16x16x32_bf16 v[68:71], v[140:143], v[162:165], v[68:71]
	v_mfma_f32_16x16x32_bf16 v[64:67], v[148:151], v[162:165], v[64:67]
	v_mfma_f32_16x16x32_bf16 v[60:63], v[140:143], v[182:185], v[60:63]
	v_mfma_f32_16x16x32_bf16 v[56:59], v[148:151], v[182:185], v[56:59]
	v_mfma_f32_16x16x32_bf16 v[52:55], v[140:143], v[200:203], v[52:55]
	v_mfma_f32_16x16x32_bf16 v[48:51], v[148:151], v[200:203], v[48:51]
	v_mfma_f32_16x16x32_bf16 v[44:47], v[140:143], v[208:211], v[44:47]
	v_mfma_f32_16x16x32_bf16 v[40:43], v[148:151], v[208:211], v[40:43]
	s_barrier
	s_add_i32 s4, s5, s21
	v_lshl_add_u64 v[136:137], v[2:3], 0, s[50:51]
	s_mov_b32 m0, s4
	v_lshl_add_u64 v[2:3], v[2:3], 0, s[58:59]
	global_load_lds_dwordx4 v[136:137], off
	s_add_i32 m0, s4, 0x2000
	s_nop 0
	global_load_lds_dwordx4 v[2:3], off
	s_waitcnt vmcnt(6)
	s_barrier
	v_mfma_f32_16x16x32_bf16 v[36:39], v[212:215], v[158:161], v[36:39]
	v_mfma_f32_16x16x32_bf16 v[32:35], v[220:223], v[158:161], v[32:35]
	v_mfma_f32_16x16x32_bf16 v[28:31], v[212:215], v[178:181], v[28:31]
	v_mfma_f32_16x16x32_bf16 v[24:27], v[220:223], v[178:181], v[24:27]
	v_mfma_f32_16x16x32_bf16 v[20:23], v[212:215], v[196:199], v[20:23]
	v_mfma_f32_16x16x32_bf16 v[16:19], v[220:223], v[196:199], v[16:19]
	v_mfma_f32_16x16x32_bf16 v[12:15], v[212:215], v[204:207], v[12:15]
	v_mfma_f32_16x16x32_bf16 v[8:11], v[220:223], v[204:207], v[8:11]
	v_mfma_f32_16x16x32_bf16 v[36:39], v[216:219], v[162:165], v[36:39]
	v_mfma_f32_16x16x32_bf16 v[32:35], v[224:227], v[162:165], v[32:35]
	v_mfma_f32_16x16x32_bf16 v[28:31], v[216:219], v[182:185], v[28:31]
	v_mfma_f32_16x16x32_bf16 v[24:27], v[224:227], v[182:185], v[24:27]
	v_mfma_f32_16x16x32_bf16 v[20:23], v[216:219], v[200:203], v[20:23]
	v_mfma_f32_16x16x32_bf16 v[16:19], v[224:227], v[200:203], v[16:19]
	v_mfma_f32_16x16x32_bf16 v[12:15], v[216:219], v[208:211], v[12:15]
	v_mfma_f32_16x16x32_bf16 v[8:11], v[224:227], v[208:211], v[8:11]
	s_add_i32 s18, s18, 2
	s_add_u32 s6, s6, 0x100
	s_addc_u32 s7, s7, 0
	s_add_u32 s8, s8, 0x100
	s_addc_u32 s9, s9, 0
	s_cmp_gt_u32 s18, 5
	s_cbranch_scc0 .Ldb_MG1_cont
	v_readfirstlane_b32 s101, v186
	s_cmpk_gt_u32 s101, 0xff
	s_cbranch_scc1 .Ldb_MG1_exit
	s_barrier
	s_branch .Ldb_MG1_exit

; #define G_STAGE(bufoff, gbase, o0, h64) do { \
;         __builtin_amdgcn_global_load_lds((const unsigned*)((const char*)(gbase) + (o0)), (LAS unsigned*)(lds + (bufoff) + ldsw), 16, 0, 0); \
;         __builtin_amdgcn_global_load_lds((const unsigned*)((const char*)(gbase) + (h64) + (o0)), (LAS unsigned*)(lds + (bufoff) + ldsw + 8192), 16, 0, 0); } while (0)
; #define G_LDA(dst, b, h) do { _Pragma("unroll") for (int m = 0; m < 4; ++m) _Pragma("unroll") for (int k = 0; k < 2; ++k) dst[m][k] = *(const LAS bf16x8*)(lds + G_SA(b, h) + aoff + m * 2048 + k * 1024); } while (0)
; #define G_LDB(dst, b, h) do { _Pragma("unroll") for (int n = 0; n < 2; ++n) _Pragma("unroll") for (int k = 0; k < 2; ++k) dst[n][k] = *(const LAS bf16x8*)(lds + G_SB(b, h) + boff + n * 2048 + k * 1024); } while (0)
; #define G_WAIT_L(n) asm volatile("s_waitcnt lgkmcnt(" #n ")" ::: "memory")
; #define G_BAR __builtin_amdgcn_s_barrier()
; #define G_SCHED __builtin_amdgcn_sched_barrier(0)
;     ...
;         for (int t = 0; t < nt; t += 2) {
;             const bool last = (t == nt - 2);
;             const char* a1 = cA + (size_t)(t + 1) * ckA;
;             const char* a2 = last ? nA : cA + (size_t)(t + 2) * ckA; const char* b2 = last ? nB : cB + (size_t)(t + 2) * kB;
;             const char* a3 = a2 + ckA; const char* b3 = b2 + kB;
;             G_LDB(B0, 0, 0); G_SCHED; G_LDA(At, 0, 0); G_STAGE(G_SA(1, 1), a1 + chA, cA0, qA);
;             G_WAIT_L(8); G_BAR; G_WAIT_L(0); G_MMA(0, 0, At, B0); G_BAR; G_SCHED;
;             G_LDB(B1, 0, 1); G_STAGE(G_SB(0, 0), b2, cB0, qB);
;             G_BAR; G_WAIT_L(0); G_MMA(0, 1, At, B1); G_BAR;
;             G_LDA(At, 0, 1); G_STAGE(G_SA(0, 0), a2, cA0, qA);
;             G_BAR; G_WAIT_L(0); G_MMA(1, 0, At, B0); G_BAR; G_SCHED;
.Ldbj_WOUT_in:
.LBB0_1037:
	s_add_u32 s4, s2, 0xfffc0080
	s_addc_u32 s5, s3, -1
	s_add_i32 s33, 0, 0x10000
	v_add_u32_e32 v0, s33, v181
	ds_read_b128 v[136:139], v0
	ds_read_b128 v[140:143], v0 offset:1024
	ds_read_b128 v[144:147], v0 offset:2048
	ds_read_b128 v[148:151], v0 offset:3072
	s_cmp_eq_u32 s15, 12
	s_cselect_b32 s5, s17, s5
	s_cselect_b32 s4, s16, s4
	s_cselect_b32 s21, s19, s7
	s_cselect_b32 s20, s18, s6
	v_lshl_add_u64 v[184:185], s[2:3], 0, v[166:167]
	s_add_i32 m0, s24, 0xc000
	ds_read_b128 v[152:155], v182
	ds_read_b128 v[156:159], v182 offset:1024
	ds_read_b128 v[160:163], v182 offset:2048
	ds_read_b128 v[172:175], v182 offset:3072
	ds_read_b128 v[176:179], v182 offset:4096
	ds_read_b128 v[196:199], v182 offset:5120
	ds_read_b128 v[200:203], v182 offset:6144
	ds_read_b128 v[204:207], v182 offset:7168
	global_load_lds_dwordx4 v[184:185], off
	v_lshl_add_u64 v[184:185], v[184:185], 0, s[0:1]
	s_add_i32 m0, s24, 0xe000
	s_nop 0
	global_load_lds_dwordx4 v[184:185], off
	s_waitcnt lgkmcnt(8)
	s_barrier
	s_waitcnt lgkmcnt(0)
	s_waitcnt lgkmcnt(0)
	v_mfma_f32_16x16x32_bf16 v[132:135], v[136:139], v[152:155], v[132:135]
	v_mfma_f32_16x16x32_bf16 v[128:131], v[144:147], v[152:155], v[128:131]
	v_mfma_f32_16x16x32_bf16 v[116:119], v[136:139], v[160:163], v[116:119]
	v_mfma_f32_16x16x32_bf16 v[112:115], v[144:147], v[160:163], v[112:115]
	v_mfma_f32_16x16x32_bf16 v[100:103], v[136:139], v[176:179], v[100:103]
	v_mfma_f32_16x16x32_bf16 v[96:99], v[144:147], v[176:179], v[96:99]
	v_mfma_f32_16x16x32_bf16 v[84:87], v[136:139], v[200:203], v[84:87]
	v_mfma_f32_16x16x32_bf16 v[80:83], v[144:147], v[200:203], v[80:83]
	v_mfma_f32_16x16x32_bf16 v[132:135], v[140:143], v[156:159], v[132:135]
	v_mfma_f32_16x16x32_bf16 v[128:131], v[148:151], v[156:159], v[128:131]
	v_mfma_f32_16x16x32_bf16 v[116:119], v[140:143], v[172:175], v[116:119]
	v_mfma_f32_16x16x32_bf16 v[112:115], v[148:151], v[172:175], v[112:115]
	v_mfma_f32_16x16x32_bf16 v[100:103], v[140:143], v[196:199], v[100:103]
	v_mfma_f32_16x16x32_bf16 v[96:99], v[148:151], v[196:199], v[96:99]
	v_mfma_f32_16x16x32_bf16 v[84:87], v[140:143], v[204:207], v[84:87]
	v_mfma_f32_16x16x32_bf16 v[80:83], v[148:151], v[204:207], v[80:83]
	s_barrier
	s_add_i32 s41, 0, 0x14000
	v_lshl_add_u64 v[184:185], s[20:21], 0, v[164:165]
	s_add_i32 s20, s33, s23
	v_add_u32_e32 v0, s41, v181
	s_mov_b32 m0, s20
	ds_read_b128 v[208:211], v0
	ds_read_b128 v[212:215], v0 offset:1024
	ds_read_b128 v[216:219], v0 offset:2048
	ds_read_b128 v[220:223], v0 offset:3072
	global_load_lds_dwordx4 v[184:185], off
	v_lshl_add_u64 v[224:225], v[184:185], 0, s[0:1]
	s_add_i32 m0, s20, 0x2000
	s_nop 0
	global_load_lds_dwordx4 v[224:225], off
	s_barrier
	s_waitcnt lgkmcnt(0)
	s_waitcnt lgkmcnt(0)
	v_mfma_f32_16x16x32_bf16 v[124:127], v[208:211], v[152:155], v[124:127]
	v_mfma_f32_16x16x32_bf16 v[120:123], v[216:219], v[152:155], v[120:123]
	v_mfma_f32_16x16x32_bf16 v[108:111], v[208:211], v[160:163], v[108:111]
	v_mfma_f32_16x16x32_bf16 v[104:107], v[216:219], v[160:163], v[104:107]
	v_mfma_f32_16x16x32_bf16 v[92:95], v[208:211], v[176:179], v[92:95]
	v_mfma_f32_16x16x32_bf16 v[88:91], v[216:219], v[176:179], v[88:91]
	v_mfma_f32_16x16x32_bf16 v[76:79], v[208:211], v[200:203], v[76:79]
	v_mfma_f32_16x16x32_bf16 v[72:75], v[216:219], v[200:203], v[72:75]
	v_mfma_f32_16x16x32_bf16 v[124:127], v[212:215], v[156:159], v[124:127]
	v_mfma_f32_16x16x32_bf16 v[120:123], v[220:223], v[156:159], v[120:123]
	v_mfma_f32_16x16x32_bf16 v[108:111], v[212:215], v[172:175], v[108:111]
	v_mfma_f32_16x16x32_bf16 v[104:107], v[220:223], v[172:175], v[104:107]
	v_mfma_f32_16x16x32_bf16 v[92:95], v[212:215], v[196:199], v[92:95]
	v_mfma_f32_16x16x32_bf16 v[88:91], v[220:223], v[196:199], v[88:91]
	v_mfma_f32_16x16x32_bf16 v[76:79], v[212:215], v[204:207], v[76:79]
	v_mfma_f32_16x16x32_bf16 v[72:75], v[220:223], v[204:207], v[72:75]
	s_mov_b32 m0, s24
	v_lshl_add_u64 v[224:225], s[4:5], 0, v[2:3]
	s_barrier
	ds_read_b128 v[152:155], v182 offset:16384
	ds_read_b128 v[156:159], v182 offset:17408
	ds_read_b128 v[160:163], v182 offset:18432
	ds_read_b128 v[172:175], v182 offset:19456
	ds_read_b128 v[176:179], v182 offset:20480
	ds_read_b128 v[196:199], v182 offset:21504
	ds_read_b128 v[200:203], v182 offset:22528
	ds_read_b128 v[204:207], v182 offset:23552
	global_load_lds_dwordx4 v[224:225], off
	v_lshl_add_u64 v[226:227], v[224:225], 0, s[0:1]
	s_mov_b32 m0, s25
	s_nop 0
	global_load_lds_dwordx4 v[226:227], off
	s_barrier
	s_waitcnt lgkmcnt(0)
	s_waitcnt lgkmcnt(0)
	v_mfma_f32_16x16x32_bf16 v[68:71], v[136:139], v[152:155], v[68:71]
	v_mfma_f32_16x16x32_bf16 v[64:67], v[144:147], v[152:155], v[64:67]
	v_mfma_f32_16x16x32_bf16 v[52:55], v[136:139], v[160:163], v[52:55]
	v_mfma_f32_16x16x32_bf16 v[48:51], v[144:147], v[160:163], v[48:51]
	v_mfma_f32_16x16x32_bf16 v[36:39], v[136:139], v[176:179], v[36:39]
	v_mfma_f32_16x16x32_bf16 v[32:35], v[144:147], v[176:179], v[32:35]
	v_mfma_f32_16x16x32_bf16 v[20:23], v[136:139], v[200:203], v[20:23]
	v_mfma_f32_16x16x32_bf16 v[16:19], v[144:147], v[200:203], v[16:19]
	v_mfma_f32_16x16x32_bf16 v[68:71], v[140:143], v[156:159], v[68:71]
	v_mfma_f32_16x16x32_bf16 v[64:67], v[148:151], v[156:159], v[64:67]
	v_mfma_f32_16x16x32_bf16 v[52:55], v[140:143], v[172:175], v[52:55]
	v_mfma_f32_16x16x32_bf16 v[48:51], v[148:151], v[172:175], v[48:51]
	v_mfma_f32_16x16x32_bf16 v[36:39], v[140:143], v[196:199], v[36:39]
	v_mfma_f32_16x16x32_bf16 v[32:35], v[148:151], v[196:199], v[32:35]
	v_mfma_f32_16x16x32_bf16 v[20:23], v[140:143], v[204:207], v[20:23]
	v_mfma_f32_16x16x32_bf16 v[16:19], v[148:151], v[204:207], v[16:19]
	s_barrier
; #define G_STAGE(bufoff, gbase, o0, h64) do { \
;         __builtin_amdgcn_global_load_lds((const unsigned*)((const char*)(gbase) + (o0)), (LAS unsigned*)(lds + (bufoff) + ldsw), 16, 0, 0); \
;         __builtin_amdgcn_global_load_lds((const unsigned*)((const char*)(gbase) + (h64) + (o0)), (LAS unsigned*)(lds + (bufoff) + ldsw + 8192), 16, 0, 0); } while (0)
; #define G_LDA(dst, b, h) do { _Pragma("unroll") for (int m = 0; m < 4; ++m) _Pragma("unroll") for (int k = 0; k < 2; ++k) dst[m][k] = *(const LAS bf16x8*)(lds + G_SA(b, h) + aoff + m * 2048 + k * 1024); } while (0)
; #define G_LDB(dst, b, h) do { _Pragma("unroll") for (int n = 0; n < 2; ++n) _Pragma("unroll") for (int k = 0; k < 2; ++k) dst[n][k] = *(const LAS bf16x8*)(lds + G_SB(b, h) + boff + n * 2048 + k * 1024); } while (0)
; #define G_WAIT_V(n) asm volatile("s_waitcnt vmcnt(" #n ")" ::: "memory")
; #define G_WAIT_L(n) asm volatile("s_waitcnt lgkmcnt(" #n ")" ::: "memory")
; #define G_BAR __builtin_amdgcn_s_barrier()
; #define G_SCHED __builtin_amdgcn_sched_barrier(0)
;     ...
;             G_STAGE(G_SB(0, 1), b2 + chB, cB0, qB);
;             G_WAIT_V(6); G_BAR; G_MMA(1, 1, At, B1); G_BAR;
;             G_LDB(B0, 1, 0); G_SCHED; G_LDA(At, 1, 0); G_STAGE(G_SA(0, 1), a2 + chA, cA0, qA);
;             G_WAIT_L(8); G_BAR; G_WAIT_L(0); G_MMA(0, 0, At, B0); G_BAR; G_SCHED;
;             G_LDB(B1, 1, 1); G_STAGE(G_SB(1, 0), b3, cB0, qB);
;             G_BAR; G_WAIT_L(0); G_MMA(0, 1, At, B1); G_BAR;
	s_add_i32 s4, s41, s23
	v_lshl_add_u64 v[136:137], v[184:185], 0, s[42:43]
	s_mov_b32 m0, s4
	s_nop 0
	global_load_lds_dwordx4 v[136:137], off
	v_lshl_add_u64 v[136:137], v[184:185], 0, s[50:51]
	s_add_i32 m0, s4, 0x2000
	s_nop 0
	global_load_lds_dwordx4 v[136:137], off
	s_waitcnt vmcnt(6)
	s_barrier
	v_mfma_f32_16x16x32_bf16 v[60:63], v[208:211], v[152:155], v[60:63]
	v_mfma_f32_16x16x32_bf16 v[56:59], v[216:219], v[152:155], v[56:59]
	v_mfma_f32_16x16x32_bf16 v[44:47], v[208:211], v[160:163], v[44:47]
	v_mfma_f32_16x16x32_bf16 v[40:43], v[216:219], v[160:163], v[40:43]
	v_mfma_f32_16x16x32_bf16 v[28:31], v[208:211], v[176:179], v[28:31]
	v_mfma_f32_16x16x32_bf16 v[24:27], v[216:219], v[176:179], v[24:27]
	v_mfma_f32_16x16x32_bf16 v[12:15], v[208:211], v[200:203], v[12:15]
	v_mfma_f32_16x16x32_bf16 v[8:11], v[216:219], v[200:203], v[8:11]
	v_mfma_f32_16x16x32_bf16 v[60:63], v[212:215], v[156:159], v[60:63]
	v_mfma_f32_16x16x32_bf16 v[56:59], v[220:223], v[156:159], v[56:59]
	v_mfma_f32_16x16x32_bf16 v[44:47], v[212:215], v[172:175], v[44:47]
	v_mfma_f32_16x16x32_bf16 v[40:43], v[220:223], v[172:175], v[40:43]
	v_mfma_f32_16x16x32_bf16 v[28:31], v[212:215], v[196:199], v[28:31]
	v_mfma_f32_16x16x32_bf16 v[24:27], v[220:223], v[196:199], v[24:27]
	v_mfma_f32_16x16x32_bf16 v[12:15], v[212:215], v[204:207], v[12:15]
	v_mfma_f32_16x16x32_bf16 v[8:11], v[220:223], v[204:207], v[8:11]
	s_add_i32 s4, 0, 0x18000
	v_add_u32_e32 v0, s4, v181
	s_barrier
	ds_read_b128 v[136:139], v0
	ds_read_b128 v[140:143], v0 offset:1024
	ds_read_b128 v[144:147], v0 offset:2048
	ds_read_b128 v[148:151], v0 offset:3072
	s_mov_b32 m0, s26
	v_lshl_add_u64 v[208:209], v[224:225], 0, s[42:43]
	ds_read_b128 v[152:155], v182 offset:32768
	ds_read_b128 v[156:159], v182 offset:33792
	ds_read_b128 v[160:163], v182 offset:34816
	ds_read_b128 v[172:175], v182 offset:35840
	ds_read_b128 v[176:179], v182 offset:36864
	ds_read_b128 v[196:199], v182 offset:37888
	ds_read_b128 v[200:203], v182 offset:38912
	ds_read_b128 v[204:207], v182 offset:39936
	global_load_lds_dwordx4 v[208:209], off
	v_lshl_add_u64 v[208:209], v[224:225], 0, s[50:51]
	s_mov_b32 m0, s27
	s_nop 0
	global_load_lds_dwordx4 v[208:209], off
	s_waitcnt lgkmcnt(8)
	s_barrier
	s_waitcnt lgkmcnt(0)
	s_waitcnt lgkmcnt(0)
	v_mfma_f32_16x16x32_bf16 v[132:135], v[136:139], v[152:155], v[132:135]
	v_mfma_f32_16x16x32_bf16 v[128:131], v[144:147], v[152:155], v[128:131]
	v_mfma_f32_16x16x32_bf16 v[116:119], v[136:139], v[160:163], v[116:119]
	v_mfma_f32_16x16x32_bf16 v[112:115], v[144:147], v[160:163], v[112:115]
	v_mfma_f32_16x16x32_bf16 v[100:103], v[136:139], v[176:179], v[100:103]
	v_mfma_f32_16x16x32_bf16 v[96:99], v[144:147], v[176:179], v[96:99]
	v_mfma_f32_16x16x32_bf16 v[84:87], v[136:139], v[200:203], v[84:87]
	v_mfma_f32_16x16x32_bf16 v[80:83], v[144:147], v[200:203], v[80:83]
	v_mfma_f32_16x16x32_bf16 v[132:135], v[140:143], v[156:159], v[132:135]
	v_mfma_f32_16x16x32_bf16 v[128:131], v[148:151], v[156:159], v[128:131]
	v_mfma_f32_16x16x32_bf16 v[116:119], v[140:143], v[172:175], v[116:119]
	v_mfma_f32_16x16x32_bf16 v[112:115], v[148:151], v[172:175], v[112:115]
	v_mfma_f32_16x16x32_bf16 v[100:103], v[140:143], v[196:199], v[100:103]
	v_mfma_f32_16x16x32_bf16 v[96:99], v[148:151], v[196:199], v[96:99]
	v_mfma_f32_16x16x32_bf16 v[84:87], v[140:143], v[204:207], v[84:87]
	v_mfma_f32_16x16x32_bf16 v[80:83], v[148:151], v[204:207], v[80:83]
	s_barrier
	s_add_i32 s5, 0, 0x1c000
	s_add_i32 s4, s4, s23
	v_add_u32_e32 v0, s5, v181
	v_lshl_add_u64 v[226:227], v[184:185], 0, s[46:47]
	s_mov_b32 m0, s4
	ds_read_b128 v[208:211], v0
	ds_read_b128 v[212:215], v0 offset:1024
	ds_read_b128 v[216:219], v0 offset:2048
	ds_read_b128 v[220:223], v0 offset:3072
	global_load_lds_dwordx4 v[226:227], off
	v_lshl_add_u64 v[226:227], v[184:185], 0, s[52:53]
	s_add_i32 m0, s4, 0x2000
	s_nop 0
	global_load_lds_dwordx4 v[226:227], off
	s_barrier
; #define G_STAGE(bufoff, gbase, o0, h64) do { \
;         __builtin_amdgcn_global_load_lds((const unsigned*)((const char*)(gbase) + (o0)), (LAS unsigned*)(lds + (bufoff) + ldsw), 16, 0, 0); \
;         __builtin_amdgcn_global_load_lds((const unsigned*)((const char*)(gbase) + (h64) + (o0)), (LAS unsigned*)(lds + (bufoff) + ldsw + 8192), 16, 0, 0); } while (0)
; #define G_LDA(dst, b, h) do { _Pragma("unroll") for (int m = 0; m < 4; ++m) _Pragma("unroll") for (int k = 0; k < 2; ++k) dst[m][k] = *(const LAS bf16x8*)(lds + G_SA(b, h) + aoff + m * 2048 + k * 1024); } while (0)
; #define G_WAIT_V(n) asm volatile("s_waitcnt vmcnt(" #n ")" ::: "memory")
; #define G_WAIT_L(n) asm volatile("s_waitcnt lgkmcnt(" #n ")" ::: "memory")
; #define G_BAR __builtin_amdgcn_s_barrier()
; #define G_SCHED __builtin_amdgcn_sched_barrier(0)
;     ...
;             G_BAR; G_WAIT_L(0); G_MMA(0, 1, At, B1); G_BAR;
;             G_LDA(At, 1, 1); G_STAGE(G_SA(1, 0), a3, cA0, qA);
;             G_BAR; G_WAIT_L(0); G_MMA(1, 0, At, B0); G_BAR; G_SCHED;
;             G_STAGE(G_SB(1, 1), b3 + chB, cB0, qB);
;             G_WAIT_V(6); G_BAR; G_MMA(1, 1, At, B1); G_BAR;
;         }
	s_waitcnt lgkmcnt(0)
	s_waitcnt lgkmcnt(0)
	v_mfma_f32_16x16x32_bf16 v[124:127], v[208:211], v[152:155], v[124:127]
	v_mfma_f32_16x16x32_bf16 v[120:123], v[216:219], v[152:155], v[120:123]
	v_mfma_f32_16x16x32_bf16 v[108:111], v[208:211], v[160:163], v[108:111]
	v_mfma_f32_16x16x32_bf16 v[104:107], v[216:219], v[160:163], v[104:107]
	v_mfma_f32_16x16x32_bf16 v[92:95], v[208:211], v[176:179], v[92:95]
	v_mfma_f32_16x16x32_bf16 v[88:91], v[216:219], v[176:179], v[88:91]
	v_mfma_f32_16x16x32_bf16 v[76:79], v[208:211], v[200:203], v[76:79]
	v_mfma_f32_16x16x32_bf16 v[72:75], v[216:219], v[200:203], v[72:75]
	v_mfma_f32_16x16x32_bf16 v[124:127], v[212:215], v[156:159], v[124:127]
	v_mfma_f32_16x16x32_bf16 v[120:123], v[220:223], v[156:159], v[120:123]
	v_mfma_f32_16x16x32_bf16 v[108:111], v[212:215], v[172:175], v[108:111]
	v_mfma_f32_16x16x32_bf16 v[104:107], v[220:223], v[172:175], v[104:107]
	v_mfma_f32_16x16x32_bf16 v[92:95], v[212:215], v[196:199], v[92:95]
	v_mfma_f32_16x16x32_bf16 v[88:91], v[220:223], v[196:199], v[88:91]
	v_mfma_f32_16x16x32_bf16 v[76:79], v[212:215], v[204:207], v[76:79]
	v_mfma_f32_16x16x32_bf16 v[72:75], v[220:223], v[204:207], v[72:75]
	s_mov_b32 m0, s29
	v_lshl_add_u64 v[226:227], v[224:225], 0, s[46:47]
	s_barrier
	ds_read_b128 v[152:155], v182 offset:49152
	ds_read_b128 v[156:159], v182 offset:50176
	ds_read_b128 v[160:163], v182 offset:51200
	ds_read_b128 v[172:175], v182 offset:52224
	ds_read_b128 v[176:179], v182 offset:53248
	ds_read_b128 v[196:199], v182 offset:54272
	ds_read_b128 v[200:203], v182 offset:55296
	ds_read_b128 v[204:207], v182 offset:56320
	global_load_lds_dwordx4 v[226:227], off
	v_lshl_add_u64 v[224:225], v[224:225], 0, s[52:53]
	s_mov_b32 m0, s30
	s_nop 0
	global_load_lds_dwordx4 v[224:225], off
	s_barrier
	s_waitcnt lgkmcnt(0)
	s_waitcnt lgkmcnt(0)
	v_mfma_f32_16x16x32_bf16 v[68:71], v[136:139], v[152:155], v[68:71]
	v_mfma_f32_16x16x32_bf16 v[64:67], v[144:147], v[152:155], v[64:67]
	v_mfma_f32_16x16x32_bf16 v[52:55], v[136:139], v[160:163], v[52:55]
	v_mfma_f32_16x16x32_bf16 v[48:51], v[144:147], v[160:163], v[48:51]
	v_mfma_f32_16x16x32_bf16 v[36:39], v[136:139], v[176:179], v[36:39]
	v_mfma_f32_16x16x32_bf16 v[32:35], v[144:147], v[176:179], v[32:35]
	v_mfma_f32_16x16x32_bf16 v[20:23], v[136:139], v[200:203], v[20:23]
	v_mfma_f32_16x16x32_bf16 v[16:19], v[144:147], v[200:203], v[16:19]
	v_mfma_f32_16x16x32_bf16 v[68:71], v[140:143], v[156:159], v[68:71]
	v_mfma_f32_16x16x32_bf16 v[64:67], v[148:151], v[156:159], v[64:67]
	v_mfma_f32_16x16x32_bf16 v[52:55], v[140:143], v[172:175], v[52:55]
	v_mfma_f32_16x16x32_bf16 v[48:51], v[148:151], v[172:175], v[48:51]
	v_mfma_f32_16x16x32_bf16 v[36:39], v[140:143], v[196:199], v[36:39]
	v_mfma_f32_16x16x32_bf16 v[32:35], v[148:151], v[196:199], v[32:35]
	v_mfma_f32_16x16x32_bf16 v[20:23], v[140:143], v[204:207], v[20:23]
	v_mfma_f32_16x16x32_bf16 v[16:19], v[148:151], v[204:207], v[16:19]
	s_barrier
	s_add_i32 s4, s5, s23
	v_lshl_add_u64 v[136:137], v[184:185], 0, s[54:55]
	s_mov_b32 m0, s4
	s_nop 0
	global_load_lds_dwordx4 v[136:137], off
	v_lshl_add_u64 v[136:137], v[184:185], 0, s[58:59]
	s_add_i32 m0, s4, 0x2000
	s_nop 0
	global_load_lds_dwordx4 v[136:137], off
	s_waitcnt vmcnt(6)
	s_barrier
	v_mfma_f32_16x16x32_bf16 v[60:63], v[208:211], v[152:155], v[60:63]
	v_mfma_f32_16x16x32_bf16 v[56:59], v[216:219], v[152:155], v[56:59]
	v_mfma_f32_16x16x32_bf16 v[44:47], v[208:211], v[160:163], v[44:47]
	v_mfma_f32_16x16x32_bf16 v[40:43], v[216:219], v[160:163], v[40:43]
	v_mfma_f32_16x16x32_bf16 v[28:31], v[208:211], v[176:179], v[28:31]
	v_mfma_f32_16x16x32_bf16 v[24:27], v[216:219], v[176:179], v[24:27]
	v_mfma_f32_16x16x32_bf16 v[12:15], v[208:211], v[200:203], v[12:15]
	v_mfma_f32_16x16x32_bf16 v[8:11], v[216:219], v[200:203], v[8:11]
	v_mfma_f32_16x16x32_bf16 v[60:63], v[212:215], v[156:159], v[60:63]
	v_mfma_f32_16x16x32_bf16 v[56:59], v[220:223], v[156:159], v[56:59]
	v_mfma_f32_16x16x32_bf16 v[44:47], v[212:215], v[172:175], v[44:47]
	v_mfma_f32_16x16x32_bf16 v[40:43], v[220:223], v[172:175], v[40:43]
	v_mfma_f32_16x16x32_bf16 v[28:31], v[212:215], v[196:199], v[28:31]
	v_mfma_f32_16x16x32_bf16 v[24:27], v[220:223], v[196:199], v[24:27]
	v_mfma_f32_16x16x32_bf16 v[12:15], v[212:215], v[204:207], v[12:15]
	v_mfma_f32_16x16x32_bf16 v[8:11], v[220:223], v[204:207], v[8:11]
	s_add_i32 s15, s15, 2
	s_add_u32 s2, s2, 0x100
	s_addc_u32 s3, s3, 0
	s_add_u32 s6, s6, 0x100
	s_addc_u32 s7, s7, 0
	s_cmp_gt_u32 s15, 13
	s_cbranch_scc0 .Ldb_WOUT_cont
	v_readfirstlane_b32 s101, v186
	s_cmpk_gt_u32 s101, 0xff
	s_cbranch_scc1 .Ldb_WOUT_exit
	s_barrier
	s_branch .Ldb_WOUT_exit

; #define G_STAGE(bufoff, gbase, o0, h64) do { \
;         __builtin_amdgcn_global_load_lds((const unsigned*)((const char*)(gbase) + (o0)), (LAS unsigned*)(lds + (bufoff) + ldsw), 16, 0, 0); \
;         __builtin_amdgcn_global_load_lds((const unsigned*)((const char*)(gbase) + (h64) + (o0)), (LAS unsigned*)(lds + (bufoff) + ldsw + 8192), 16, 0, 0); } while (0)
; #define G_LDA(dst, b, h) do { _Pragma("unroll") for (int m = 0; m < 4; ++m) _Pragma("unroll") for (int k = 0; k < 2; ++k) dst[m][k] = *(const LAS bf16x8*)(lds + G_SA(b, h) + aoff + m * 2048 + k * 1024); } while (0)
; #define G_LDB(dst, b, h) do { _Pragma("unroll") for (int n = 0; n < 2; ++n) _Pragma("unroll") for (int k = 0; k < 2; ++k) dst[n][k] = *(const LAS bf16x8*)(lds + G_SB(b, h) + boff + n * 2048 + k * 1024); } while (0)
; #define G_WAIT_L(n) asm volatile("s_waitcnt lgkmcnt(" #n ")" ::: "memory")
; #define G_BAR __builtin_amdgcn_s_barrier()
; #define G_SCHED __builtin_amdgcn_sched_barrier(0)
;     ...
;         for (int t = 0; t < nt; t += 2) {
;             const bool last = (t == nt - 2);
;             const char* a1 = cA + (size_t)(t + 1) * ckA;
;             const char* a2 = last ? nA : cA + (size_t)(t + 2) * ckA; const char* b2 = last ? nB : cB + (size_t)(t + 2) * kB;
;             const char* a3 = a2 + ckA; const char* b3 = b2 + kB;
;             G_LDB(B0, 0, 0); G_SCHED; G_LDA(At, 0, 0); G_STAGE(G_SA(1, 1), a1 + chA, cA0, qA);
;             G_WAIT_L(8); G_BAR; G_WAIT_L(0); G_MMA(0, 0, At, B0); G_BAR; G_SCHED;
;             G_LDB(B1, 0, 1); G_STAGE(G_SB(0, 0), b2, cB0, qB);
;             G_BAR; G_WAIT_L(0); G_MMA(0, 1, At, B1); G_BAR;
;             G_LDA(At, 0, 1); G_STAGE(G_SA(0, 0), a2, cA0, qA);
;             G_BAR; G_WAIT_L(0); G_MMA(1, 0, At, B0); G_BAR; G_SCHED;
.Ldbj_FFI_in:
.LBB0_1120:
	s_add_u32 s4, s2, 0xfffc0080
	s_addc_u32 s5, s3, -1
	s_add_i32 s19, 0, 0x10000
	v_add_u32_e32 v0, s19, v149
	ds_read_b128 v[140:143], v0
	ds_read_b128 v[144:147], v0 offset:1024
	ds_read_b128 v[152:155], v0 offset:2048
	ds_read_b128 v[156:159], v0 offset:3072
	s_cmp_eq_u32 s18, 12
	s_cselect_b32 s5, s13, s5
	s_cselect_b32 s4, s12, s4
	s_cselect_b32 s41, s15, s17
	s_cselect_b32 s40, s14, s16
	v_lshl_add_u64 v[184:185], s[2:3], 0, v[138:139]
	s_add_i32 m0, s26, 0xc000
	ds_read_b128 v[160:163], v150
	ds_read_b128 v[164:167], v150 offset:1024
	ds_read_b128 v[172:175], v150 offset:2048
	ds_read_b128 v[176:179], v150 offset:3072
	ds_read_b128 v[180:183], v150 offset:4096
	ds_read_b128 v[196:199], v150 offset:5120
	ds_read_b128 v[200:203], v150 offset:6144
	ds_read_b128 v[204:207], v150 offset:7168
	global_load_lds_dwordx4 v[184:185], off
	v_lshl_add_u64 v[184:185], v[184:185], 0, s[0:1]
	s_add_i32 m0, s26, 0xe000
	s_nop 0
	global_load_lds_dwordx4 v[184:185], off
	s_waitcnt lgkmcnt(8)
	s_barrier
	s_waitcnt lgkmcnt(0)
	s_waitcnt lgkmcnt(0)
	v_mfma_f32_16x16x32_bf16 v[132:135], v[140:143], v[160:163], v[132:135]
	v_mfma_f32_16x16x32_bf16 v[124:127], v[152:155], v[160:163], v[124:127]
	v_mfma_f32_16x16x32_bf16 v[116:119], v[140:143], v[172:175], v[116:119]
	v_mfma_f32_16x16x32_bf16 v[108:111], v[152:155], v[172:175], v[108:111]
	v_mfma_f32_16x16x32_bf16 v[100:103], v[140:143], v[180:183], v[100:103]
	v_mfma_f32_16x16x32_bf16 v[92:95], v[152:155], v[180:183], v[92:95]
	v_mfma_f32_16x16x32_bf16 v[84:87], v[140:143], v[200:203], v[84:87]
	v_mfma_f32_16x16x32_bf16 v[76:79], v[152:155], v[200:203], v[76:79]
	v_mfma_f32_16x16x32_bf16 v[132:135], v[144:147], v[164:167], v[132:135]
	v_mfma_f32_16x16x32_bf16 v[124:127], v[156:159], v[164:167], v[124:127]
	v_mfma_f32_16x16x32_bf16 v[116:119], v[144:147], v[176:179], v[116:119]
	v_mfma_f32_16x16x32_bf16 v[108:111], v[156:159], v[176:179], v[108:111]
	v_mfma_f32_16x16x32_bf16 v[100:103], v[144:147], v[196:199], v[100:103]
	v_mfma_f32_16x16x32_bf16 v[92:95], v[156:159], v[196:199], v[92:95]
	v_mfma_f32_16x16x32_bf16 v[84:87], v[144:147], v[204:207], v[84:87]
	v_mfma_f32_16x16x32_bf16 v[76:79], v[156:159], v[204:207], v[76:79]
	s_barrier
	s_add_i32 s39, 0, 0x14000
	s_add_i32 s19, s19, s21
	v_add_u32_e32 v0, s39, v149
	v_lshl_add_u64 v[184:185], s[40:41], 0, v[2:3]
	s_mov_b32 m0, s19
	ds_read_b128 v[208:211], v0
	ds_read_b128 v[212:215], v0 offset:1024
	ds_read_b128 v[216:219], v0 offset:2048
	ds_read_b128 v[220:223], v0 offset:3072
	global_load_lds_dwordx4 v[184:185], off
	v_lshl_add_u64 v[224:225], v[184:185], 0, s[0:1]
	s_add_i32 m0, s19, 0x2000
	s_nop 0
	global_load_lds_dwordx4 v[224:225], off
	s_barrier
	s_waitcnt lgkmcnt(0)
	s_waitcnt lgkmcnt(0)
	v_mfma_f32_16x16x32_bf16 v[128:131], v[208:211], v[160:163], v[128:131]
	v_mfma_f32_16x16x32_bf16 v[120:123], v[216:219], v[160:163], v[120:123]
	v_mfma_f32_16x16x32_bf16 v[112:115], v[208:211], v[172:175], v[112:115]
	v_mfma_f32_16x16x32_bf16 v[104:107], v[216:219], v[172:175], v[104:107]
	v_mfma_f32_16x16x32_bf16 v[96:99], v[208:211], v[180:183], v[96:99]
	v_mfma_f32_16x16x32_bf16 v[88:91], v[216:219], v[180:183], v[88:91]
	v_mfma_f32_16x16x32_bf16 v[80:83], v[208:211], v[200:203], v[80:83]
	v_mfma_f32_16x16x32_bf16 v[72:75], v[216:219], v[200:203], v[72:75]
	v_mfma_f32_16x16x32_bf16 v[128:131], v[212:215], v[164:167], v[128:131]
	v_mfma_f32_16x16x32_bf16 v[120:123], v[220:223], v[164:167], v[120:123]
	v_mfma_f32_16x16x32_bf16 v[112:115], v[212:215], v[176:179], v[112:115]
	v_mfma_f32_16x16x32_bf16 v[104:107], v[220:223], v[176:179], v[104:107]
	v_mfma_f32_16x16x32_bf16 v[96:99], v[212:215], v[196:199], v[96:99]
	v_mfma_f32_16x16x32_bf16 v[88:91], v[220:223], v[196:199], v[88:91]
	v_mfma_f32_16x16x32_bf16 v[80:83], v[212:215], v[204:207], v[80:83]
	v_mfma_f32_16x16x32_bf16 v[72:75], v[220:223], v[204:207], v[72:75]
	s_mov_b32 m0, s26
	v_lshl_add_u64 v[224:225], s[4:5], 0, v[136:137]
	s_barrier
	ds_read_b128 v[160:163], v150 offset:16384
	ds_read_b128 v[164:167], v150 offset:17408
	ds_read_b128 v[172:175], v150 offset:18432
	ds_read_b128 v[176:179], v150 offset:19456
	ds_read_b128 v[180:183], v150 offset:20480
	ds_read_b128 v[196:199], v150 offset:21504
	ds_read_b128 v[200:203], v150 offset:22528
	ds_read_b128 v[204:207], v150 offset:23552
	global_load_lds_dwordx4 v[224:225], off
	v_lshl_add_u64 v[226:227], v[224:225], 0, s[0:1]
	s_mov_b32 m0, s27
	s_nop 0
	global_load_lds_dwordx4 v[226:227], off
	s_barrier
	s_waitcnt lgkmcnt(0)
	s_waitcnt lgkmcnt(0)
	v_mfma_f32_16x16x32_bf16 v[68:71], v[140:143], v[160:163], v[68:71]
	v_mfma_f32_16x16x32_bf16 v[60:63], v[152:155], v[160:163], v[60:63]
	v_mfma_f32_16x16x32_bf16 v[52:55], v[140:143], v[172:175], v[52:55]
	v_mfma_f32_16x16x32_bf16 v[44:47], v[152:155], v[172:175], v[44:47]
	v_mfma_f32_16x16x32_bf16 v[36:39], v[140:143], v[180:183], v[36:39]
	v_mfma_f32_16x16x32_bf16 v[28:31], v[152:155], v[180:183], v[28:31]
	v_mfma_f32_16x16x32_bf16 v[20:23], v[140:143], v[200:203], v[20:23]
	v_mfma_f32_16x16x32_bf16 v[12:15], v[152:155], v[200:203], v[12:15]
	v_mfma_f32_16x16x32_bf16 v[68:71], v[144:147], v[164:167], v[68:71]
	v_mfma_f32_16x16x32_bf16 v[60:63], v[156:159], v[164:167], v[60:63]
	v_mfma_f32_16x16x32_bf16 v[52:55], v[144:147], v[176:179], v[52:55]
	v_mfma_f32_16x16x32_bf16 v[44:47], v[156:159], v[176:179], v[44:47]
	v_mfma_f32_16x16x32_bf16 v[36:39], v[144:147], v[196:199], v[36:39]
	v_mfma_f32_16x16x32_bf16 v[28:31], v[156:159], v[196:199], v[28:31]
	v_mfma_f32_16x16x32_bf16 v[20:23], v[144:147], v[204:207], v[20:23]
	v_mfma_f32_16x16x32_bf16 v[12:15], v[156:159], v[204:207], v[12:15]
	s_barrier
; #define G_STAGE(bufoff, gbase, o0, h64) do { \
;         __builtin_amdgcn_global_load_lds((const unsigned*)((const char*)(gbase) + (o0)), (LAS unsigned*)(lds + (bufoff) + ldsw), 16, 0, 0); \
;         __builtin_amdgcn_global_load_lds((const unsigned*)((const char*)(gbase) + (h64) + (o0)), (LAS unsigned*)(lds + (bufoff) + ldsw + 8192), 16, 0, 0); } while (0)
; #define G_LDA(dst, b, h) do { _Pragma("unroll") for (int m = 0; m < 4; ++m) _Pragma("unroll") for (int k = 0; k < 2; ++k) dst[m][k] = *(const LAS bf16x8*)(lds + G_SA(b, h) + aoff + m * 2048 + k * 1024); } while (0)
; #define G_LDB(dst, b, h) do { _Pragma("unroll") for (int n = 0; n < 2; ++n) _Pragma("unroll") for (int k = 0; k < 2; ++k) dst[n][k] = *(const LAS bf16x8*)(lds + G_SB(b, h) + boff + n * 2048 + k * 1024); } while (0)
; #define G_WAIT_V(n) asm volatile("s_waitcnt vmcnt(" #n ")" ::: "memory")
; #define G_WAIT_L(n) asm volatile("s_waitcnt lgkmcnt(" #n ")" ::: "memory")
; #define G_BAR __builtin_amdgcn_s_barrier()
; #define G_SCHED __builtin_amdgcn_sched_barrier(0)
;     ...
;             G_STAGE(G_SB(0, 1), b2 + chB, cB0, qB);
;             G_WAIT_V(6); G_BAR; G_MMA(1, 1, At, B1); G_BAR;
;             G_LDB(B0, 1, 0); G_SCHED; G_LDA(At, 1, 0); G_STAGE(G_SA(0, 1), a2 + chA, cA0, qA);
;             G_WAIT_L(8); G_BAR; G_WAIT_L(0); G_MMA(0, 0, At, B0); G_BAR; G_SCHED;
;             G_LDB(B1, 1, 1); G_STAGE(G_SB(1, 0), b3, cB0, qB);
;             G_BAR; G_WAIT_L(0); G_MMA(0, 1, At, B1); G_BAR;
	s_add_i32 s4, s39, s21
	v_lshl_add_u64 v[140:141], v[184:185], 0, s[42:43]
	s_mov_b32 m0, s4
	s_nop 0
	global_load_lds_dwordx4 v[140:141], off
	v_lshl_add_u64 v[140:141], v[184:185], 0, s[50:51]
	s_add_i32 m0, s4, 0x2000
	s_nop 0
	global_load_lds_dwordx4 v[140:141], off
	s_waitcnt vmcnt(6)
	s_barrier
	v_mfma_f32_16x16x32_bf16 v[64:67], v[208:211], v[160:163], v[64:67]
	v_mfma_f32_16x16x32_bf16 v[56:59], v[216:219], v[160:163], v[56:59]
	v_mfma_f32_16x16x32_bf16 v[48:51], v[208:211], v[172:175], v[48:51]
	v_mfma_f32_16x16x32_bf16 v[40:43], v[216:219], v[172:175], v[40:43]
	v_mfma_f32_16x16x32_bf16 v[32:35], v[208:211], v[180:183], v[32:35]
	v_mfma_f32_16x16x32_bf16 v[24:27], v[216:219], v[180:183], v[24:27]
	v_mfma_f32_16x16x32_bf16 v[16:19], v[208:211], v[200:203], v[16:19]
	v_mfma_f32_16x16x32_bf16 v[8:11], v[216:219], v[200:203], v[8:11]
	v_mfma_f32_16x16x32_bf16 v[64:67], v[212:215], v[164:167], v[64:67]
	v_mfma_f32_16x16x32_bf16 v[56:59], v[220:223], v[164:167], v[56:59]
	v_mfma_f32_16x16x32_bf16 v[48:51], v[212:215], v[176:179], v[48:51]
	v_mfma_f32_16x16x32_bf16 v[40:43], v[220:223], v[176:179], v[40:43]
	v_mfma_f32_16x16x32_bf16 v[32:35], v[212:215], v[196:199], v[32:35]
	v_mfma_f32_16x16x32_bf16 v[24:27], v[220:223], v[196:199], v[24:27]
	v_mfma_f32_16x16x32_bf16 v[16:19], v[212:215], v[204:207], v[16:19]
	v_mfma_f32_16x16x32_bf16 v[8:11], v[220:223], v[204:207], v[8:11]
	s_add_i32 s4, 0, 0x18000
	v_add_u32_e32 v0, s4, v149
	s_barrier
	ds_read_b128 v[140:143], v0
	ds_read_b128 v[144:147], v0 offset:1024
	ds_read_b128 v[152:155], v0 offset:2048
	ds_read_b128 v[156:159], v0 offset:3072
	s_mov_b32 m0, s29
	v_lshl_add_u64 v[208:209], v[224:225], 0, s[42:43]
	ds_read_b128 v[160:163], v150 offset:32768
	ds_read_b128 v[164:167], v150 offset:33792
	ds_read_b128 v[172:175], v150 offset:34816
	ds_read_b128 v[176:179], v150 offset:35840
	ds_read_b128 v[180:183], v150 offset:36864
	ds_read_b128 v[196:199], v150 offset:37888
	ds_read_b128 v[200:203], v150 offset:38912
	ds_read_b128 v[204:207], v150 offset:39936
	global_load_lds_dwordx4 v[208:209], off
	v_lshl_add_u64 v[208:209], v[224:225], 0, s[50:51]
	s_mov_b32 m0, s30
	s_nop 0
	global_load_lds_dwordx4 v[208:209], off
	s_waitcnt lgkmcnt(8)
	s_barrier
	s_waitcnt lgkmcnt(0)
	s_waitcnt lgkmcnt(0)
	v_mfma_f32_16x16x32_bf16 v[132:135], v[140:143], v[160:163], v[132:135]
	v_mfma_f32_16x16x32_bf16 v[124:127], v[152:155], v[160:163], v[124:127]
	v_mfma_f32_16x16x32_bf16 v[116:119], v[140:143], v[172:175], v[116:119]
	v_mfma_f32_16x16x32_bf16 v[108:111], v[152:155], v[172:175], v[108:111]
	v_mfma_f32_16x16x32_bf16 v[100:103], v[140:143], v[180:183], v[100:103]
	v_mfma_f32_16x16x32_bf16 v[92:95], v[152:155], v[180:183], v[92:95]
	v_mfma_f32_16x16x32_bf16 v[84:87], v[140:143], v[200:203], v[84:87]
	v_mfma_f32_16x16x32_bf16 v[76:79], v[152:155], v[200:203], v[76:79]
	v_mfma_f32_16x16x32_bf16 v[132:135], v[144:147], v[164:167], v[132:135]
	v_mfma_f32_16x16x32_bf16 v[124:127], v[156:159], v[164:167], v[124:127]
	v_mfma_f32_16x16x32_bf16 v[116:119], v[144:147], v[176:179], v[116:119]
	v_mfma_f32_16x16x32_bf16 v[108:111], v[156:159], v[176:179], v[108:111]
	v_mfma_f32_16x16x32_bf16 v[100:103], v[144:147], v[196:199], v[100:103]
	v_mfma_f32_16x16x32_bf16 v[92:95], v[156:159], v[196:199], v[92:95]
	v_mfma_f32_16x16x32_bf16 v[84:87], v[144:147], v[204:207], v[84:87]
	v_mfma_f32_16x16x32_bf16 v[76:79], v[156:159], v[204:207], v[76:79]
	s_barrier
	s_add_i32 s5, 0, 0x1c000
	s_add_i32 s4, s4, s21
	v_add_u32_e32 v0, s5, v149
	v_lshl_add_u64 v[226:227], v[184:185], 0, s[46:47]
	s_mov_b32 m0, s4
	ds_read_b128 v[208:211], v0
	ds_read_b128 v[212:215], v0 offset:1024
	ds_read_b128 v[216:219], v0 offset:2048
	ds_read_b128 v[220:223], v0 offset:3072
	global_load_lds_dwordx4 v[226:227], off
	v_lshl_add_u64 v[226:227], v[184:185], 0, s[52:53]
	s_add_i32 m0, s4, 0x2000
	s_nop 0
	global_load_lds_dwordx4 v[226:227], off
	s_barrier
; #define G_STAGE(bufoff, gbase, o0, h64) do { \
;         __builtin_amdgcn_global_load_lds((const unsigned*)((const char*)(gbase) + (o0)), (LAS unsigned*)(lds + (bufoff) + ldsw), 16, 0, 0); \
;         __builtin_amdgcn_global_load_lds((const unsigned*)((const char*)(gbase) + (h64) + (o0)), (LAS unsigned*)(lds + (bufoff) + ldsw + 8192), 16, 0, 0); } while (0)
; #define G_LDA(dst, b, h) do { _Pragma("unroll") for (int m = 0; m < 4; ++m) _Pragma("unroll") for (int k = 0; k < 2; ++k) dst[m][k] = *(const LAS bf16x8*)(lds + G_SA(b, h) + aoff + m * 2048 + k * 1024); } while (0)
; #define G_WAIT_V(n) asm volatile("s_waitcnt vmcnt(" #n ")" ::: "memory")
; #define G_WAIT_L(n) asm volatile("s_waitcnt lgkmcnt(" #n ")" ::: "memory")
; #define G_BAR __builtin_amdgcn_s_barrier()
; #define G_SCHED __builtin_amdgcn_sched_barrier(0)
;     ...
;             G_BAR; G_WAIT_L(0); G_MMA(0, 1, At, B1); G_BAR;
;             G_LDA(At, 1, 1); G_STAGE(G_SA(1, 0), a3, cA0, qA);
;             G_BAR; G_WAIT_L(0); G_MMA(1, 0, At, B0); G_BAR; G_SCHED;
;             G_STAGE(G_SB(1, 1), b3 + chB, cB0, qB);
;             G_WAIT_V(6); G_BAR; G_MMA(1, 1, At, B1); G_BAR;
;         }
	s_waitcnt lgkmcnt(0)
	s_waitcnt lgkmcnt(0)
	v_mfma_f32_16x16x32_bf16 v[128:131], v[208:211], v[160:163], v[128:131]
	v_mfma_f32_16x16x32_bf16 v[120:123], v[216:219], v[160:163], v[120:123]
	v_mfma_f32_16x16x32_bf16 v[112:115], v[208:211], v[172:175], v[112:115]
	v_mfma_f32_16x16x32_bf16 v[104:107], v[216:219], v[172:175], v[104:107]
	v_mfma_f32_16x16x32_bf16 v[96:99], v[208:211], v[180:183], v[96:99]
	v_mfma_f32_16x16x32_bf16 v[88:91], v[216:219], v[180:183], v[88:91]
	v_mfma_f32_16x16x32_bf16 v[80:83], v[208:211], v[200:203], v[80:83]
	v_mfma_f32_16x16x32_bf16 v[72:75], v[216:219], v[200:203], v[72:75]
	v_mfma_f32_16x16x32_bf16 v[128:131], v[212:215], v[164:167], v[128:131]
	v_mfma_f32_16x16x32_bf16 v[120:123], v[220:223], v[164:167], v[120:123]
	v_mfma_f32_16x16x32_bf16 v[112:115], v[212:215], v[176:179], v[112:115]
	v_mfma_f32_16x16x32_bf16 v[104:107], v[220:223], v[176:179], v[104:107]
	v_mfma_f32_16x16x32_bf16 v[96:99], v[212:215], v[196:199], v[96:99]
	v_mfma_f32_16x16x32_bf16 v[88:91], v[220:223], v[196:199], v[88:91]
	v_mfma_f32_16x16x32_bf16 v[80:83], v[212:215], v[204:207], v[80:83]
	v_mfma_f32_16x16x32_bf16 v[72:75], v[220:223], v[204:207], v[72:75]
	s_mov_b32 m0, s31
	v_lshl_add_u64 v[226:227], v[224:225], 0, s[46:47]
	s_barrier
	ds_read_b128 v[160:163], v150 offset:49152
	ds_read_b128 v[164:167], v150 offset:50176
	ds_read_b128 v[172:175], v150 offset:51200
	ds_read_b128 v[176:179], v150 offset:52224
	ds_read_b128 v[180:183], v150 offset:53248
	ds_read_b128 v[196:199], v150 offset:54272
	ds_read_b128 v[200:203], v150 offset:55296
	ds_read_b128 v[204:207], v150 offset:56320
	global_load_lds_dwordx4 v[226:227], off
	v_lshl_add_u64 v[224:225], v[224:225], 0, s[52:53]
	s_mov_b32 m0, s34
	s_nop 0
	global_load_lds_dwordx4 v[224:225], off
	s_barrier
	s_waitcnt lgkmcnt(0)
	s_waitcnt lgkmcnt(0)
	v_mfma_f32_16x16x32_bf16 v[68:71], v[140:143], v[160:163], v[68:71]
	v_mfma_f32_16x16x32_bf16 v[60:63], v[152:155], v[160:163], v[60:63]
	v_mfma_f32_16x16x32_bf16 v[52:55], v[140:143], v[172:175], v[52:55]
	v_mfma_f32_16x16x32_bf16 v[44:47], v[152:155], v[172:175], v[44:47]
	v_mfma_f32_16x16x32_bf16 v[36:39], v[140:143], v[180:183], v[36:39]
	v_mfma_f32_16x16x32_bf16 v[28:31], v[152:155], v[180:183], v[28:31]
	v_mfma_f32_16x16x32_bf16 v[20:23], v[140:143], v[200:203], v[20:23]
	v_mfma_f32_16x16x32_bf16 v[12:15], v[152:155], v[200:203], v[12:15]
	v_mfma_f32_16x16x32_bf16 v[68:71], v[144:147], v[164:167], v[68:71]
	v_mfma_f32_16x16x32_bf16 v[60:63], v[156:159], v[164:167], v[60:63]
	v_mfma_f32_16x16x32_bf16 v[52:55], v[144:147], v[176:179], v[52:55]
	v_mfma_f32_16x16x32_bf16 v[44:47], v[156:159], v[176:179], v[44:47]
	v_mfma_f32_16x16x32_bf16 v[36:39], v[144:147], v[196:199], v[36:39]
	v_mfma_f32_16x16x32_bf16 v[28:31], v[156:159], v[196:199], v[28:31]
	v_mfma_f32_16x16x32_bf16 v[20:23], v[144:147], v[204:207], v[20:23]
	v_mfma_f32_16x16x32_bf16 v[12:15], v[156:159], v[204:207], v[12:15]
	s_barrier
	s_add_i32 s4, s5, s21
	v_lshl_add_u64 v[140:141], v[184:185], 0, s[54:55]
	s_mov_b32 m0, s4
	s_nop 0
	global_load_lds_dwordx4 v[140:141], off
	v_lshl_add_u64 v[140:141], v[184:185], 0, s[58:59]
	s_add_i32 m0, s4, 0x2000
	s_nop 0
	global_load_lds_dwordx4 v[140:141], off
	s_waitcnt vmcnt(6)
	s_barrier
	v_mfma_f32_16x16x32_bf16 v[64:67], v[208:211], v[160:163], v[64:67]
	v_mfma_f32_16x16x32_bf16 v[56:59], v[216:219], v[160:163], v[56:59]
	v_mfma_f32_16x16x32_bf16 v[48:51], v[208:211], v[172:175], v[48:51]
	v_mfma_f32_16x16x32_bf16 v[40:43], v[216:219], v[172:175], v[40:43]
	v_mfma_f32_16x16x32_bf16 v[32:35], v[208:211], v[180:183], v[32:35]
	v_mfma_f32_16x16x32_bf16 v[24:27], v[216:219], v[180:183], v[24:27]
	v_mfma_f32_16x16x32_bf16 v[16:19], v[208:211], v[200:203], v[16:19]
	v_mfma_f32_16x16x32_bf16 v[8:11], v[216:219], v[200:203], v[8:11]
	v_mfma_f32_16x16x32_bf16 v[64:67], v[212:215], v[164:167], v[64:67]
	v_mfma_f32_16x16x32_bf16 v[56:59], v[220:223], v[164:167], v[56:59]
	v_mfma_f32_16x16x32_bf16 v[48:51], v[212:215], v[176:179], v[48:51]
	v_mfma_f32_16x16x32_bf16 v[40:43], v[220:223], v[176:179], v[40:43]
	v_mfma_f32_16x16x32_bf16 v[32:35], v[212:215], v[196:199], v[32:35]
	v_mfma_f32_16x16x32_bf16 v[24:27], v[220:223], v[196:199], v[24:27]
	v_mfma_f32_16x16x32_bf16 v[16:19], v[212:215], v[204:207], v[16:19]
	v_mfma_f32_16x16x32_bf16 v[8:11], v[220:223], v[204:207], v[8:11]
	s_add_i32 s18, s18, 2
	s_add_u32 s2, s2, 0x100
	s_addc_u32 s3, s3, 0
	s_add_u32 s16, s16, 0x100
	s_addc_u32 s17, s17, 0
	s_cmp_gt_u32 s18, 13
	s_cbranch_scc0 .Ldb_FFI_cont
	v_readfirstlane_b32 s101, v186
	s_cmpk_gt_u32 s101, 0xff
	s_cbranch_scc1 .Ldb_FFI_exit
	s_barrier
	s_branch .Ldb_FFI_exit

; #define G_STAGE(bufoff, gbase, o0, h64) do { \
;         __builtin_amdgcn_global_load_lds((const unsigned*)((const char*)(gbase) + (o0)), (LAS unsigned*)(lds + (bufoff) + ldsw), 16, 0, 0); \
;         __builtin_amdgcn_global_load_lds((const unsigned*)((const char*)(gbase) + (h64) + (o0)), (LAS unsigned*)(lds + (bufoff) + ldsw + 8192), 16, 0, 0); } while (0)
; #define G_LDA(dst, b, h) do { _Pragma("unroll") for (int m = 0; m < 4; ++m) _Pragma("unroll") for (int k = 0; k < 2; ++k) dst[m][k] = *(const LAS bf16x8*)(lds + G_SA(b, h) + aoff + m * 2048 + k * 1024); } while (0)
; #define G_LDB(dst, b, h) do { _Pragma("unroll") for (int n = 0; n < 2; ++n) _Pragma("unroll") for (int k = 0; k < 2; ++k) dst[n][k] = *(const LAS bf16x8*)(lds + G_SB(b, h) + boff + n * 2048 + k * 1024); } while (0)
; #define G_WAIT_L(n) asm volatile("s_waitcnt lgkmcnt(" #n ")" ::: "memory")
; #define G_BAR __builtin_amdgcn_s_barrier()
; #define G_SCHED __builtin_amdgcn_sched_barrier(0)
;     ...
;         for (int t = 0; t < nt; t += 2) {
;             const bool last = (t == nt - 2);
;             const char* a1 = cA + (size_t)(t + 1) * ckA;
;             const char* a2 = last ? nA : cA + (size_t)(t + 2) * ckA; const char* b2 = last ? nB : cB + (size_t)(t + 2) * kB;
;             const char* a3 = a2 + ckA; const char* b3 = b2 + kB;
;             G_LDB(B0, 0, 0); G_SCHED; G_LDA(At, 0, 0); G_STAGE(G_SA(1, 1), a1 + chA, cA0, qA);
;             G_WAIT_L(8); G_BAR; G_WAIT_L(0); G_MMA(0, 0, At, B0); G_BAR; G_SCHED;
;             G_LDB(B1, 0, 1); G_STAGE(G_SB(0, 0), b2, cB0, qB);
;             G_BAR; G_WAIT_L(0); G_MMA(0, 1, At, B1); G_BAR;
;             G_LDA(At, 0, 1); G_STAGE(G_SA(0, 0), a2, cA0, qA);
;             G_BAR; G_WAIT_L(0); G_MMA(1, 0, At, B0); G_BAR; G_SCHED;
.Ldbj_FFO_in:
.LBB0_1185:
	s_add_u32 s4, s2, 0xfff50080
	s_addc_u32 s5, s3, -1
	s_add_i32 s33, 0, 0x10000
	v_add_u32_e32 v0, s33, v185
	ds_read_b128 v[136:139], v0
	ds_read_b128 v[140:143], v0 offset:1024
	ds_read_b128 v[144:147], v0 offset:2048
	ds_read_b128 v[148:151], v0 offset:3072
	s_cmp_eq_u32 s21, 40
	s_cselect_b32 s5, s17, s5
	s_cselect_b32 s4, s16, s4
	s_cselect_b32 s23, s19, s7
	s_cselect_b32 s22, s18, s6
	v_lshl_add_u64 v[204:205], s[2:3], 0, v[174:175]
	s_add_i32 m0, s26, 0xc000
	ds_read_b128 v[152:155], v195
	ds_read_b128 v[156:159], v195 offset:1024
	ds_read_b128 v[160:163], v195 offset:2048
	ds_read_b128 v[164:167], v195 offset:3072
	ds_read_b128 v[176:179], v195 offset:4096
	ds_read_b128 v[180:183], v195 offset:5120
	ds_read_b128 v[196:199], v195 offset:6144
	ds_read_b128 v[200:203], v195 offset:7168
	global_load_lds_dwordx4 v[204:205], off
	v_lshl_add_u64 v[204:205], v[204:205], 0, s[86:87]
	s_add_i32 m0, s26, 0xe000
	s_nop 0
	global_load_lds_dwordx4 v[204:205], off
	s_waitcnt lgkmcnt(8)
	s_barrier
	s_waitcnt lgkmcnt(0)
	s_waitcnt lgkmcnt(0)
	v_mfma_f32_16x16x32_bf16 v[132:135], v[136:139], v[152:155], v[132:135]
	v_mfma_f32_16x16x32_bf16 v[128:131], v[144:147], v[152:155], v[128:131]
	v_mfma_f32_16x16x32_bf16 v[116:119], v[136:139], v[160:163], v[116:119]
	v_mfma_f32_16x16x32_bf16 v[112:115], v[144:147], v[160:163], v[112:115]
	v_mfma_f32_16x16x32_bf16 v[100:103], v[136:139], v[176:179], v[100:103]
	v_mfma_f32_16x16x32_bf16 v[96:99], v[144:147], v[176:179], v[96:99]
	v_mfma_f32_16x16x32_bf16 v[84:87], v[136:139], v[196:199], v[84:87]
	v_mfma_f32_16x16x32_bf16 v[80:83], v[144:147], v[196:199], v[80:83]
	v_mfma_f32_16x16x32_bf16 v[132:135], v[140:143], v[156:159], v[132:135]
	v_mfma_f32_16x16x32_bf16 v[128:131], v[148:151], v[156:159], v[128:131]
	v_mfma_f32_16x16x32_bf16 v[116:119], v[140:143], v[164:167], v[116:119]
	v_mfma_f32_16x16x32_bf16 v[112:115], v[148:151], v[164:167], v[112:115]
	v_mfma_f32_16x16x32_bf16 v[100:103], v[140:143], v[180:183], v[100:103]
	v_mfma_f32_16x16x32_bf16 v[96:99], v[148:151], v[180:183], v[96:99]
	v_mfma_f32_16x16x32_bf16 v[84:87], v[140:143], v[200:203], v[84:87]
	v_mfma_f32_16x16x32_bf16 v[80:83], v[148:151], v[200:203], v[80:83]
	s_barrier
	s_add_i32 s44, 0, 0x14000
	v_lshl_add_u64 v[220:221], s[22:23], 0, v[172:173]
	s_add_i32 s22, s33, s25
	v_add_u32_e32 v0, s44, v185
	s_mov_b32 m0, s22
	ds_read_b128 v[204:207], v0
	ds_read_b128 v[208:211], v0 offset:1024
	ds_read_b128 v[212:215], v0 offset:2048
	ds_read_b128 v[216:219], v0 offset:3072
	global_load_lds_dwordx4 v[220:221], off
	v_lshl_add_u64 v[222:223], v[220:221], 0, s[86:87]
	s_add_i32 m0, s22, 0x2000
	s_nop 0
	global_load_lds_dwordx4 v[222:223], off
	s_barrier
	s_waitcnt lgkmcnt(0)
	s_waitcnt lgkmcnt(0)
	v_mfma_f32_16x16x32_bf16 v[124:127], v[204:207], v[152:155], v[124:127]
	v_mfma_f32_16x16x32_bf16 v[120:123], v[212:215], v[152:155], v[120:123]
	v_mfma_f32_16x16x32_bf16 v[108:111], v[204:207], v[160:163], v[108:111]
	v_mfma_f32_16x16x32_bf16 v[104:107], v[212:215], v[160:163], v[104:107]
	v_mfma_f32_16x16x32_bf16 v[92:95], v[204:207], v[176:179], v[92:95]
	v_mfma_f32_16x16x32_bf16 v[88:91], v[212:215], v[176:179], v[88:91]
	v_mfma_f32_16x16x32_bf16 v[76:79], v[204:207], v[196:199], v[76:79]
	v_mfma_f32_16x16x32_bf16 v[72:75], v[212:215], v[196:199], v[72:75]
	v_mfma_f32_16x16x32_bf16 v[124:127], v[208:211], v[156:159], v[124:127]
	v_mfma_f32_16x16x32_bf16 v[120:123], v[216:219], v[156:159], v[120:123]
	v_mfma_f32_16x16x32_bf16 v[108:111], v[208:211], v[164:167], v[108:111]
	v_mfma_f32_16x16x32_bf16 v[104:107], v[216:219], v[164:167], v[104:107]
	v_mfma_f32_16x16x32_bf16 v[92:95], v[208:211], v[180:183], v[92:95]
	v_mfma_f32_16x16x32_bf16 v[88:91], v[216:219], v[180:183], v[88:91]
	v_mfma_f32_16x16x32_bf16 v[76:79], v[208:211], v[200:203], v[76:79]
	v_mfma_f32_16x16x32_bf16 v[72:75], v[216:219], v[200:203], v[72:75]
	s_mov_b32 m0, s26
	v_lshl_add_u64 v[222:223], s[4:5], 0, v[2:3]
	s_barrier
	ds_read_b128 v[152:155], v195 offset:16384
	ds_read_b128 v[156:159], v195 offset:17408
	ds_read_b128 v[160:163], v195 offset:18432
	ds_read_b128 v[164:167], v195 offset:19456
	ds_read_b128 v[176:179], v195 offset:20480
	ds_read_b128 v[180:183], v195 offset:21504
	ds_read_b128 v[196:199], v195 offset:22528
	ds_read_b128 v[200:203], v195 offset:23552
	global_load_lds_dwordx4 v[222:223], off
	v_lshl_add_u64 v[224:225], v[222:223], 0, s[86:87]
	s_mov_b32 m0, s27
	s_nop 0
	global_load_lds_dwordx4 v[224:225], off
	s_barrier
	s_waitcnt lgkmcnt(0)
	s_waitcnt lgkmcnt(0)
	v_mfma_f32_16x16x32_bf16 v[68:71], v[136:139], v[152:155], v[68:71]
	v_mfma_f32_16x16x32_bf16 v[64:67], v[144:147], v[152:155], v[64:67]
	v_mfma_f32_16x16x32_bf16 v[52:55], v[136:139], v[160:163], v[52:55]
	v_mfma_f32_16x16x32_bf16 v[48:51], v[144:147], v[160:163], v[48:51]
	v_mfma_f32_16x16x32_bf16 v[36:39], v[136:139], v[176:179], v[36:39]
	v_mfma_f32_16x16x32_bf16 v[32:35], v[144:147], v[176:179], v[32:35]
	v_mfma_f32_16x16x32_bf16 v[20:23], v[136:139], v[196:199], v[20:23]
	v_mfma_f32_16x16x32_bf16 v[16:19], v[144:147], v[196:199], v[16:19]
	v_mfma_f32_16x16x32_bf16 v[68:71], v[140:143], v[156:159], v[68:71]
	v_mfma_f32_16x16x32_bf16 v[64:67], v[148:151], v[156:159], v[64:67]
	v_mfma_f32_16x16x32_bf16 v[52:55], v[140:143], v[164:167], v[52:55]
	v_mfma_f32_16x16x32_bf16 v[48:51], v[148:151], v[164:167], v[48:51]
	v_mfma_f32_16x16x32_bf16 v[36:39], v[140:143], v[180:183], v[36:39]
	v_mfma_f32_16x16x32_bf16 v[32:35], v[148:151], v[180:183], v[32:35]
	v_mfma_f32_16x16x32_bf16 v[20:23], v[140:143], v[200:203], v[20:23]
	v_mfma_f32_16x16x32_bf16 v[16:19], v[148:151], v[200:203], v[16:19]
	s_barrier
; #define G_STAGE(bufoff, gbase, o0, h64) do { \
;         __builtin_amdgcn_global_load_lds((const unsigned*)((const char*)(gbase) + (o0)), (LAS unsigned*)(lds + (bufoff) + ldsw), 16, 0, 0); \
;         __builtin_amdgcn_global_load_lds((const unsigned*)((const char*)(gbase) + (h64) + (o0)), (LAS unsigned*)(lds + (bufoff) + ldsw + 8192), 16, 0, 0); } while (0)
; #define G_LDA(dst, b, h) do { _Pragma("unroll") for (int m = 0; m < 4; ++m) _Pragma("unroll") for (int k = 0; k < 2; ++k) dst[m][k] = *(const LAS bf16x8*)(lds + G_SA(b, h) + aoff + m * 2048 + k * 1024); } while (0)
; #define G_LDB(dst, b, h) do { _Pragma("unroll") for (int n = 0; n < 2; ++n) _Pragma("unroll") for (int k = 0; k < 2; ++k) dst[n][k] = *(const LAS bf16x8*)(lds + G_SB(b, h) + boff + n * 2048 + k * 1024); } while (0)
; #define G_WAIT_V(n) asm volatile("s_waitcnt vmcnt(" #n ")" ::: "memory")
; #define G_WAIT_L(n) asm volatile("s_waitcnt lgkmcnt(" #n ")" ::: "memory")
; #define G_BAR __builtin_amdgcn_s_barrier()
; #define G_SCHED __builtin_amdgcn_sched_barrier(0)
;     ...
;             G_STAGE(G_SB(0, 1), b2 + chB, cB0, qB);
;             G_WAIT_V(6); G_BAR; G_MMA(1, 1, At, B1); G_BAR;
;             G_LDB(B0, 1, 0); G_SCHED; G_LDA(At, 1, 0); G_STAGE(G_SA(0, 1), a2 + chA, cA0, qA);
;             G_WAIT_L(8); G_BAR; G_WAIT_L(0); G_MMA(0, 0, At, B0); G_BAR; G_SCHED;
;             G_LDB(B1, 1, 1); G_STAGE(G_SB(1, 0), b3, cB0, qB);
;             G_BAR; G_WAIT_L(0); G_MMA(0, 1, At, B1); G_BAR;
	s_add_i32 s4, s44, s25
	v_lshl_add_u64 v[136:137], v[220:221], 0, s[88:89]
	s_mov_b32 m0, s4
	s_nop 0
	global_load_lds_dwordx4 v[136:137], off
	v_lshl_add_u64 v[136:137], v[220:221], 0, s[64:65]
	s_add_i32 m0, s4, 0x2000
	s_nop 0
	global_load_lds_dwordx4 v[136:137], off
	s_waitcnt vmcnt(6)
	s_barrier
	v_mfma_f32_16x16x32_bf16 v[60:63], v[204:207], v[152:155], v[60:63]
	v_mfma_f32_16x16x32_bf16 v[56:59], v[212:215], v[152:155], v[56:59]
	v_mfma_f32_16x16x32_bf16 v[44:47], v[204:207], v[160:163], v[44:47]
	v_mfma_f32_16x16x32_bf16 v[40:43], v[212:215], v[160:163], v[40:43]
	v_mfma_f32_16x16x32_bf16 v[28:31], v[204:207], v[176:179], v[28:31]
	v_mfma_f32_16x16x32_bf16 v[24:27], v[212:215], v[176:179], v[24:27]
	v_mfma_f32_16x16x32_bf16 v[12:15], v[204:207], v[196:199], v[12:15]
	v_mfma_f32_16x16x32_bf16 v[8:11], v[212:215], v[196:199], v[8:11]
	v_mfma_f32_16x16x32_bf16 v[60:63], v[208:211], v[156:159], v[60:63]
	v_mfma_f32_16x16x32_bf16 v[56:59], v[216:219], v[156:159], v[56:59]
	v_mfma_f32_16x16x32_bf16 v[44:47], v[208:211], v[164:167], v[44:47]
	v_mfma_f32_16x16x32_bf16 v[40:43], v[216:219], v[164:167], v[40:43]
	v_mfma_f32_16x16x32_bf16 v[28:31], v[208:211], v[180:183], v[28:31]
	v_mfma_f32_16x16x32_bf16 v[24:27], v[216:219], v[180:183], v[24:27]
	v_mfma_f32_16x16x32_bf16 v[12:15], v[208:211], v[200:203], v[12:15]
	v_mfma_f32_16x16x32_bf16 v[8:11], v[216:219], v[200:203], v[8:11]
	s_add_i32 s4, 0, 0x18000
	v_add_u32_e32 v0, s4, v185
	s_barrier
	ds_read_b128 v[136:139], v0
	ds_read_b128 v[140:143], v0 offset:1024
	ds_read_b128 v[144:147], v0 offset:2048
	ds_read_b128 v[148:151], v0 offset:3072
	s_mov_b32 m0, s29
	v_lshl_add_u64 v[204:205], v[222:223], 0, s[88:89]
	ds_read_b128 v[152:155], v195 offset:32768
	ds_read_b128 v[156:159], v195 offset:33792
	ds_read_b128 v[160:163], v195 offset:34816
	ds_read_b128 v[164:167], v195 offset:35840
	ds_read_b128 v[176:179], v195 offset:36864
	ds_read_b128 v[180:183], v195 offset:37888
	ds_read_b128 v[196:199], v195 offset:38912
	ds_read_b128 v[200:203], v195 offset:39936
	global_load_lds_dwordx4 v[204:205], off
	v_lshl_add_u64 v[204:205], v[222:223], 0, s[64:65]
	s_mov_b32 m0, s30
	s_nop 0
	global_load_lds_dwordx4 v[204:205], off
	s_waitcnt lgkmcnt(8)
	s_barrier
	s_waitcnt lgkmcnt(0)
	s_waitcnt lgkmcnt(0)
	v_mfma_f32_16x16x32_bf16 v[132:135], v[136:139], v[152:155], v[132:135]
	v_mfma_f32_16x16x32_bf16 v[128:131], v[144:147], v[152:155], v[128:131]
	v_mfma_f32_16x16x32_bf16 v[116:119], v[136:139], v[160:163], v[116:119]
	v_mfma_f32_16x16x32_bf16 v[112:115], v[144:147], v[160:163], v[112:115]
	v_mfma_f32_16x16x32_bf16 v[100:103], v[136:139], v[176:179], v[100:103]
	v_mfma_f32_16x16x32_bf16 v[96:99], v[144:147], v[176:179], v[96:99]
	v_mfma_f32_16x16x32_bf16 v[84:87], v[136:139], v[196:199], v[84:87]
	v_mfma_f32_16x16x32_bf16 v[80:83], v[144:147], v[196:199], v[80:83]
	v_mfma_f32_16x16x32_bf16 v[132:135], v[140:143], v[156:159], v[132:135]
	v_mfma_f32_16x16x32_bf16 v[128:131], v[148:151], v[156:159], v[128:131]
	v_mfma_f32_16x16x32_bf16 v[116:119], v[140:143], v[164:167], v[116:119]
	v_mfma_f32_16x16x32_bf16 v[112:115], v[148:151], v[164:167], v[112:115]
	v_mfma_f32_16x16x32_bf16 v[100:103], v[140:143], v[180:183], v[100:103]
	v_mfma_f32_16x16x32_bf16 v[96:99], v[148:151], v[180:183], v[96:99]
	v_mfma_f32_16x16x32_bf16 v[84:87], v[140:143], v[200:203], v[84:87]
	v_mfma_f32_16x16x32_bf16 v[80:83], v[148:151], v[200:203], v[80:83]
	s_barrier
	s_add_i32 s5, 0, 0x1c000
	s_add_i32 s4, s4, s25
	v_add_u32_e32 v0, s5, v185
	v_lshl_add_u64 v[224:225], v[220:221], 0, s[46:47]
	s_mov_b32 m0, s4
	ds_read_b128 v[204:207], v0
	ds_read_b128 v[208:211], v0 offset:1024
	ds_read_b128 v[212:215], v0 offset:2048
	ds_read_b128 v[216:219], v0 offset:3072
	global_load_lds_dwordx4 v[224:225], off
	v_lshl_add_u64 v[224:225], v[220:221], 0, s[66:67]
	s_add_i32 m0, s4, 0x2000
	s_nop 0
	global_load_lds_dwordx4 v[224:225], off
	s_barrier
; #define G_STAGE(bufoff, gbase, o0, h64) do { \
;         __builtin_amdgcn_global_load_lds((const unsigned*)((const char*)(gbase) + (o0)), (LAS unsigned*)(lds + (bufoff) + ldsw), 16, 0, 0); \
;         __builtin_amdgcn_global_load_lds((const unsigned*)((const char*)(gbase) + (h64) + (o0)), (LAS unsigned*)(lds + (bufoff) + ldsw + 8192), 16, 0, 0); } while (0)
; #define G_LDA(dst, b, h) do { _Pragma("unroll") for (int m = 0; m < 4; ++m) _Pragma("unroll") for (int k = 0; k < 2; ++k) dst[m][k] = *(const LAS bf16x8*)(lds + G_SA(b, h) + aoff + m * 2048 + k * 1024); } while (0)
; #define G_WAIT_V(n) asm volatile("s_waitcnt vmcnt(" #n ")" ::: "memory")
; #define G_WAIT_L(n) asm volatile("s_waitcnt lgkmcnt(" #n ")" ::: "memory")
; #define G_BAR __builtin_amdgcn_s_barrier()
; #define G_SCHED __builtin_amdgcn_sched_barrier(0)
;     ...
;             G_BAR; G_WAIT_L(0); G_MMA(0, 1, At, B1); G_BAR;
;             G_LDA(At, 1, 1); G_STAGE(G_SA(1, 0), a3, cA0, qA);
;             G_BAR; G_WAIT_L(0); G_MMA(1, 0, At, B0); G_BAR; G_SCHED;
;             G_STAGE(G_SB(1, 1), b3 + chB, cB0, qB);
;             G_WAIT_V(6); G_BAR; G_MMA(1, 1, At, B1); G_BAR;
;         }
	s_waitcnt lgkmcnt(0)
	s_waitcnt lgkmcnt(0)
	v_mfma_f32_16x16x32_bf16 v[124:127], v[204:207], v[152:155], v[124:127]
	v_mfma_f32_16x16x32_bf16 v[120:123], v[212:215], v[152:155], v[120:123]
	v_mfma_f32_16x16x32_bf16 v[108:111], v[204:207], v[160:163], v[108:111]
	v_mfma_f32_16x16x32_bf16 v[104:107], v[212:215], v[160:163], v[104:107]
	v_mfma_f32_16x16x32_bf16 v[92:95], v[204:207], v[176:179], v[92:95]
	v_mfma_f32_16x16x32_bf16 v[88:91], v[212:215], v[176:179], v[88:91]
	v_mfma_f32_16x16x32_bf16 v[76:79], v[204:207], v[196:199], v[76:79]
	v_mfma_f32_16x16x32_bf16 v[72:75], v[212:215], v[196:199], v[72:75]
	v_mfma_f32_16x16x32_bf16 v[124:127], v[208:211], v[156:159], v[124:127]
	v_mfma_f32_16x16x32_bf16 v[120:123], v[216:219], v[156:159], v[120:123]
	v_mfma_f32_16x16x32_bf16 v[108:111], v[208:211], v[164:167], v[108:111]
	v_mfma_f32_16x16x32_bf16 v[104:107], v[216:219], v[164:167], v[104:107]
	v_mfma_f32_16x16x32_bf16 v[92:95], v[208:211], v[180:183], v[92:95]
	v_mfma_f32_16x16x32_bf16 v[88:91], v[216:219], v[180:183], v[88:91]
	v_mfma_f32_16x16x32_bf16 v[76:79], v[208:211], v[200:203], v[76:79]
	v_mfma_f32_16x16x32_bf16 v[72:75], v[216:219], v[200:203], v[72:75]
	s_mov_b32 m0, s31
	v_lshl_add_u64 v[224:225], v[222:223], 0, s[46:47]
	s_barrier
	ds_read_b128 v[152:155], v195 offset:49152
	ds_read_b128 v[156:159], v195 offset:50176
	ds_read_b128 v[160:163], v195 offset:51200
	ds_read_b128 v[164:167], v195 offset:52224
	ds_read_b128 v[176:179], v195 offset:53248
	ds_read_b128 v[180:183], v195 offset:54272
	ds_read_b128 v[196:199], v195 offset:55296
	ds_read_b128 v[200:203], v195 offset:56320
	global_load_lds_dwordx4 v[224:225], off
	v_lshl_add_u64 v[222:223], v[222:223], 0, s[66:67]
	s_mov_b32 m0, s34
	s_nop 0
	global_load_lds_dwordx4 v[222:223], off
	s_barrier
	s_waitcnt lgkmcnt(0)
	s_waitcnt lgkmcnt(0)
	v_mfma_f32_16x16x32_bf16 v[68:71], v[136:139], v[152:155], v[68:71]
	v_mfma_f32_16x16x32_bf16 v[64:67], v[144:147], v[152:155], v[64:67]
	v_mfma_f32_16x16x32_bf16 v[52:55], v[136:139], v[160:163], v[52:55]
	v_mfma_f32_16x16x32_bf16 v[48:51], v[144:147], v[160:163], v[48:51]
	v_mfma_f32_16x16x32_bf16 v[36:39], v[136:139], v[176:179], v[36:39]
	v_mfma_f32_16x16x32_bf16 v[32:35], v[144:147], v[176:179], v[32:35]
	v_mfma_f32_16x16x32_bf16 v[20:23], v[136:139], v[196:199], v[20:23]
	v_mfma_f32_16x16x32_bf16 v[16:19], v[144:147], v[196:199], v[16:19]
	v_mfma_f32_16x16x32_bf16 v[68:71], v[140:143], v[156:159], v[68:71]
	v_mfma_f32_16x16x32_bf16 v[64:67], v[148:151], v[156:159], v[64:67]
	v_mfma_f32_16x16x32_bf16 v[52:55], v[140:143], v[164:167], v[52:55]
	v_mfma_f32_16x16x32_bf16 v[48:51], v[148:151], v[164:167], v[48:51]
	v_mfma_f32_16x16x32_bf16 v[36:39], v[140:143], v[180:183], v[36:39]
	v_mfma_f32_16x16x32_bf16 v[32:35], v[148:151], v[180:183], v[32:35]
	v_mfma_f32_16x16x32_bf16 v[20:23], v[140:143], v[200:203], v[20:23]
	v_mfma_f32_16x16x32_bf16 v[16:19], v[148:151], v[200:203], v[16:19]
	s_barrier
	s_add_i32 s4, s5, s25
	v_lshl_add_u64 v[136:137], v[220:221], 0, s[52:53]
	s_mov_b32 m0, s4
	s_nop 0
	global_load_lds_dwordx4 v[136:137], off
	v_lshl_add_u64 v[136:137], v[220:221], 0, s[54:55]
	s_add_i32 m0, s4, 0x2000
	s_nop 0
	global_load_lds_dwordx4 v[136:137], off
	s_waitcnt vmcnt(6)
	s_barrier
	v_mfma_f32_16x16x32_bf16 v[60:63], v[204:207], v[152:155], v[60:63]
	v_mfma_f32_16x16x32_bf16 v[56:59], v[212:215], v[152:155], v[56:59]
	v_mfma_f32_16x16x32_bf16 v[44:47], v[204:207], v[160:163], v[44:47]
	v_mfma_f32_16x16x32_bf16 v[40:43], v[212:215], v[160:163], v[40:43]
	v_mfma_f32_16x16x32_bf16 v[28:31], v[204:207], v[176:179], v[28:31]
	v_mfma_f32_16x16x32_bf16 v[24:27], v[212:215], v[176:179], v[24:27]
	v_mfma_f32_16x16x32_bf16 v[12:15], v[204:207], v[196:199], v[12:15]
	v_mfma_f32_16x16x32_bf16 v[8:11], v[212:215], v[196:199], v[8:11]
	v_mfma_f32_16x16x32_bf16 v[60:63], v[208:211], v[156:159], v[60:63]
	v_mfma_f32_16x16x32_bf16 v[56:59], v[216:219], v[156:159], v[56:59]
	v_mfma_f32_16x16x32_bf16 v[44:47], v[208:211], v[164:167], v[44:47]
	v_mfma_f32_16x16x32_bf16 v[40:43], v[216:219], v[164:167], v[40:43]
	v_mfma_f32_16x16x32_bf16 v[28:31], v[208:211], v[180:183], v[28:31]
	v_mfma_f32_16x16x32_bf16 v[24:27], v[216:219], v[180:183], v[24:27]
	v_mfma_f32_16x16x32_bf16 v[12:15], v[208:211], v[200:203], v[12:15]
	v_mfma_f32_16x16x32_bf16 v[8:11], v[216:219], v[200:203], v[8:11]
	s_add_i32 s21, s21, 2
	s_add_u32 s2, s2, 0x100
	s_addc_u32 s3, s3, 0
	s_add_u32 s6, s6, 0x100
	s_addc_u32 s7, s7, 0
	s_cmp_gt_u32 s21, 41
	s_cbranch_scc0 .Ldb_FFO_cont
	v_readfirstlane_b32 s101, v186
	s_cmpk_gt_u32 s101, 0xff
	s_cbranch_scc1 .Ldb_FFO_exit
	s_barrier
	s_branch .Ldb_FFO_exit

; #define G_STAGE(bufoff, gbase, o0, h64) do { \
;         __builtin_amdgcn_global_load_lds((const unsigned*)((const char*)(gbase) + (o0)), (LAS unsigned*)(lds + (bufoff) + ldsw), 16, 0, 0); \
;         __builtin_amdgcn_global_load_lds((const unsigned*)((const char*)(gbase) + (h64) + (o0)), (LAS unsigned*)(lds + (bufoff) + ldsw + 8192), 16, 0, 0); } while (0)
; #define G_LDA(dst, b, h) do { _Pragma("unroll") for (int m = 0; m < 4; ++m) _Pragma("unroll") for (int k = 0; k < 2; ++k) dst[m][k] = *(const LAS bf16x8*)(lds + G_SA(b, h) + aoff + m * 2048 + k * 1024); } while (0)
; #define G_LDB(dst, b, h) do { _Pragma("unroll") for (int n = 0; n < 2; ++n) _Pragma("unroll") for (int k = 0; k < 2; ++k) dst[n][k] = *(const LAS bf16x8*)(lds + G_SB(b, h) + boff + n * 2048 + k * 1024); } while (0)
; #define G_WAIT_L(n) asm volatile("s_waitcnt lgkmcnt(" #n ")" ::: "memory")
; #define G_BAR __builtin_amdgcn_s_barrier()
; #define G_SCHED __builtin_amdgcn_sched_barrier(0)
;     ...
;         for (int t = 0; t < nt; t += 2) {
;             const bool last = (t == nt - 2);
;             const char* a1 = cA + (size_t)(t + 1) * ckA;
;             const char* a2 = last ? nA : cA + (size_t)(t + 2) * ckA; const char* b2 = last ? nB : cB + (size_t)(t + 2) * kB;
;             const char* a3 = a2 + ckA; const char* b3 = b2 + kB;
;             G_LDB(B0, 0, 0); G_SCHED; G_LDA(At, 0, 0); G_STAGE(G_SA(1, 1), a1 + chA, cA0, qA);
;             G_WAIT_L(8); G_BAR; G_WAIT_L(0); G_MMA(0, 0, At, B0); G_BAR; G_SCHED;
;             G_LDB(B1, 0, 1); G_STAGE(G_SB(0, 0), b2, cB0, qB);
;             G_BAR; G_WAIT_L(0); G_MMA(0, 1, At, B1); G_BAR;
;             G_LDA(At, 0, 1); G_STAGE(G_SA(0, 0), a2, cA0, qA);
;             G_BAR; G_WAIT_L(0); G_MMA(1, 0, At, B0); G_BAR; G_SCHED;
.Ldbj_PLE0_in:
.LBB0_1260:
	s_add_u32 s22, s10, s18
	s_addc_u32 s23, s11, s19
	s_add_u32 s20, s22, 0x100
	s_addc_u32 s21, s23, 0
	s_and_b64 s[4:5], s[16:17], exec
	s_cselect_b32 s20, s6, s20
	s_cselect_b32 s21, s7, s21
	s_add_u32 s4, s12, s18
	s_addc_u32 s5, s13, s19
	s_add_u32 s18, s4, 0x100
	s_addc_u32 s19, s5, 0
	s_add_i32 s44, 0, 0x10000
	v_add_u32_e32 v139, s44, v137
	ds_read_b128 v[140:143], v139
	ds_read_b128 v[144:147], v139 offset:1024
	ds_read_b128 v[148:151], v139 offset:2048
	ds_read_b128 v[152:155], v139 offset:3072
	s_and_b64 s[4:5], s[16:17], exec
	s_cselect_b32 s16, s8, s18
	s_cselect_b32 s17, s9, s19
	s_add_i32 s5, 0, 0x14000
	s_add_i32 s43, 0, 0x18000
	s_add_i32 s18, 0, 0x1c000
	s_add_i32 s45, s44, s25
	s_add_i32 s51, s5, s25
	s_add_i32 s19, s43, s25
	s_add_i32 s53, s18, s25
	s_mov_b64 s[64:65], 0x8000
	s_mov_b64 s[62:63], 0x10080
	s_add_i32 m0, s31, 0xc000
	s_add_i32 s4, s31, 0xe000
	s_add_i32 s54, s45, 0x2000
	s_add_i32 s50, s51, 0x2000
	s_add_i32 s44, s19, 0x2000
	s_add_i32 s52, s53, 0x2000
	v_lshl_add_u64 v[184:185], s[22:23], 0, v[2:3]
	v_lshl_add_u64 v[204:205], v[184:185], 0, s[62:63]
	ds_read_b128 v[156:159], v138
	ds_read_b128 v[160:163], v138 offset:1024
	ds_read_b128 v[164:167], v138 offset:2048
	ds_read_b128 v[172:175], v138 offset:3072
	ds_read_b128 v[176:179], v138 offset:4096
	ds_read_b128 v[180:183], v138 offset:5120
	ds_read_b128 v[196:199], v138 offset:6144
	ds_read_b128 v[200:203], v138 offset:7168
	global_load_lds_dwordx4 v[204:205], off
	v_lshl_add_u64 v[184:185], v[184:185], 0, s[68:69]
	s_mov_b32 m0, s4
	s_nop 0
	global_load_lds_dwordx4 v[184:185], off
	s_waitcnt lgkmcnt(8)
	s_barrier
	s_waitcnt lgkmcnt(0)
	s_waitcnt lgkmcnt(0)
	v_mfma_f32_16x16x32_bf16 v[132:135], v[140:143], v[156:159], v[132:135]
	v_mfma_f32_16x16x32_bf16 v[128:131], v[148:151], v[156:159], v[128:131]
	v_mfma_f32_16x16x32_bf16 v[124:127], v[140:143], v[164:167], v[124:127]
	v_mfma_f32_16x16x32_bf16 v[116:119], v[148:151], v[164:167], v[116:119]
	v_mfma_f32_16x16x32_bf16 v[108:111], v[140:143], v[176:179], v[108:111]
	v_mfma_f32_16x16x32_bf16 v[100:103], v[148:151], v[176:179], v[100:103]
	v_mfma_f32_16x16x32_bf16 v[92:95], v[140:143], v[196:199], v[92:95]
	v_mfma_f32_16x16x32_bf16 v[84:87], v[148:151], v[196:199], v[84:87]
	v_mfma_f32_16x16x32_bf16 v[132:135], v[144:147], v[160:163], v[132:135]
	v_mfma_f32_16x16x32_bf16 v[128:131], v[152:155], v[160:163], v[128:131]
	v_mfma_f32_16x16x32_bf16 v[124:127], v[144:147], v[172:175], v[124:127]
	v_mfma_f32_16x16x32_bf16 v[116:119], v[152:155], v[172:175], v[116:119]
	v_mfma_f32_16x16x32_bf16 v[108:111], v[144:147], v[180:183], v[108:111]
	v_mfma_f32_16x16x32_bf16 v[100:103], v[152:155], v[180:183], v[100:103]
	v_mfma_f32_16x16x32_bf16 v[92:95], v[144:147], v[200:203], v[92:95]
	v_mfma_f32_16x16x32_bf16 v[84:87], v[152:155], v[200:203], v[84:87]
	s_barrier
	s_mov_b32 m0, s45
	v_add_u32_e32 v139, s5, v137
	v_lshl_add_u64 v[184:185], s[16:17], 0, v[0:1]
	ds_read_b128 v[204:207], v139
	ds_read_b128 v[208:211], v139 offset:1024
	ds_read_b128 v[212:215], v139 offset:2048
	ds_read_b128 v[216:219], v139 offset:3072
	global_load_lds_dwordx4 v[184:185], off
	v_lshl_add_u64 v[220:221], v[184:185], 0, s[64:65]
	s_mov_b32 m0, s54
	s_nop 0
	global_load_lds_dwordx4 v[220:221], off
	s_barrier
	s_waitcnt lgkmcnt(0)
	s_waitcnt lgkmcnt(0)
	v_mfma_f32_16x16x32_bf16 v[120:123], v[204:207], v[156:159], v[120:123]
	v_mfma_f32_16x16x32_bf16 v[112:115], v[212:215], v[156:159], v[112:115]
	v_mfma_f32_16x16x32_bf16 v[104:107], v[204:207], v[164:167], v[104:107]
	v_mfma_f32_16x16x32_bf16 v[96:99], v[212:215], v[164:167], v[96:99]
	v_mfma_f32_16x16x32_bf16 v[88:91], v[204:207], v[176:179], v[88:91]
	v_mfma_f32_16x16x32_bf16 v[80:83], v[212:215], v[176:179], v[80:83]
	v_mfma_f32_16x16x32_bf16 v[76:79], v[204:207], v[196:199], v[76:79]
	v_mfma_f32_16x16x32_bf16 v[72:75], v[212:215], v[196:199], v[72:75]
	v_mfma_f32_16x16x32_bf16 v[120:123], v[208:211], v[160:163], v[120:123]
	v_mfma_f32_16x16x32_bf16 v[112:115], v[216:219], v[160:163], v[112:115]
	v_mfma_f32_16x16x32_bf16 v[104:107], v[208:211], v[172:175], v[104:107]
	v_mfma_f32_16x16x32_bf16 v[96:99], v[216:219], v[172:175], v[96:99]
	v_mfma_f32_16x16x32_bf16 v[88:91], v[208:211], v[180:183], v[88:91]
	v_mfma_f32_16x16x32_bf16 v[80:83], v[216:219], v[180:183], v[80:83]
	v_mfma_f32_16x16x32_bf16 v[76:79], v[208:211], v[200:203], v[76:79]
	v_mfma_f32_16x16x32_bf16 v[72:75], v[216:219], v[200:203], v[72:75]
	s_mov_b32 m0, s31
	v_lshl_add_u64 v[220:221], s[20:21], 0, v[2:3]
	s_mov_b64 s[4:5], 0x8000
	s_barrier
	ds_read_b128 v[156:159], v138 offset:16384
	ds_read_b128 v[160:163], v138 offset:17408
	ds_read_b128 v[164:167], v138 offset:18432
	ds_read_b128 v[172:175], v138 offset:19456
	ds_read_b128 v[176:179], v138 offset:20480
	ds_read_b128 v[180:183], v138 offset:21504
	ds_read_b128 v[196:199], v138 offset:22528
	ds_read_b128 v[200:203], v138 offset:23552
	global_load_lds_dwordx4 v[220:221], off
	v_lshl_add_u64 v[222:223], v[220:221], 0, s[4:5]
	s_mov_b32 m0, s33
	s_mov_b64 s[16:17], 0x18000
	global_load_lds_dwordx4 v[222:223], off
	s_barrier
; #define G_STAGE(bufoff, gbase, o0, h64) do { \
;         __builtin_amdgcn_global_load_lds((const unsigned*)((const char*)(gbase) + (o0)), (LAS unsigned*)(lds + (bufoff) + ldsw), 16, 0, 0); \
;         __builtin_amdgcn_global_load_lds((const unsigned*)((const char*)(gbase) + (h64) + (o0)), (LAS unsigned*)(lds + (bufoff) + ldsw + 8192), 16, 0, 0); } while (0)
; #define G_LDA(dst, b, h) do { _Pragma("unroll") for (int m = 0; m < 4; ++m) _Pragma("unroll") for (int k = 0; k < 2; ++k) dst[m][k] = *(const LAS bf16x8*)(lds + G_SA(b, h) + aoff + m * 2048 + k * 1024); } while (0)
; #define G_LDB(dst, b, h) do { _Pragma("unroll") for (int n = 0; n < 2; ++n) _Pragma("unroll") for (int k = 0; k < 2; ++k) dst[n][k] = *(const LAS bf16x8*)(lds + G_SB(b, h) + boff + n * 2048 + k * 1024); } while (0)
; #define G_WAIT_V(n) asm volatile("s_waitcnt vmcnt(" #n ")" ::: "memory")
; #define G_WAIT_L(n) asm volatile("s_waitcnt lgkmcnt(" #n ")" ::: "memory")
; #define G_BAR __builtin_amdgcn_s_barrier()
; #define G_SCHED __builtin_amdgcn_sched_barrier(0)
;     ...
;             G_BAR; G_WAIT_L(0); G_MMA(1, 0, At, B0); G_BAR; G_SCHED;
;             G_STAGE(G_SB(0, 1), b2 + chB, cB0, qB);
;             G_WAIT_V(6); G_BAR; G_MMA(1, 1, At, B1); G_BAR;
;             G_LDB(B0, 1, 0); G_SCHED; G_LDA(At, 1, 0); G_STAGE(G_SA(0, 1), a2 + chA, cA0, qA);
;             G_WAIT_L(8); G_BAR; G_WAIT_L(0); G_MMA(0, 0, At, B0); G_BAR; G_SCHED;
;             G_LDB(B1, 1, 1); G_STAGE(G_SB(1, 0), b3, cB0, qB);
;             G_BAR; G_WAIT_L(0); G_MMA(0, 1, At, B1); G_BAR;
	s_waitcnt lgkmcnt(0)
	s_mov_b64 s[20:21], 0x8080
	s_waitcnt lgkmcnt(0)
	v_mfma_f32_16x16x32_bf16 v[68:71], v[140:143], v[156:159], v[68:71]
	v_mfma_f32_16x16x32_bf16 v[64:67], v[148:151], v[156:159], v[64:67]
	v_mfma_f32_16x16x32_bf16 v[60:63], v[140:143], v[164:167], v[60:63]
	v_mfma_f32_16x16x32_bf16 v[52:55], v[148:151], v[164:167], v[52:55]
	v_mfma_f32_16x16x32_bf16 v[44:47], v[140:143], v[176:179], v[44:47]
	v_mfma_f32_16x16x32_bf16 v[36:39], v[148:151], v[176:179], v[36:39]
	v_mfma_f32_16x16x32_bf16 v[28:31], v[140:143], v[196:199], v[28:31]
	v_mfma_f32_16x16x32_bf16 v[20:23], v[148:151], v[196:199], v[20:23]
	v_mfma_f32_16x16x32_bf16 v[68:71], v[144:147], v[160:163], v[68:71]
	v_mfma_f32_16x16x32_bf16 v[64:67], v[152:155], v[160:163], v[64:67]
	v_mfma_f32_16x16x32_bf16 v[60:63], v[144:147], v[172:175], v[60:63]
	v_mfma_f32_16x16x32_bf16 v[52:55], v[152:155], v[172:175], v[52:55]
	v_mfma_f32_16x16x32_bf16 v[44:47], v[144:147], v[180:183], v[44:47]
	v_mfma_f32_16x16x32_bf16 v[36:39], v[152:155], v[180:183], v[36:39]
	v_mfma_f32_16x16x32_bf16 v[28:31], v[144:147], v[200:203], v[28:31]
	v_mfma_f32_16x16x32_bf16 v[20:23], v[152:155], v[200:203], v[20:23]
	s_barrier
	s_mov_b32 m0, s51
	v_lshl_add_u64 v[140:141], v[184:185], 0, s[58:59]
	global_load_lds_dwordx4 v[140:141], off
	v_lshl_add_u64 v[140:141], v[184:185], 0, s[16:17]
	s_mov_b32 m0, s50
	s_nop 0
	global_load_lds_dwordx4 v[140:141], off
	s_waitcnt vmcnt(6)
	s_barrier
	v_mfma_f32_16x16x32_bf16 v[56:59], v[204:207], v[156:159], v[56:59]
	v_mfma_f32_16x16x32_bf16 v[48:51], v[212:215], v[156:159], v[48:51]
	v_mfma_f32_16x16x32_bf16 v[40:43], v[204:207], v[164:167], v[40:43]
	v_mfma_f32_16x16x32_bf16 v[32:35], v[212:215], v[164:167], v[32:35]
	v_mfma_f32_16x16x32_bf16 v[24:27], v[204:207], v[176:179], v[24:27]
	v_mfma_f32_16x16x32_bf16 v[16:19], v[212:215], v[176:179], v[16:19]
	v_mfma_f32_16x16x32_bf16 v[12:15], v[204:207], v[196:199], v[12:15]
	v_mfma_f32_16x16x32_bf16 v[8:11], v[212:215], v[196:199], v[8:11]
	v_mfma_f32_16x16x32_bf16 v[56:59], v[208:211], v[160:163], v[56:59]
	v_mfma_f32_16x16x32_bf16 v[48:51], v[216:219], v[160:163], v[48:51]
	v_mfma_f32_16x16x32_bf16 v[40:43], v[208:211], v[172:175], v[40:43]
	v_mfma_f32_16x16x32_bf16 v[32:35], v[216:219], v[172:175], v[32:35]
	v_mfma_f32_16x16x32_bf16 v[24:27], v[208:211], v[180:183], v[24:27]
	v_mfma_f32_16x16x32_bf16 v[16:19], v[216:219], v[180:183], v[16:19]
	v_mfma_f32_16x16x32_bf16 v[12:15], v[208:211], v[200:203], v[12:15]
	v_mfma_f32_16x16x32_bf16 v[8:11], v[216:219], v[200:203], v[8:11]
	v_add_u32_e32 v139, s43, v137
	s_barrier
	ds_read_b128 v[140:143], v139
	ds_read_b128 v[144:147], v139 offset:1024
	ds_read_b128 v[148:151], v139 offset:2048
	ds_read_b128 v[152:155], v139 offset:3072
	s_mov_b32 m0, s34
	v_lshl_add_u64 v[204:205], v[220:221], 0, s[58:59]
	ds_read_b128 v[156:159], v138 offset:32768
	ds_read_b128 v[160:163], v138 offset:33792
	ds_read_b128 v[164:167], v138 offset:34816
	ds_read_b128 v[172:175], v138 offset:35840
	ds_read_b128 v[176:179], v138 offset:36864
	ds_read_b128 v[180:183], v138 offset:37888
	ds_read_b128 v[196:199], v138 offset:38912
	ds_read_b128 v[200:203], v138 offset:39936
	global_load_lds_dwordx4 v[204:205], off
	v_lshl_add_u64 v[204:205], v[220:221], 0, s[16:17]
	s_mov_b32 m0, s35
	s_nop 0
	global_load_lds_dwordx4 v[204:205], off
	s_waitcnt lgkmcnt(8)
	s_barrier
	s_waitcnt lgkmcnt(0)
	s_waitcnt lgkmcnt(0)
	v_mfma_f32_16x16x32_bf16 v[132:135], v[140:143], v[156:159], v[132:135]
	v_mfma_f32_16x16x32_bf16 v[128:131], v[148:151], v[156:159], v[128:131]
	v_mfma_f32_16x16x32_bf16 v[124:127], v[140:143], v[164:167], v[124:127]
	v_mfma_f32_16x16x32_bf16 v[116:119], v[148:151], v[164:167], v[116:119]
	v_mfma_f32_16x16x32_bf16 v[108:111], v[140:143], v[176:179], v[108:111]
	v_mfma_f32_16x16x32_bf16 v[100:103], v[148:151], v[176:179], v[100:103]
	v_mfma_f32_16x16x32_bf16 v[92:95], v[140:143], v[196:199], v[92:95]
	v_mfma_f32_16x16x32_bf16 v[84:87], v[148:151], v[196:199], v[84:87]
	v_mfma_f32_16x16x32_bf16 v[132:135], v[144:147], v[160:163], v[132:135]
	v_mfma_f32_16x16x32_bf16 v[128:131], v[152:155], v[160:163], v[128:131]
	v_mfma_f32_16x16x32_bf16 v[124:127], v[144:147], v[172:175], v[124:127]
	v_mfma_f32_16x16x32_bf16 v[116:119], v[152:155], v[172:175], v[116:119]
	v_mfma_f32_16x16x32_bf16 v[108:111], v[144:147], v[180:183], v[108:111]
	v_mfma_f32_16x16x32_bf16 v[100:103], v[152:155], v[180:183], v[100:103]
	v_mfma_f32_16x16x32_bf16 v[92:95], v[144:147], v[200:203], v[92:95]
	v_mfma_f32_16x16x32_bf16 v[84:87], v[152:155], v[200:203], v[84:87]
	s_barrier
; #define G_STAGE(bufoff, gbase, o0, h64) do { \
;         __builtin_amdgcn_global_load_lds((const unsigned*)((const char*)(gbase) + (o0)), (LAS unsigned*)(lds + (bufoff) + ldsw), 16, 0, 0); \
;         __builtin_amdgcn_global_load_lds((const unsigned*)((const char*)(gbase) + (h64) + (o0)), (LAS unsigned*)(lds + (bufoff) + ldsw + 8192), 16, 0, 0); } while (0)
; #define G_LDA(dst, b, h) do { _Pragma("unroll") for (int m = 0; m < 4; ++m) _Pragma("unroll") for (int k = 0; k < 2; ++k) dst[m][k] = *(const LAS bf16x8*)(lds + G_SA(b, h) + aoff + m * 2048 + k * 1024); } while (0)
; #define G_WAIT_V(n) asm volatile("s_waitcnt vmcnt(" #n ")" ::: "memory")
; #define G_WAIT_L(n) asm volatile("s_waitcnt lgkmcnt(" #n ")" ::: "memory")
; #define G_BAR __builtin_amdgcn_s_barrier()
; #define G_SCHED __builtin_amdgcn_sched_barrier(0)
;     ...
;             G_BAR; G_WAIT_L(0); G_MMA(0, 1, At, B1); G_BAR;
;             G_LDA(At, 1, 1); G_STAGE(G_SA(1, 0), a3, cA0, qA);
;             G_BAR; G_WAIT_L(0); G_MMA(1, 0, At, B0); G_BAR; G_SCHED;
;             G_STAGE(G_SB(1, 1), b3 + chB, cB0, qB);
;             G_WAIT_V(6); G_BAR; G_MMA(1, 1, At, B1); G_BAR;
;         }
;         E.template run<cs.kind>(acc, cur, tid);
;         if (!has_next) break;
	s_mov_b32 m0, s19
	v_add_u32_e32 v139, s18, v137
	v_lshl_add_u64 v[222:223], v[184:185], 0, s[46:47]
	ds_read_b128 v[204:207], v139
	ds_read_b128 v[208:211], v139 offset:1024
	ds_read_b128 v[212:215], v139 offset:2048
	ds_read_b128 v[216:219], v139 offset:3072
	global_load_lds_dwordx4 v[222:223], off
	v_lshl_add_u64 v[222:223], v[184:185], 0, s[20:21]
	s_mov_b32 m0, s44
	s_mov_b64 s[4:5], 0x10080
	global_load_lds_dwordx4 v[222:223], off
	s_barrier
	s_waitcnt lgkmcnt(0)
	s_waitcnt lgkmcnt(0)
	v_mfma_f32_16x16x32_bf16 v[120:123], v[204:207], v[156:159], v[120:123]
	v_mfma_f32_16x16x32_bf16 v[112:115], v[212:215], v[156:159], v[112:115]
	v_mfma_f32_16x16x32_bf16 v[104:107], v[204:207], v[164:167], v[104:107]
	v_mfma_f32_16x16x32_bf16 v[96:99], v[212:215], v[164:167], v[96:99]
	v_mfma_f32_16x16x32_bf16 v[88:91], v[204:207], v[176:179], v[88:91]
	v_mfma_f32_16x16x32_bf16 v[80:83], v[212:215], v[176:179], v[80:83]
	v_mfma_f32_16x16x32_bf16 v[76:79], v[204:207], v[196:199], v[76:79]
	v_mfma_f32_16x16x32_bf16 v[72:75], v[212:215], v[196:199], v[72:75]
	v_mfma_f32_16x16x32_bf16 v[120:123], v[208:211], v[160:163], v[120:123]
	v_mfma_f32_16x16x32_bf16 v[112:115], v[216:219], v[160:163], v[112:115]
	v_mfma_f32_16x16x32_bf16 v[104:107], v[208:211], v[172:175], v[104:107]
	v_mfma_f32_16x16x32_bf16 v[96:99], v[216:219], v[172:175], v[96:99]
	v_mfma_f32_16x16x32_bf16 v[88:91], v[208:211], v[180:183], v[88:91]
	v_mfma_f32_16x16x32_bf16 v[80:83], v[216:219], v[180:183], v[80:83]
	v_mfma_f32_16x16x32_bf16 v[76:79], v[208:211], v[200:203], v[76:79]
	v_mfma_f32_16x16x32_bf16 v[72:75], v[216:219], v[200:203], v[72:75]
	s_mov_b32 m0, s36
	v_lshl_add_u64 v[222:223], v[220:221], 0, s[46:47]
	s_barrier
	ds_read_b128 v[156:159], v138 offset:49152
	ds_read_b128 v[160:163], v138 offset:50176
	ds_read_b128 v[164:167], v138 offset:51200
	ds_read_b128 v[172:175], v138 offset:52224
	ds_read_b128 v[176:179], v138 offset:53248
	ds_read_b128 v[180:183], v138 offset:54272
	ds_read_b128 v[196:199], v138 offset:55296
	ds_read_b128 v[200:203], v138 offset:56320
	global_load_lds_dwordx4 v[222:223], off
	v_lshl_add_u64 v[220:221], v[220:221], 0, s[20:21]
	s_mov_b32 m0, s37
	s_nop 0
	global_load_lds_dwordx4 v[220:221], off
	s_barrier
	s_waitcnt lgkmcnt(0)
	s_waitcnt lgkmcnt(0)
	v_mfma_f32_16x16x32_bf16 v[68:71], v[140:143], v[156:159], v[68:71]
	v_mfma_f32_16x16x32_bf16 v[64:67], v[148:151], v[156:159], v[64:67]
	v_mfma_f32_16x16x32_bf16 v[60:63], v[140:143], v[164:167], v[60:63]
	v_mfma_f32_16x16x32_bf16 v[52:55], v[148:151], v[164:167], v[52:55]
	v_mfma_f32_16x16x32_bf16 v[44:47], v[140:143], v[176:179], v[44:47]
	v_mfma_f32_16x16x32_bf16 v[36:39], v[148:151], v[176:179], v[36:39]
	v_mfma_f32_16x16x32_bf16 v[28:31], v[140:143], v[196:199], v[28:31]
	v_mfma_f32_16x16x32_bf16 v[20:23], v[148:151], v[196:199], v[20:23]
	v_mfma_f32_16x16x32_bf16 v[68:71], v[144:147], v[160:163], v[68:71]
	v_mfma_f32_16x16x32_bf16 v[64:67], v[152:155], v[160:163], v[64:67]
	v_mfma_f32_16x16x32_bf16 v[60:63], v[144:147], v[172:175], v[60:63]
	v_mfma_f32_16x16x32_bf16 v[52:55], v[152:155], v[172:175], v[52:55]
	v_mfma_f32_16x16x32_bf16 v[44:47], v[144:147], v[180:183], v[44:47]
	v_mfma_f32_16x16x32_bf16 v[36:39], v[152:155], v[180:183], v[36:39]
	v_mfma_f32_16x16x32_bf16 v[28:31], v[144:147], v[200:203], v[28:31]
	v_mfma_f32_16x16x32_bf16 v[20:23], v[152:155], v[200:203], v[20:23]
	s_barrier
	s_mov_b32 m0, s53
	v_lshl_add_u64 v[140:141], v[184:185], 0, s[4:5]
	global_load_lds_dwordx4 v[140:141], off
	v_lshl_add_u64 v[140:141], v[184:185], 0, s[68:69]
	s_mov_b32 m0, s52
	s_nop 0
	global_load_lds_dwordx4 v[140:141], off
	s_waitcnt vmcnt(6)
	s_barrier
	v_mfma_f32_16x16x32_bf16 v[56:59], v[204:207], v[156:159], v[56:59]
	v_mfma_f32_16x16x32_bf16 v[48:51], v[212:215], v[156:159], v[48:51]
	v_mfma_f32_16x16x32_bf16 v[40:43], v[204:207], v[164:167], v[40:43]
	v_mfma_f32_16x16x32_bf16 v[32:35], v[212:215], v[164:167], v[32:35]
	v_mfma_f32_16x16x32_bf16 v[24:27], v[204:207], v[176:179], v[24:27]
	v_mfma_f32_16x16x32_bf16 v[16:19], v[212:215], v[176:179], v[16:19]
	v_mfma_f32_16x16x32_bf16 v[12:15], v[204:207], v[196:199], v[12:15]
	v_mfma_f32_16x16x32_bf16 v[8:11], v[212:215], v[196:199], v[8:11]
	v_mfma_f32_16x16x32_bf16 v[56:59], v[208:211], v[160:163], v[56:59]
	v_mfma_f32_16x16x32_bf16 v[48:51], v[216:219], v[160:163], v[48:51]
	v_mfma_f32_16x16x32_bf16 v[40:43], v[208:211], v[172:175], v[40:43]
	v_mfma_f32_16x16x32_bf16 v[32:35], v[216:219], v[172:175], v[32:35]
	v_mfma_f32_16x16x32_bf16 v[24:27], v[208:211], v[180:183], v[24:27]
	v_mfma_f32_16x16x32_bf16 v[16:19], v[216:219], v[180:183], v[16:19]
	v_mfma_f32_16x16x32_bf16 v[12:15], v[208:211], v[200:203], v[12:15]
	v_mfma_f32_16x16x32_bf16 v[8:11], v[216:219], v[200:203], v[8:11]
	s_andn2_b64 vcc, exec, s[14:15]
	s_mov_b64 s[16:17], -1
	s_mov_b64 s[14:15], 0
	s_mov_b64 s[18:19], 0x100
	s_cbranch_vccz .Ldb_PLE0_cont
	v_readfirstlane_b32 s101, v186
	s_cmpk_gt_u32 s101, 0xff
	s_cbranch_scc1 .Ldb_PLE0_exit
	s_barrier
	s_branch .Ldb_PLE0_exit

; #define G_STAGE(bufoff, gbase, o0, h64) do { \
;         __builtin_amdgcn_global_load_lds((const unsigned*)((const char*)(gbase) + (o0)), (LAS unsigned*)(lds + (bufoff) + ldsw), 16, 0, 0); \
;         __builtin_amdgcn_global_load_lds((const unsigned*)((const char*)(gbase) + (h64) + (o0)), (LAS unsigned*)(lds + (bufoff) + ldsw + 8192), 16, 0, 0); } while (0)
; #define G_LDA(dst, b, h) do { _Pragma("unroll") for (int m = 0; m < 4; ++m) _Pragma("unroll") for (int k = 0; k < 2; ++k) dst[m][k] = *(const LAS bf16x8*)(lds + G_SA(b, h) + aoff + m * 2048 + k * 1024); } while (0)
; #define G_LDB(dst, b, h) do { _Pragma("unroll") for (int n = 0; n < 2; ++n) _Pragma("unroll") for (int k = 0; k < 2; ++k) dst[n][k] = *(const LAS bf16x8*)(lds + G_SB(b, h) + boff + n * 2048 + k * 1024); } while (0)
; #define G_WAIT_L(n) asm volatile("s_waitcnt lgkmcnt(" #n ")" ::: "memory")
; #define G_BAR __builtin_amdgcn_s_barrier()
; #define G_SCHED __builtin_amdgcn_sched_barrier(0)
;     ...
;         for (int t = 0; t < nt; t += 2) {
;             const bool last = (t == nt - 2);
;             const char* a1 = cA + (size_t)(t + 1) * ckA;
;             const char* a2 = last ? nA : cA + (size_t)(t + 2) * ckA; const char* b2 = last ? nB : cB + (size_t)(t + 2) * kB;
;             const char* a3 = a2 + ckA; const char* b3 = b2 + kB;
;             G_LDB(B0, 0, 0); G_SCHED; G_LDA(At, 0, 0); G_STAGE(G_SA(1, 1), a1 + chA, cA0, qA);
;             G_WAIT_L(8); G_BAR; G_WAIT_L(0); G_MMA(0, 0, At, B0); G_BAR; G_SCHED;
;             G_LDB(B1, 0, 1); G_STAGE(G_SB(0, 0), b2, cB0, qB);
;             G_BAR; G_WAIT_L(0); G_MMA(0, 1, At, B1); G_BAR;
;             G_LDA(At, 0, 1); G_STAGE(G_SA(0, 0), a2, cA0, qA);
;             G_BAR; G_WAIT_L(0); G_MMA(1, 0, At, B0); G_BAR; G_SCHED;
.Ldbj_PLE1_in:
.LBB0_1283:
	s_add_u32 s4, s2, 0xfffc0080
	s_addc_u32 s5, s3, -1
	s_add_i32 s25, 0, 0x10000
	v_add_u32_e32 v0, s25, v181
	ds_read_b128 v[136:139], v0
	ds_read_b128 v[140:143], v0 offset:1024
	ds_read_b128 v[144:147], v0 offset:2048
	ds_read_b128 v[148:151], v0 offset:3072
	s_cmp_eq_u32 s24, 12
	s_cselect_b32 s5, s19, s5
	s_cselect_b32 s4, s18, s4
	s_cselect_b32 s41, s21, s23
	s_cselect_b32 s40, s20, s22
	v_lshl_add_u64 v[184:185], s[2:3], 0, v[158:159]
	s_add_i32 m0, s29, 0xc000
	ds_read_b128 v[152:155], v182
	ds_read_b128 v[160:163], v182 offset:1024
	ds_read_b128 v[164:167], v182 offset:2048
	ds_read_b128 v[172:175], v182 offset:3072
	ds_read_b128 v[176:179], v182 offset:4096
	ds_read_b128 v[196:199], v182 offset:5120
	ds_read_b128 v[200:203], v182 offset:6144
	ds_read_b128 v[204:207], v182 offset:7168
	global_load_lds_dwordx4 v[184:185], off
	v_lshl_add_u64 v[184:185], v[184:185], 0, s[0:1]
	s_add_i32 m0, s29, 0xe000
	s_nop 0
	global_load_lds_dwordx4 v[184:185], off
	s_waitcnt lgkmcnt(8)
	s_barrier
	s_waitcnt lgkmcnt(0)
	s_waitcnt lgkmcnt(0)
	v_mfma_f32_16x16x32_bf16 v[132:135], v[136:139], v[152:155], v[132:135]
	v_mfma_f32_16x16x32_bf16 v[128:131], v[144:147], v[152:155], v[128:131]
	v_mfma_f32_16x16x32_bf16 v[116:119], v[136:139], v[164:167], v[116:119]
	v_mfma_f32_16x16x32_bf16 v[112:115], v[144:147], v[164:167], v[112:115]
	v_mfma_f32_16x16x32_bf16 v[100:103], v[136:139], v[176:179], v[100:103]
	v_mfma_f32_16x16x32_bf16 v[96:99], v[144:147], v[176:179], v[96:99]
	v_mfma_f32_16x16x32_bf16 v[84:87], v[136:139], v[200:203], v[84:87]
	v_mfma_f32_16x16x32_bf16 v[80:83], v[144:147], v[200:203], v[80:83]
	v_mfma_f32_16x16x32_bf16 v[132:135], v[140:143], v[160:163], v[132:135]
	v_mfma_f32_16x16x32_bf16 v[128:131], v[148:151], v[160:163], v[128:131]
	v_mfma_f32_16x16x32_bf16 v[116:119], v[140:143], v[172:175], v[116:119]
	v_mfma_f32_16x16x32_bf16 v[112:115], v[148:151], v[172:175], v[112:115]
	v_mfma_f32_16x16x32_bf16 v[100:103], v[140:143], v[196:199], v[100:103]
	v_mfma_f32_16x16x32_bf16 v[96:99], v[148:151], v[196:199], v[96:99]
	v_mfma_f32_16x16x32_bf16 v[84:87], v[140:143], v[204:207], v[84:87]
	v_mfma_f32_16x16x32_bf16 v[80:83], v[148:151], v[204:207], v[80:83]
	s_barrier
	s_add_i32 s44, 0, 0x14000
	s_add_i32 s25, s25, s27
	v_add_u32_e32 v0, s44, v181
	v_lshl_add_u64 v[184:185], s[40:41], 0, v[156:157]
	s_mov_b32 m0, s25
	ds_read_b128 v[208:211], v0
	ds_read_b128 v[212:215], v0 offset:1024
	ds_read_b128 v[216:219], v0 offset:2048
	ds_read_b128 v[220:223], v0 offset:3072
	global_load_lds_dwordx4 v[184:185], off
	v_lshl_add_u64 v[224:225], v[184:185], 0, s[0:1]
	s_add_i32 m0, s25, 0x2000
	s_nop 0
	global_load_lds_dwordx4 v[224:225], off
	s_barrier
	s_waitcnt lgkmcnt(0)
	s_waitcnt lgkmcnt(0)
	v_mfma_f32_16x16x32_bf16 v[124:127], v[208:211], v[152:155], v[124:127]
	v_mfma_f32_16x16x32_bf16 v[120:123], v[216:219], v[152:155], v[120:123]
	v_mfma_f32_16x16x32_bf16 v[108:111], v[208:211], v[164:167], v[108:111]
	v_mfma_f32_16x16x32_bf16 v[104:107], v[216:219], v[164:167], v[104:107]
	v_mfma_f32_16x16x32_bf16 v[92:95], v[208:211], v[176:179], v[92:95]
	v_mfma_f32_16x16x32_bf16 v[88:91], v[216:219], v[176:179], v[88:91]
	v_mfma_f32_16x16x32_bf16 v[76:79], v[208:211], v[200:203], v[76:79]
	v_mfma_f32_16x16x32_bf16 v[72:75], v[216:219], v[200:203], v[72:75]
	v_mfma_f32_16x16x32_bf16 v[124:127], v[212:215], v[160:163], v[124:127]
	v_mfma_f32_16x16x32_bf16 v[120:123], v[220:223], v[160:163], v[120:123]
	v_mfma_f32_16x16x32_bf16 v[108:111], v[212:215], v[172:175], v[108:111]
	v_mfma_f32_16x16x32_bf16 v[104:107], v[220:223], v[172:175], v[104:107]
	v_mfma_f32_16x16x32_bf16 v[92:95], v[212:215], v[196:199], v[92:95]
	v_mfma_f32_16x16x32_bf16 v[88:91], v[220:223], v[196:199], v[88:91]
	v_mfma_f32_16x16x32_bf16 v[76:79], v[212:215], v[204:207], v[76:79]
	v_mfma_f32_16x16x32_bf16 v[72:75], v[220:223], v[204:207], v[72:75]
	s_mov_b32 m0, s29
	v_lshl_add_u64 v[224:225], s[4:5], 0, v[2:3]
	s_barrier
	ds_read_b128 v[152:155], v182 offset:16384
	ds_read_b128 v[160:163], v182 offset:17408
	ds_read_b128 v[164:167], v182 offset:18432
	ds_read_b128 v[172:175], v182 offset:19456
	ds_read_b128 v[176:179], v182 offset:20480
	ds_read_b128 v[196:199], v182 offset:21504
	ds_read_b128 v[200:203], v182 offset:22528
	ds_read_b128 v[204:207], v182 offset:23552
	global_load_lds_dwordx4 v[224:225], off
	v_lshl_add_u64 v[226:227], v[224:225], 0, s[0:1]
	s_mov_b32 m0, s30
	s_nop 0
	global_load_lds_dwordx4 v[226:227], off
	s_barrier
	s_waitcnt lgkmcnt(0)
	s_waitcnt lgkmcnt(0)
	v_mfma_f32_16x16x32_bf16 v[68:71], v[136:139], v[152:155], v[68:71]
	v_mfma_f32_16x16x32_bf16 v[64:67], v[144:147], v[152:155], v[64:67]
	v_mfma_f32_16x16x32_bf16 v[52:55], v[136:139], v[164:167], v[52:55]
	v_mfma_f32_16x16x32_bf16 v[48:51], v[144:147], v[164:167], v[48:51]
	v_mfma_f32_16x16x32_bf16 v[36:39], v[136:139], v[176:179], v[36:39]
	v_mfma_f32_16x16x32_bf16 v[32:35], v[144:147], v[176:179], v[32:35]
	v_mfma_f32_16x16x32_bf16 v[20:23], v[136:139], v[200:203], v[20:23]
	v_mfma_f32_16x16x32_bf16 v[16:19], v[144:147], v[200:203], v[16:19]
	v_mfma_f32_16x16x32_bf16 v[68:71], v[140:143], v[160:163], v[68:71]
	v_mfma_f32_16x16x32_bf16 v[64:67], v[148:151], v[160:163], v[64:67]
	v_mfma_f32_16x16x32_bf16 v[52:55], v[140:143], v[172:175], v[52:55]
	v_mfma_f32_16x16x32_bf16 v[48:51], v[148:151], v[172:175], v[48:51]
	v_mfma_f32_16x16x32_bf16 v[36:39], v[140:143], v[196:199], v[36:39]
	v_mfma_f32_16x16x32_bf16 v[32:35], v[148:151], v[196:199], v[32:35]
	v_mfma_f32_16x16x32_bf16 v[20:23], v[140:143], v[204:207], v[20:23]
	v_mfma_f32_16x16x32_bf16 v[16:19], v[148:151], v[204:207], v[16:19]
	s_barrier
; #define G_STAGE(bufoff, gbase, o0, h64) do { \
;         __builtin_amdgcn_global_load_lds((const unsigned*)((const char*)(gbase) + (o0)), (LAS unsigned*)(lds + (bufoff) + ldsw), 16, 0, 0); \
;         __builtin_amdgcn_global_load_lds((const unsigned*)((const char*)(gbase) + (h64) + (o0)), (LAS unsigned*)(lds + (bufoff) + ldsw + 8192), 16, 0, 0); } while (0)
; #define G_LDA(dst, b, h) do { _Pragma("unroll") for (int m = 0; m < 4; ++m) _Pragma("unroll") for (int k = 0; k < 2; ++k) dst[m][k] = *(const LAS bf16x8*)(lds + G_SA(b, h) + aoff + m * 2048 + k * 1024); } while (0)
; #define G_LDB(dst, b, h) do { _Pragma("unroll") for (int n = 0; n < 2; ++n) _Pragma("unroll") for (int k = 0; k < 2; ++k) dst[n][k] = *(const LAS bf16x8*)(lds + G_SB(b, h) + boff + n * 2048 + k * 1024); } while (0)
; #define G_WAIT_V(n) asm volatile("s_waitcnt vmcnt(" #n ")" ::: "memory")
; #define G_WAIT_L(n) asm volatile("s_waitcnt lgkmcnt(" #n ")" ::: "memory")
; #define G_BAR __builtin_amdgcn_s_barrier()
; #define G_SCHED __builtin_amdgcn_sched_barrier(0)
;     ...
;             G_STAGE(G_SB(0, 1), b2 + chB, cB0, qB);
;             G_WAIT_V(6); G_BAR; G_MMA(1, 1, At, B1); G_BAR;
;             G_LDB(B0, 1, 0); G_SCHED; G_LDA(At, 1, 0); G_STAGE(G_SA(0, 1), a2 + chA, cA0, qA);
;             G_WAIT_L(8); G_BAR; G_WAIT_L(0); G_MMA(0, 0, At, B0); G_BAR; G_SCHED;
;             G_LDB(B1, 1, 1); G_STAGE(G_SB(1, 0), b3, cB0, qB);
;             G_BAR; G_WAIT_L(0); G_MMA(0, 1, At, B1); G_BAR;
	s_add_i32 s4, s44, s27
	v_lshl_add_u64 v[136:137], v[184:185], 0, s[54:55]
	s_mov_b32 m0, s4
	s_nop 0
	global_load_lds_dwordx4 v[136:137], off
	v_lshl_add_u64 v[136:137], v[184:185], 0, s[58:59]
	s_add_i32 m0, s4, 0x2000
	s_nop 0
	global_load_lds_dwordx4 v[136:137], off
	s_waitcnt vmcnt(6)
	s_barrier
	v_mfma_f32_16x16x32_bf16 v[60:63], v[208:211], v[152:155], v[60:63]
	v_mfma_f32_16x16x32_bf16 v[56:59], v[216:219], v[152:155], v[56:59]
	v_mfma_f32_16x16x32_bf16 v[44:47], v[208:211], v[164:167], v[44:47]
	v_mfma_f32_16x16x32_bf16 v[40:43], v[216:219], v[164:167], v[40:43]
	v_mfma_f32_16x16x32_bf16 v[28:31], v[208:211], v[176:179], v[28:31]
	v_mfma_f32_16x16x32_bf16 v[24:27], v[216:219], v[176:179], v[24:27]
	v_mfma_f32_16x16x32_bf16 v[12:15], v[208:211], v[200:203], v[12:15]
	v_mfma_f32_16x16x32_bf16 v[8:11], v[216:219], v[200:203], v[8:11]
	v_mfma_f32_16x16x32_bf16 v[60:63], v[212:215], v[160:163], v[60:63]
	v_mfma_f32_16x16x32_bf16 v[56:59], v[220:223], v[160:163], v[56:59]
	v_mfma_f32_16x16x32_bf16 v[44:47], v[212:215], v[172:175], v[44:47]
	v_mfma_f32_16x16x32_bf16 v[40:43], v[220:223], v[172:175], v[40:43]
	v_mfma_f32_16x16x32_bf16 v[28:31], v[212:215], v[196:199], v[28:31]
	v_mfma_f32_16x16x32_bf16 v[24:27], v[220:223], v[196:199], v[24:27]
	v_mfma_f32_16x16x32_bf16 v[12:15], v[212:215], v[204:207], v[12:15]
	v_mfma_f32_16x16x32_bf16 v[8:11], v[220:223], v[204:207], v[8:11]
	s_add_i32 s4, 0, 0x18000
	v_add_u32_e32 v0, s4, v181
	s_barrier
	ds_read_b128 v[136:139], v0
	ds_read_b128 v[140:143], v0 offset:1024
	ds_read_b128 v[144:147], v0 offset:2048
	ds_read_b128 v[148:151], v0 offset:3072
	s_mov_b32 m0, s31
	v_lshl_add_u64 v[208:209], v[224:225], 0, s[54:55]
	ds_read_b128 v[152:155], v182 offset:32768
	ds_read_b128 v[160:163], v182 offset:33792
	ds_read_b128 v[164:167], v182 offset:34816
	ds_read_b128 v[172:175], v182 offset:35840
	ds_read_b128 v[176:179], v182 offset:36864
	ds_read_b128 v[196:199], v182 offset:37888
	ds_read_b128 v[200:203], v182 offset:38912
	ds_read_b128 v[204:207], v182 offset:39936
	global_load_lds_dwordx4 v[208:209], off
	v_lshl_add_u64 v[208:209], v[224:225], 0, s[58:59]
	s_mov_b32 m0, s34
	s_nop 0
	global_load_lds_dwordx4 v[208:209], off
	s_waitcnt lgkmcnt(8)
	s_barrier
	s_waitcnt lgkmcnt(0)
	s_waitcnt lgkmcnt(0)
	v_mfma_f32_16x16x32_bf16 v[132:135], v[136:139], v[152:155], v[132:135]
	v_mfma_f32_16x16x32_bf16 v[128:131], v[144:147], v[152:155], v[128:131]
	v_mfma_f32_16x16x32_bf16 v[116:119], v[136:139], v[164:167], v[116:119]
	v_mfma_f32_16x16x32_bf16 v[112:115], v[144:147], v[164:167], v[112:115]
	v_mfma_f32_16x16x32_bf16 v[100:103], v[136:139], v[176:179], v[100:103]
	v_mfma_f32_16x16x32_bf16 v[96:99], v[144:147], v[176:179], v[96:99]
	v_mfma_f32_16x16x32_bf16 v[84:87], v[136:139], v[200:203], v[84:87]
	v_mfma_f32_16x16x32_bf16 v[80:83], v[144:147], v[200:203], v[80:83]
	v_mfma_f32_16x16x32_bf16 v[132:135], v[140:143], v[160:163], v[132:135]
	v_mfma_f32_16x16x32_bf16 v[128:131], v[148:151], v[160:163], v[128:131]
	v_mfma_f32_16x16x32_bf16 v[116:119], v[140:143], v[172:175], v[116:119]
	v_mfma_f32_16x16x32_bf16 v[112:115], v[148:151], v[172:175], v[112:115]
	v_mfma_f32_16x16x32_bf16 v[100:103], v[140:143], v[196:199], v[100:103]
	v_mfma_f32_16x16x32_bf16 v[96:99], v[148:151], v[196:199], v[96:99]
	v_mfma_f32_16x16x32_bf16 v[84:87], v[140:143], v[204:207], v[84:87]
	v_mfma_f32_16x16x32_bf16 v[80:83], v[148:151], v[204:207], v[80:83]
	s_barrier
	s_add_i32 s5, 0, 0x1c000
	s_add_i32 s4, s4, s27
	v_add_u32_e32 v0, s5, v181
	v_lshl_add_u64 v[226:227], v[184:185], 0, s[46:47]
	s_mov_b32 m0, s4
	ds_read_b128 v[208:211], v0
	ds_read_b128 v[212:215], v0 offset:1024
	ds_read_b128 v[216:219], v0 offset:2048
	ds_read_b128 v[220:223], v0 offset:3072
	global_load_lds_dwordx4 v[226:227], off
	v_lshl_add_u64 v[226:227], v[184:185], 0, s[62:63]
	s_add_i32 m0, s4, 0x2000
	s_nop 0
	global_load_lds_dwordx4 v[226:227], off
	s_barrier
; #define G_STAGE(bufoff, gbase, o0, h64) do { \
;         __builtin_amdgcn_global_load_lds((const unsigned*)((const char*)(gbase) + (o0)), (LAS unsigned*)(lds + (bufoff) + ldsw), 16, 0, 0); \
;         __builtin_amdgcn_global_load_lds((const unsigned*)((const char*)(gbase) + (h64) + (o0)), (LAS unsigned*)(lds + (bufoff) + ldsw + 8192), 16, 0, 0); } while (0)
; #define G_LDA(dst, b, h) do { _Pragma("unroll") for (int m = 0; m < 4; ++m) _Pragma("unroll") for (int k = 0; k < 2; ++k) dst[m][k] = *(const LAS bf16x8*)(lds + G_SA(b, h) + aoff + m * 2048 + k * 1024); } while (0)
; #define G_WAIT_V(n) asm volatile("s_waitcnt vmcnt(" #n ")" ::: "memory")
; #define G_WAIT_L(n) asm volatile("s_waitcnt lgkmcnt(" #n ")" ::: "memory")
; #define G_BAR __builtin_amdgcn_s_barrier()
; #define G_SCHED __builtin_amdgcn_sched_barrier(0)
;     ...
;             G_BAR; G_WAIT_L(0); G_MMA(0, 1, At, B1); G_BAR;
;             G_LDA(At, 1, 1); G_STAGE(G_SA(1, 0), a3, cA0, qA);
;             G_BAR; G_WAIT_L(0); G_MMA(1, 0, At, B0); G_BAR; G_SCHED;
;             G_STAGE(G_SB(1, 1), b3 + chB, cB0, qB);
;             G_WAIT_V(6); G_BAR; G_MMA(1, 1, At, B1); G_BAR;
;         }
	s_waitcnt lgkmcnt(0)
	s_waitcnt lgkmcnt(0)
	v_mfma_f32_16x16x32_bf16 v[124:127], v[208:211], v[152:155], v[124:127]
	v_mfma_f32_16x16x32_bf16 v[120:123], v[216:219], v[152:155], v[120:123]
	v_mfma_f32_16x16x32_bf16 v[108:111], v[208:211], v[164:167], v[108:111]
	v_mfma_f32_16x16x32_bf16 v[104:107], v[216:219], v[164:167], v[104:107]
	v_mfma_f32_16x16x32_bf16 v[92:95], v[208:211], v[176:179], v[92:95]
	v_mfma_f32_16x16x32_bf16 v[88:91], v[216:219], v[176:179], v[88:91]
	v_mfma_f32_16x16x32_bf16 v[76:79], v[208:211], v[200:203], v[76:79]
	v_mfma_f32_16x16x32_bf16 v[72:75], v[216:219], v[200:203], v[72:75]
	v_mfma_f32_16x16x32_bf16 v[124:127], v[212:215], v[160:163], v[124:127]
	v_mfma_f32_16x16x32_bf16 v[120:123], v[220:223], v[160:163], v[120:123]
	v_mfma_f32_16x16x32_bf16 v[108:111], v[212:215], v[172:175], v[108:111]
	v_mfma_f32_16x16x32_bf16 v[104:107], v[220:223], v[172:175], v[104:107]
	v_mfma_f32_16x16x32_bf16 v[92:95], v[212:215], v[196:199], v[92:95]
	v_mfma_f32_16x16x32_bf16 v[88:91], v[220:223], v[196:199], v[88:91]
	v_mfma_f32_16x16x32_bf16 v[76:79], v[212:215], v[204:207], v[76:79]
	v_mfma_f32_16x16x32_bf16 v[72:75], v[220:223], v[204:207], v[72:75]
	s_mov_b32 m0, s35
	v_lshl_add_u64 v[226:227], v[224:225], 0, s[46:47]
	s_barrier
	ds_read_b128 v[152:155], v182 offset:49152
	ds_read_b128 v[160:163], v182 offset:50176
	ds_read_b128 v[164:167], v182 offset:51200
	ds_read_b128 v[172:175], v182 offset:52224
	ds_read_b128 v[176:179], v182 offset:53248
	ds_read_b128 v[196:199], v182 offset:54272
	ds_read_b128 v[200:203], v182 offset:55296
	ds_read_b128 v[204:207], v182 offset:56320
	global_load_lds_dwordx4 v[226:227], off
	v_lshl_add_u64 v[224:225], v[224:225], 0, s[62:63]
	s_mov_b32 m0, s36
	s_nop 0
	global_load_lds_dwordx4 v[224:225], off
	s_barrier
	s_waitcnt lgkmcnt(0)
	s_waitcnt lgkmcnt(0)
	v_mfma_f32_16x16x32_bf16 v[68:71], v[136:139], v[152:155], v[68:71]
	v_mfma_f32_16x16x32_bf16 v[64:67], v[144:147], v[152:155], v[64:67]
	v_mfma_f32_16x16x32_bf16 v[52:55], v[136:139], v[164:167], v[52:55]
	v_mfma_f32_16x16x32_bf16 v[48:51], v[144:147], v[164:167], v[48:51]
	v_mfma_f32_16x16x32_bf16 v[36:39], v[136:139], v[176:179], v[36:39]
	v_mfma_f32_16x16x32_bf16 v[32:35], v[144:147], v[176:179], v[32:35]
	v_mfma_f32_16x16x32_bf16 v[20:23], v[136:139], v[200:203], v[20:23]
	v_mfma_f32_16x16x32_bf16 v[16:19], v[144:147], v[200:203], v[16:19]
	v_mfma_f32_16x16x32_bf16 v[68:71], v[140:143], v[160:163], v[68:71]
	v_mfma_f32_16x16x32_bf16 v[64:67], v[148:151], v[160:163], v[64:67]
	v_mfma_f32_16x16x32_bf16 v[52:55], v[140:143], v[172:175], v[52:55]
	v_mfma_f32_16x16x32_bf16 v[48:51], v[148:151], v[172:175], v[48:51]
	v_mfma_f32_16x16x32_bf16 v[36:39], v[140:143], v[196:199], v[36:39]
	v_mfma_f32_16x16x32_bf16 v[32:35], v[148:151], v[196:199], v[32:35]
	v_mfma_f32_16x16x32_bf16 v[20:23], v[140:143], v[204:207], v[20:23]
	v_mfma_f32_16x16x32_bf16 v[16:19], v[148:151], v[204:207], v[16:19]
	s_barrier
	s_add_i32 s4, s5, s27
	v_lshl_add_u64 v[136:137], v[184:185], 0, s[64:65]
	s_mov_b32 m0, s4
	s_nop 0
	global_load_lds_dwordx4 v[136:137], off
	v_lshl_add_u64 v[136:137], v[184:185], 0, s[66:67]
	s_add_i32 m0, s4, 0x2000
	s_nop 0
	global_load_lds_dwordx4 v[136:137], off
	s_waitcnt vmcnt(6)
	s_barrier
	v_mfma_f32_16x16x32_bf16 v[60:63], v[208:211], v[152:155], v[60:63]
	v_mfma_f32_16x16x32_bf16 v[56:59], v[216:219], v[152:155], v[56:59]
	v_mfma_f32_16x16x32_bf16 v[44:47], v[208:211], v[164:167], v[44:47]
	v_mfma_f32_16x16x32_bf16 v[40:43], v[216:219], v[164:167], v[40:43]
	v_mfma_f32_16x16x32_bf16 v[28:31], v[208:211], v[176:179], v[28:31]
	v_mfma_f32_16x16x32_bf16 v[24:27], v[216:219], v[176:179], v[24:27]
	v_mfma_f32_16x16x32_bf16 v[12:15], v[208:211], v[200:203], v[12:15]
	v_mfma_f32_16x16x32_bf16 v[8:11], v[216:219], v[200:203], v[8:11]
	v_mfma_f32_16x16x32_bf16 v[60:63], v[212:215], v[160:163], v[60:63]
	v_mfma_f32_16x16x32_bf16 v[56:59], v[220:223], v[160:163], v[56:59]
	v_mfma_f32_16x16x32_bf16 v[44:47], v[212:215], v[172:175], v[44:47]
	v_mfma_f32_16x16x32_bf16 v[40:43], v[220:223], v[172:175], v[40:43]
	v_mfma_f32_16x16x32_bf16 v[28:31], v[212:215], v[196:199], v[28:31]
	v_mfma_f32_16x16x32_bf16 v[24:27], v[220:223], v[196:199], v[24:27]
	v_mfma_f32_16x16x32_bf16 v[12:15], v[212:215], v[204:207], v[12:15]
	v_mfma_f32_16x16x32_bf16 v[8:11], v[220:223], v[204:207], v[8:11]
	s_add_i32 s24, s24, 2
	s_add_u32 s2, s2, 0x100
	s_addc_u32 s3, s3, 0
	s_add_u32 s22, s22, 0x100
	s_addc_u32 s23, s23, 0
	s_cmp_gt_u32 s24, 13
	s_cbranch_scc0 .Ldb_PLE1_cont
	v_readfirstlane_b32 s101, v186
	s_cmpk_gt_u32 s101, 0xff
	s_cbranch_scc1 .Ldb_PLE1_exit
	s_barrier
	s_branch .Ldb_PLE1_exit
